# Barrier ending each MFMA burst signalled four MFMAs early with the tail at priority 2
# baseline (speedup 1.0000x reference)
; #define PG8_STAGE(bufoff, gbase, voff) do { _Pragma("unroll") for (int _i = 0; _i < 2; ++_i) \
;         __builtin_amdgcn_global_load_lds((const unsigned*)((const char*)(gbase) + (voff)[_i]), (PG8_LAS unsigned*)(lds + (bufoff) + ldsw + _i * 8192), 16, 0, 0); } while (0)
; #define PG8_LDA(dst, b, h) do { _Pragma("unroll") for (int m = 0; m < 4; ++m) _Pragma("unroll") for (int k = 0; k < 2; ++k) dst[m][k] = *(const PG8_LAS bf16x8*)(lds + PG8_SA(b, h) + aoff + m * 2048 + k * 1024); } while (0)
; #define PG8_LDB(dst, b, h) do { _Pragma("unroll") for (int n = 0; n < 2; ++n) _Pragma("unroll") for (int k = 0; k < 2; ++k) dst[n][k] = *(const PG8_LAS bf16x8*)(lds + PG8_SB(b, h) + boff + n * 2048 + k * 1024); } while (0)
; #define PG8_MMA(ai, bj, At, Bt) do { __builtin_amdgcn_s_setprio(1); _Pragma("unroll") for (int m = 0; m < 4; ++m) _Pragma("unroll") for (int n = 0; n < 2; ++n) _Pragma("unroll") for (int k = 0; k < 2; ++k) \
;         acc[ai][bj][m][n] = __builtin_amdgcn_mfma_f32_16x16x32_bf16(Bt[n][k], At[m][k], acc[ai][bj][m][n], 0, 0, 0); __builtin_amdgcn_s_setprio(0); } while (0)
; #define PG8_WAIT_V(n) asm volatile("s_waitcnt vmcnt(" #n ")" ::: "memory")
; #define PG8_WAIT_L(n) asm volatile("s_waitcnt lgkmcnt(" #n ")" ::: "memory")
; #define PG8_BAR __builtin_amdgcn_s_barrier()
; template <class Epi, class Sched, bool ALIGN_EPI = false, bool SP2 = false>
; __device__ __forceinline__ void gemm_phase(PG8_LAS unsigned char* lds, const Gemm g, const Sched& S, const Epi& E) {
;     ...
;             const bool last = (t == nt - 2);
;             const char* a1 = cA + (size_t)(t + 1) * kstep;
;             const char* a2 = last ? nA : cA + (size_t)(t + 2) * kstep; const char* b2 = last ? nB : cB + (size_t)(t + 2) * kstep;
;             const char* a3 = a2 + kstep; const char* b3 = b2 + kstep;
;             if constexpr (SP2) {
;             PG8_LDB(B0, 0, 0); PG8_LDB(B1, 0, 1); PG8_SCHED; PG8_LDA(At, 0, 0); PG8_STAGE(PG8_SA(1, 1), a1 + hstep, voffA);
;             PG8_WAIT_V(8); PG8_WAIT_L(0); PG8_BAR; PG8_MMA(0, 0, At, B0); PG8_MMA(0, 1, At, B1); PG8_BAR; PG8_SCHED;
;             PG8_LDA(At, 0, 1); PG8_STAGE(PG8_SB(0, 0), b2, voffB); PG8_STAGE(PG8_SB(0, 1), b2 + hstep, voffB); PG8_STAGE(PG8_SA(0, 0), a2, voffA);
;             PG8_WAIT_V(8); PG8_WAIT_L(0); PG8_BAR; PG8_MMA(1, 0, At, B0); PG8_MMA(1, 1, At, B1); PG8_BAR; PG8_SCHED;
.LBB0_200:
	ds_read_b128 v[148:151], v164
	ds_read_b128 v[152:155], v164 offset:1024
	ds_read_b128 v[156:159], v164 offset:2048
	ds_read_b128 v[168:171], v164 offset:3072
	ds_read_b128 v[172:175], v165
	ds_read_b128 v[176:179], v165 offset:1024
	ds_read_b128 v[180:183], v165 offset:2048
	ds_read_b128 v[184:187], v165 offset:3072
	s_add_u32 s52, s70, 0xfff80080
	s_addc_u32 s53, s71, -1
	s_cmp_eq_u32 s93, 28
	s_cselect_b32 s75, s39, s53
	s_cselect_b32 s74, s69, s52
	s_cselect_b32 s73, s35, s92
	s_cselect_b32 s72, s90, s91
	v_lshl_add_u64 v[220:221], s[70:71], 0, v[138:139]
	s_add_i32 m0, s33, 0xc000
	ds_read_b128 v[188:191], v166
	ds_read_b128 v[192:195], v166 offset:1024
	ds_read_b128 v[196:199], v166 offset:2048
	ds_read_b128 v[200:203], v166 offset:3072
	ds_read_b128 v[204:207], v166 offset:4096
	ds_read_b128 v[208:211], v166 offset:5120
	ds_read_b128 v[212:215], v166 offset:6144
	ds_read_b128 v[216:219], v166 offset:7168
	global_load_lds_dwordx4 v[220:221], off
	v_lshl_add_u64 v[220:221], s[70:71], 0, v[140:141]
	s_add_i32 m0, s33, 0xe000
	s_nop 0
	global_load_lds_dwordx4 v[220:221], off
	s_waitcnt vmcnt(8)
	s_waitcnt lgkmcnt(0)
	s_barrier
	s_setprio 1
	s_waitcnt lgkmcnt(0)
	v_mfma_f32_16x16x32_bf16 v[124:127], v[148:151], v[188:191], v[124:127]
	v_mfma_f32_16x16x32_bf16 v[120:123], v[156:159], v[188:191], v[120:123]
	v_mfma_f32_16x16x32_bf16 v[116:119], v[148:151], v[196:199], v[116:119]
	v_mfma_f32_16x16x32_bf16 v[108:111], v[156:159], v[196:199], v[108:111]
	v_mfma_f32_16x16x32_bf16 v[100:103], v[148:151], v[204:207], v[100:103]
	v_mfma_f32_16x16x32_bf16 v[92:95], v[156:159], v[204:207], v[92:95]
	v_mfma_f32_16x16x32_bf16 v[84:87], v[148:151], v[212:215], v[84:87]
	v_mfma_f32_16x16x32_bf16 v[76:79], v[156:159], v[212:215], v[76:79]
	v_mfma_f32_16x16x32_bf16 v[124:127], v[152:155], v[192:195], v[124:127]
	v_mfma_f32_16x16x32_bf16 v[120:123], v[168:171], v[192:195], v[120:123]
	v_mfma_f32_16x16x32_bf16 v[116:119], v[152:155], v[200:203], v[116:119]
	v_mfma_f32_16x16x32_bf16 v[108:111], v[168:171], v[200:203], v[108:111]
	v_mfma_f32_16x16x32_bf16 v[100:103], v[152:155], v[208:211], v[100:103]
	v_mfma_f32_16x16x32_bf16 v[92:95], v[168:171], v[208:211], v[92:95]
	v_mfma_f32_16x16x32_bf16 v[84:87], v[152:155], v[216:219], v[84:87]
	v_mfma_f32_16x16x32_bf16 v[76:79], v[168:171], v[216:219], v[76:79]
	s_setprio 0
	s_setprio 1
	v_mfma_f32_16x16x32_bf16 v[112:115], v[172:175], v[188:191], v[112:115]
	v_mfma_f32_16x16x32_bf16 v[104:107], v[180:183], v[188:191], v[104:107]
	v_mfma_f32_16x16x32_bf16 v[96:99], v[172:175], v[196:199], v[96:99]
	v_mfma_f32_16x16x32_bf16 v[88:91], v[180:183], v[196:199], v[88:91]
	v_mfma_f32_16x16x32_bf16 v[80:83], v[172:175], v[204:207], v[80:83]
	v_mfma_f32_16x16x32_bf16 v[72:75], v[180:183], v[204:207], v[72:75]
	v_mfma_f32_16x16x32_bf16 v[68:71], v[172:175], v[212:215], v[68:71]
	v_mfma_f32_16x16x32_bf16 v[64:67], v[180:183], v[212:215], v[64:67]
	v_mfma_f32_16x16x32_bf16 v[112:115], v[176:179], v[192:195], v[112:115]
	v_mfma_f32_16x16x32_bf16 v[104:107], v[184:187], v[192:195], v[104:107]
	v_mfma_f32_16x16x32_bf16 v[96:99], v[176:179], v[200:203], v[96:99]
	v_mfma_f32_16x16x32_bf16 v[88:91], v[184:187], v[200:203], v[88:91]
	s_setprio 2
	s_barrier
	v_mfma_f32_16x16x32_bf16 v[80:83], v[176:179], v[208:211], v[80:83]
	v_mfma_f32_16x16x32_bf16 v[72:75], v[184:187], v[208:211], v[72:75]
	v_mfma_f32_16x16x32_bf16 v[68:71], v[176:179], v[216:219], v[68:71]
	v_mfma_f32_16x16x32_bf16 v[64:67], v[184:187], v[216:219], v[64:67]
	s_setprio 0
	s_add_i32 s52, s84, s3
	v_lshl_add_u64 v[220:221], s[72:73], 0, v[132:133]
	s_mov_b32 m0, s52
	ds_read_b128 v[188:191], v166 offset:16384
	ds_read_b128 v[192:195], v166 offset:17408
	ds_read_b128 v[196:199], v166 offset:18432
	ds_read_b128 v[200:203], v166 offset:19456
	ds_read_b128 v[204:207], v166 offset:20480
	ds_read_b128 v[208:211], v166 offset:21504
	ds_read_b128 v[212:215], v166 offset:22528
	ds_read_b128 v[216:219], v166 offset:23552
	global_load_lds_dwordx4 v[220:221], off
	s_add_i32 m0, s52, 0x2000
	s_add_u32 s96, s72, 0x80000
	v_lshl_add_u64 v[222:223], s[72:73], 0, v[128:129]
	s_addc_u32 s97, s73, 0
	s_add_i32 s52, s85, s3
	global_load_lds_dwordx4 v[222:223], off
	v_lshl_add_u64 v[224:225], s[96:97], 0, v[132:133]
	s_mov_b32 m0, s52
	v_lshl_add_u64 v[226:227], s[74:75], 0, v[130:131]
	global_load_lds_dwordx4 v[224:225], off
	v_lshl_add_u64 v[224:225], s[96:97], 0, v[128:129]
	s_add_i32 m0, s52, 0x2000
	s_nop 0
	global_load_lds_dwordx4 v[224:225], off
	v_lshl_add_u64 v[224:225], s[74:75], 0, v[134:135]
	s_mov_b32 m0, s33
	s_nop 0
	global_load_lds_dwordx4 v[224:225], off
	s_mov_b32 m0, s76
	s_nop 0
	global_load_lds_dwordx4 v[226:227], off
	s_waitcnt vmcnt(8)
	s_waitcnt lgkmcnt(0)
	s_barrier
; #define PG8_STAGE(bufoff, gbase, voff) do { _Pragma("unroll") for (int _i = 0; _i < 2; ++_i) \
;         __builtin_amdgcn_global_load_lds((const unsigned*)((const char*)(gbase) + (voff)[_i]), (PG8_LAS unsigned*)(lds + (bufoff) + ldsw + _i * 8192), 16, 0, 0); } while (0)
; #define PG8_LDA(dst, b, h) do { _Pragma("unroll") for (int m = 0; m < 4; ++m) _Pragma("unroll") for (int k = 0; k < 2; ++k) dst[m][k] = *(const PG8_LAS bf16x8*)(lds + PG8_SA(b, h) + aoff + m * 2048 + k * 1024); } while (0)
; #define PG8_LDB(dst, b, h) do { _Pragma("unroll") for (int n = 0; n < 2; ++n) _Pragma("unroll") for (int k = 0; k < 2; ++k) dst[n][k] = *(const PG8_LAS bf16x8*)(lds + PG8_SB(b, h) + boff + n * 2048 + k * 1024); } while (0)
; #define PG8_MMA(ai, bj, At, Bt) do { __builtin_amdgcn_s_setprio(1); _Pragma("unroll") for (int m = 0; m < 4; ++m) _Pragma("unroll") for (int n = 0; n < 2; ++n) _Pragma("unroll") for (int k = 0; k < 2; ++k) \
;         acc[ai][bj][m][n] = __builtin_amdgcn_mfma_f32_16x16x32_bf16(Bt[n][k], At[m][k], acc[ai][bj][m][n], 0, 0, 0); __builtin_amdgcn_s_setprio(0); } while (0)
; #define PG8_WAIT_V(n) asm volatile("s_waitcnt vmcnt(" #n ")" ::: "memory")
; #define PG8_WAIT_L(n) asm volatile("s_waitcnt lgkmcnt(" #n ")" ::: "memory")
; #define PG8_BAR __builtin_amdgcn_s_barrier()
; #define PG8_SCHED __builtin_amdgcn_sched_barrier(0)
; template <class Epi, class Sched, bool ALIGN_EPI = false, bool SP2 = false>
; __device__ __forceinline__ void gemm_phase(PG8_LAS unsigned char* lds, const Gemm g, const Sched& S, const Epi& E) {
;     ...
;             PG8_WAIT_V(8); PG8_WAIT_L(0); PG8_BAR; PG8_MMA(1, 0, At, B0); PG8_MMA(1, 1, At, B1); PG8_BAR; PG8_SCHED;
;             PG8_LDB(B0, 1, 0); PG8_LDB(B1, 1, 1); PG8_SCHED; PG8_LDA(At, 1, 0); PG8_STAGE(PG8_SA(0, 1), a2 + hstep, voffA);
;             PG8_WAIT_V(8); PG8_WAIT_L(0); PG8_BAR; PG8_MMA(0, 0, At, B0); PG8_MMA(0, 1, At, B1); PG8_BAR; PG8_SCHED;
;             PG8_LDA(At, 1, 1); PG8_STAGE(PG8_SB(1, 0), b3, voffB); PG8_STAGE(PG8_SB(1, 1), b3 + hstep, voffB); PG8_STAGE(PG8_SA(1, 0), a3, voffA);
;             PG8_WAIT_V(8); PG8_WAIT_L(0); PG8_BAR; PG8_MMA(1, 0, At, B0); PG8_MMA(1, 1, At, B1); PG8_BAR; PG8_SCHED;
	s_setprio 1
	s_waitcnt lgkmcnt(0)
	v_mfma_f32_16x16x32_bf16 v[60:63], v[148:151], v[188:191], v[60:63]
	v_mfma_f32_16x16x32_bf16 v[56:59], v[156:159], v[188:191], v[56:59]
	v_mfma_f32_16x16x32_bf16 v[52:55], v[148:151], v[196:199], v[52:55]
	v_mfma_f32_16x16x32_bf16 v[44:47], v[156:159], v[196:199], v[44:47]
	v_mfma_f32_16x16x32_bf16 v[36:39], v[148:151], v[204:207], v[36:39]
	v_mfma_f32_16x16x32_bf16 v[28:31], v[156:159], v[204:207], v[28:31]
	v_mfma_f32_16x16x32_bf16 v[20:23], v[148:151], v[212:215], v[20:23]
	v_mfma_f32_16x16x32_bf16 v[12:15], v[156:159], v[212:215], v[12:15]
	v_mfma_f32_16x16x32_bf16 v[60:63], v[152:155], v[192:195], v[60:63]
	v_mfma_f32_16x16x32_bf16 v[56:59], v[168:171], v[192:195], v[56:59]
	v_mfma_f32_16x16x32_bf16 v[52:55], v[152:155], v[200:203], v[52:55]
	v_mfma_f32_16x16x32_bf16 v[44:47], v[168:171], v[200:203], v[44:47]
	v_mfma_f32_16x16x32_bf16 v[36:39], v[152:155], v[208:211], v[36:39]
	v_mfma_f32_16x16x32_bf16 v[28:31], v[168:171], v[208:211], v[28:31]
	v_mfma_f32_16x16x32_bf16 v[20:23], v[152:155], v[216:219], v[20:23]
	v_mfma_f32_16x16x32_bf16 v[12:15], v[168:171], v[216:219], v[12:15]
	s_setprio 0
	s_setprio 1
	v_mfma_f32_16x16x32_bf16 v[48:51], v[172:175], v[188:191], v[48:51]
	v_mfma_f32_16x16x32_bf16 v[40:43], v[180:183], v[188:191], v[40:43]
	v_mfma_f32_16x16x32_bf16 v[32:35], v[172:175], v[196:199], v[32:35]
	v_mfma_f32_16x16x32_bf16 v[24:27], v[180:183], v[196:199], v[24:27]
	v_mfma_f32_16x16x32_bf16 v[16:19], v[172:175], v[204:207], v[16:19]
	v_mfma_f32_16x16x32_bf16 v[8:11], v[180:183], v[204:207], v[8:11]
	v_mfma_f32_16x16x32_bf16 v[4:7], v[172:175], v[212:215], v[4:7]
	v_mfma_f32_16x16x32_bf16 v[0:3], v[180:183], v[212:215], v[0:3]
	v_mfma_f32_16x16x32_bf16 v[48:51], v[176:179], v[192:195], v[48:51]
	v_mfma_f32_16x16x32_bf16 v[40:43], v[184:187], v[192:195], v[40:43]
	v_mfma_f32_16x16x32_bf16 v[32:35], v[176:179], v[200:203], v[32:35]
	v_mfma_f32_16x16x32_bf16 v[24:27], v[184:187], v[200:203], v[24:27]
	s_setprio 2
	s_barrier
	v_mfma_f32_16x16x32_bf16 v[16:19], v[176:179], v[208:211], v[16:19]
	v_mfma_f32_16x16x32_bf16 v[8:11], v[184:187], v[208:211], v[8:11]
	v_mfma_f32_16x16x32_bf16 v[4:7], v[176:179], v[216:219], v[4:7]
	v_mfma_f32_16x16x32_bf16 v[0:3], v[184:187], v[216:219], v[0:3]
	s_setprio 0
	s_add_i32 s52, 0, 0x18000
	v_add_u32_e32 v136, s52, v161
	s_add_i32 s53, 0, 0x1c000
	ds_read_b128 v[148:151], v136
	ds_read_b128 v[152:155], v136 offset:1024
	ds_read_b128 v[156:159], v136 offset:2048
	ds_read_b128 v[168:171], v136 offset:3072
	v_add_u32_e32 v136, s53, v161
	ds_read_b128 v[172:175], v136
	ds_read_b128 v[176:179], v136 offset:1024
	ds_read_b128 v[180:183], v136 offset:2048
	ds_read_b128 v[184:187], v136 offset:3072
	s_add_u32 s74, s74, 0x80000
	s_addc_u32 s75, s75, 0
	s_mov_b32 m0, s77
	v_lshl_add_u64 v[228:229], s[74:75], 0, v[134:135]
	ds_read_b128 v[188:191], v166 offset:32768
	ds_read_b128 v[192:195], v166 offset:33792
	ds_read_b128 v[196:199], v166 offset:34816
	ds_read_b128 v[200:203], v166 offset:35840
	ds_read_b128 v[204:207], v166 offset:36864
	ds_read_b128 v[208:211], v166 offset:37888
	ds_read_b128 v[212:215], v166 offset:38912
	ds_read_b128 v[216:219], v166 offset:39936
	global_load_lds_dwordx4 v[228:229], off
	v_lshl_add_u64 v[228:229], s[74:75], 0, v[130:131]
	s_mov_b32 m0, s78
	s_nop 0
	global_load_lds_dwordx4 v[228:229], off
	s_waitcnt vmcnt(8)
	s_waitcnt lgkmcnt(0)
	s_barrier
	s_setprio 1
	s_waitcnt lgkmcnt(0)
	v_mfma_f32_16x16x32_bf16 v[124:127], v[148:151], v[188:191], v[124:127]
	v_mfma_f32_16x16x32_bf16 v[120:123], v[156:159], v[188:191], v[120:123]
	v_mfma_f32_16x16x32_bf16 v[116:119], v[148:151], v[196:199], v[116:119]
	v_mfma_f32_16x16x32_bf16 v[108:111], v[156:159], v[196:199], v[108:111]
	v_mfma_f32_16x16x32_bf16 v[100:103], v[148:151], v[204:207], v[100:103]
	v_mfma_f32_16x16x32_bf16 v[92:95], v[156:159], v[204:207], v[92:95]
	v_mfma_f32_16x16x32_bf16 v[84:87], v[148:151], v[212:215], v[84:87]
	v_mfma_f32_16x16x32_bf16 v[76:79], v[156:159], v[212:215], v[76:79]
	v_mfma_f32_16x16x32_bf16 v[124:127], v[152:155], v[192:195], v[124:127]
	v_mfma_f32_16x16x32_bf16 v[120:123], v[168:171], v[192:195], v[120:123]
	v_mfma_f32_16x16x32_bf16 v[116:119], v[152:155], v[200:203], v[116:119]
	v_mfma_f32_16x16x32_bf16 v[108:111], v[168:171], v[200:203], v[108:111]
	v_mfma_f32_16x16x32_bf16 v[100:103], v[152:155], v[208:211], v[100:103]
	v_mfma_f32_16x16x32_bf16 v[92:95], v[168:171], v[208:211], v[92:95]
	v_mfma_f32_16x16x32_bf16 v[84:87], v[152:155], v[216:219], v[84:87]
	v_mfma_f32_16x16x32_bf16 v[76:79], v[168:171], v[216:219], v[76:79]
	s_setprio 0
	s_setprio 1
	v_mfma_f32_16x16x32_bf16 v[112:115], v[172:175], v[188:191], v[112:115]
	v_mfma_f32_16x16x32_bf16 v[104:107], v[180:183], v[188:191], v[104:107]
	v_mfma_f32_16x16x32_bf16 v[96:99], v[172:175], v[196:199], v[96:99]
	v_mfma_f32_16x16x32_bf16 v[88:91], v[180:183], v[196:199], v[88:91]
	v_mfma_f32_16x16x32_bf16 v[80:83], v[172:175], v[204:207], v[80:83]
	v_mfma_f32_16x16x32_bf16 v[72:75], v[180:183], v[204:207], v[72:75]
	v_mfma_f32_16x16x32_bf16 v[68:71], v[172:175], v[212:215], v[68:71]
	v_mfma_f32_16x16x32_bf16 v[64:67], v[180:183], v[212:215], v[64:67]
	v_mfma_f32_16x16x32_bf16 v[112:115], v[176:179], v[192:195], v[112:115]
	v_mfma_f32_16x16x32_bf16 v[104:107], v[184:187], v[192:195], v[104:107]
	v_mfma_f32_16x16x32_bf16 v[96:99], v[176:179], v[200:203], v[96:99]
	v_mfma_f32_16x16x32_bf16 v[88:91], v[184:187], v[200:203], v[88:91]
	s_setprio 2
	s_barrier
; #define PG8_STAGE(bufoff, gbase, voff) do { _Pragma("unroll") for (int _i = 0; _i < 2; ++_i) \
;         __builtin_amdgcn_global_load_lds((const unsigned*)((const char*)(gbase) + (voff)[_i]), (PG8_LAS unsigned*)(lds + (bufoff) + ldsw + _i * 8192), 16, 0, 0); } while (0)
; #define PG8_LDA(dst, b, h) do { _Pragma("unroll") for (int m = 0; m < 4; ++m) _Pragma("unroll") for (int k = 0; k < 2; ++k) dst[m][k] = *(const PG8_LAS bf16x8*)(lds + PG8_SA(b, h) + aoff + m * 2048 + k * 1024); } while (0)
; #define PG8_MMA(ai, bj, At, Bt) do { __builtin_amdgcn_s_setprio(1); _Pragma("unroll") for (int m = 0; m < 4; ++m) _Pragma("unroll") for (int n = 0; n < 2; ++n) _Pragma("unroll") for (int k = 0; k < 2; ++k) \
;         acc[ai][bj][m][n] = __builtin_amdgcn_mfma_f32_16x16x32_bf16(Bt[n][k], At[m][k], acc[ai][bj][m][n], 0, 0, 0); __builtin_amdgcn_s_setprio(0); } while (0)
; #define PG8_WAIT_V(n) asm volatile("s_waitcnt vmcnt(" #n ")" ::: "memory")
; #define PG8_WAIT_L(n) asm volatile("s_waitcnt lgkmcnt(" #n ")" ::: "memory")
; #define PG8_BAR __builtin_amdgcn_s_barrier()
; #define PG8_SCHED __builtin_amdgcn_sched_barrier(0)
; template <class Epi, class Sched, bool ALIGN_EPI = false, bool SP2 = false>
; __device__ __forceinline__ void gemm_phase(PG8_LAS unsigned char* lds, const Gemm g, const Sched& S, const Epi& E) {
;     ...
;         for (int t = 0; t < nt; t += 2) {
;             const bool last = (t == nt - 2);
;             const char* a1 = cA + (size_t)(t + 1) * kstep;
;             const char* a2 = last ? nA : cA + (size_t)(t + 2) * kstep; const char* b2 = last ? nB : cB + (size_t)(t + 2) * kstep;
;             const char* a3 = a2 + kstep; const char* b3 = b2 + kstep;
;     ...
;             PG8_WAIT_V(8); PG8_WAIT_L(0); PG8_BAR; PG8_MMA(0, 0, At, B0); PG8_MMA(0, 1, At, B1); PG8_BAR; PG8_SCHED;
;             PG8_LDA(At, 1, 1); PG8_STAGE(PG8_SB(1, 0), b3, voffB); PG8_STAGE(PG8_SB(1, 1), b3 + hstep, voffB); PG8_STAGE(PG8_SA(1, 0), a3, voffA);
;             PG8_WAIT_V(8); PG8_WAIT_L(0); PG8_BAR; PG8_MMA(1, 0, At, B0); PG8_MMA(1, 1, At, B1); PG8_BAR; PG8_SCHED;
	v_mfma_f32_16x16x32_bf16 v[80:83], v[176:179], v[208:211], v[80:83]
	v_mfma_f32_16x16x32_bf16 v[72:75], v[184:187], v[208:211], v[72:75]
	v_mfma_f32_16x16x32_bf16 v[68:71], v[176:179], v[216:219], v[68:71]
	v_mfma_f32_16x16x32_bf16 v[64:67], v[184:187], v[216:219], v[64:67]
	s_setprio 0
	s_add_i32 s52, s52, s3
	v_lshl_add_u64 v[220:221], v[220:221], 0, s[12:13]
	s_mov_b32 m0, s52
	ds_read_b128 v[188:191], v166 offset:49152
	ds_read_b128 v[192:195], v166 offset:50176
	ds_read_b128 v[196:199], v166 offset:51200
	ds_read_b128 v[200:203], v166 offset:52224
	ds_read_b128 v[204:207], v166 offset:53248
	ds_read_b128 v[208:211], v166 offset:54272
	ds_read_b128 v[212:215], v166 offset:55296
	ds_read_b128 v[216:219], v166 offset:56320
	global_load_lds_dwordx4 v[220:221], off
	s_add_i32 m0, s52, 0x2000
	s_add_u32 s72, s72, 0x80080
	v_lshl_add_u64 v[220:221], v[222:223], 0, s[12:13]
	s_addc_u32 s73, s73, 0
	s_add_i32 s52, s53, s3
	global_load_lds_dwordx4 v[220:221], off
	v_lshl_add_u64 v[220:221], s[72:73], 0, v[132:133]
	s_mov_b32 m0, s52
	s_nop 0
	global_load_lds_dwordx4 v[220:221], off
	v_lshl_add_u64 v[220:221], s[72:73], 0, v[128:129]
	s_add_i32 m0, s52, 0x2000
	s_nop 0
	global_load_lds_dwordx4 v[220:221], off
	v_lshl_add_u64 v[220:221], v[224:225], 0, s[12:13]
	s_mov_b32 m0, s80
	s_nop 0
	global_load_lds_dwordx4 v[220:221], off
	v_lshl_add_u64 v[220:221], v[226:227], 0, s[12:13]
	s_mov_b32 m0, s81
	s_nop 0
	global_load_lds_dwordx4 v[220:221], off
	s_waitcnt vmcnt(8)
	s_waitcnt lgkmcnt(0)
	s_barrier
	s_setprio 1
	s_waitcnt lgkmcnt(0)
	v_mfma_f32_16x16x32_bf16 v[60:63], v[148:151], v[188:191], v[60:63]
	v_mfma_f32_16x16x32_bf16 v[56:59], v[156:159], v[188:191], v[56:59]
	v_mfma_f32_16x16x32_bf16 v[52:55], v[148:151], v[196:199], v[52:55]
	v_mfma_f32_16x16x32_bf16 v[44:47], v[156:159], v[196:199], v[44:47]
	v_mfma_f32_16x16x32_bf16 v[36:39], v[148:151], v[204:207], v[36:39]
	v_mfma_f32_16x16x32_bf16 v[28:31], v[156:159], v[204:207], v[28:31]
	v_mfma_f32_16x16x32_bf16 v[20:23], v[148:151], v[212:215], v[20:23]
	v_mfma_f32_16x16x32_bf16 v[12:15], v[156:159], v[212:215], v[12:15]
	v_mfma_f32_16x16x32_bf16 v[60:63], v[152:155], v[192:195], v[60:63]
	v_mfma_f32_16x16x32_bf16 v[56:59], v[168:171], v[192:195], v[56:59]
	v_mfma_f32_16x16x32_bf16 v[52:55], v[152:155], v[200:203], v[52:55]
	v_mfma_f32_16x16x32_bf16 v[44:47], v[168:171], v[200:203], v[44:47]
	v_mfma_f32_16x16x32_bf16 v[36:39], v[152:155], v[208:211], v[36:39]
	v_mfma_f32_16x16x32_bf16 v[28:31], v[168:171], v[208:211], v[28:31]
	v_mfma_f32_16x16x32_bf16 v[20:23], v[152:155], v[216:219], v[20:23]
	v_mfma_f32_16x16x32_bf16 v[12:15], v[168:171], v[216:219], v[12:15]
	s_setprio 0
	s_setprio 1
	v_mfma_f32_16x16x32_bf16 v[48:51], v[172:175], v[188:191], v[48:51]
	v_mfma_f32_16x16x32_bf16 v[40:43], v[180:183], v[188:191], v[40:43]
	v_mfma_f32_16x16x32_bf16 v[32:35], v[172:175], v[196:199], v[32:35]
	v_mfma_f32_16x16x32_bf16 v[24:27], v[180:183], v[196:199], v[24:27]
	v_mfma_f32_16x16x32_bf16 v[16:19], v[172:175], v[204:207], v[16:19]
	v_mfma_f32_16x16x32_bf16 v[8:11], v[180:183], v[204:207], v[8:11]
	v_mfma_f32_16x16x32_bf16 v[4:7], v[172:175], v[212:215], v[4:7]
	v_mfma_f32_16x16x32_bf16 v[0:3], v[180:183], v[212:215], v[0:3]
	v_mfma_f32_16x16x32_bf16 v[48:51], v[176:179], v[192:195], v[48:51]
	v_mfma_f32_16x16x32_bf16 v[40:43], v[184:187], v[192:195], v[40:43]
	v_mfma_f32_16x16x32_bf16 v[32:35], v[176:179], v[200:203], v[32:35]
	v_mfma_f32_16x16x32_bf16 v[24:27], v[184:187], v[200:203], v[24:27]
	s_setprio 2
	s_barrier
	v_mfma_f32_16x16x32_bf16 v[16:19], v[176:179], v[208:211], v[16:19]
	v_mfma_f32_16x16x32_bf16 v[8:11], v[184:187], v[208:211], v[8:11]
	v_mfma_f32_16x16x32_bf16 v[4:7], v[176:179], v[216:219], v[4:7]
	v_mfma_f32_16x16x32_bf16 v[0:3], v[184:187], v[216:219], v[0:3]
	s_setprio 0
	s_add_i32 s93, s93, 2
	s_add_u32 s70, s70, 0x100
	s_addc_u32 s71, s71, 0
	s_add_u32 s91, s91, 0x100
	s_addc_u32 s92, s92, 0
	s_cmp_gt_u32 s93, 29
	s_cbranch_scc0 .LBB0_200
	s_and_b64 vcc, exec, s[14:15]
	s_cbranch_vccz .LBB0_203
	s_barrier

; #define PG8_STAGE(bufoff, gbase, voff) do { _Pragma("unroll") for (int _i = 0; _i < 2; ++_i) \
;         __builtin_amdgcn_global_load_lds((const unsigned*)((const char*)(gbase) + (voff)[_i]), (PG8_LAS unsigned*)(lds + (bufoff) + ldsw + _i * 8192), 16, 0, 0); } while (0)
; #define PG8_LDA(dst, b, h) do { _Pragma("unroll") for (int m = 0; m < 4; ++m) _Pragma("unroll") for (int k = 0; k < 2; ++k) dst[m][k] = *(const PG8_LAS bf16x8*)(lds + PG8_SA(b, h) + aoff + m * 2048 + k * 1024); } while (0)
; #define PG8_LDB(dst, b, h) do { _Pragma("unroll") for (int n = 0; n < 2; ++n) _Pragma("unroll") for (int k = 0; k < 2; ++k) dst[n][k] = *(const PG8_LAS bf16x8*)(lds + PG8_SB(b, h) + boff + n * 2048 + k * 1024); } while (0)
; #define PG8_MMA(ai, bj, At, Bt) do { __builtin_amdgcn_s_setprio(1); _Pragma("unroll") for (int m = 0; m < 4; ++m) _Pragma("unroll") for (int n = 0; n < 2; ++n) _Pragma("unroll") for (int k = 0; k < 2; ++k) \
;         acc[ai][bj][m][n] = __builtin_amdgcn_mfma_f32_16x16x32_bf16(Bt[n][k], At[m][k], acc[ai][bj][m][n], 0, 0, 0); __builtin_amdgcn_s_setprio(0); } while (0)
; #define PG8_WAIT_V(n) asm volatile("s_waitcnt vmcnt(" #n ")" ::: "memory")
; #define PG8_WAIT_L(n) asm volatile("s_waitcnt lgkmcnt(" #n ")" ::: "memory")
; #define PG8_BAR __builtin_amdgcn_s_barrier()
; template <class Epi, class Sched, bool ALIGN_EPI = false, bool SP2 = false>
; __device__ __forceinline__ void gemm_phase(PG8_LAS unsigned char* lds, const Gemm g, const Sched& S, const Epi& E) {
;     ...
;             const bool last = (t == nt - 2);
;             const char* a1 = cA + (size_t)(t + 1) * kstep;
;             const char* a2 = last ? nA : cA + (size_t)(t + 2) * kstep; const char* b2 = last ? nB : cB + (size_t)(t + 2) * kstep;
;             const char* a3 = a2 + kstep; const char* b3 = b2 + kstep;
;             if constexpr (SP2) {
;             PG8_LDB(B0, 0, 0); PG8_LDB(B1, 0, 1); PG8_SCHED; PG8_LDA(At, 0, 0); PG8_STAGE(PG8_SA(1, 1), a1 + hstep, voffA);
;             PG8_WAIT_V(8); PG8_WAIT_L(0); PG8_BAR; PG8_MMA(0, 0, At, B0); PG8_MMA(0, 1, At, B1); PG8_BAR; PG8_SCHED;
;             PG8_LDA(At, 0, 1); PG8_STAGE(PG8_SB(0, 0), b2, voffB); PG8_STAGE(PG8_SB(0, 1), b2 + hstep, voffB); PG8_STAGE(PG8_SA(0, 0), a2, voffA);
;             PG8_WAIT_V(8); PG8_WAIT_L(0); PG8_BAR; PG8_MMA(1, 0, At, B0); PG8_MMA(1, 1, At, B1); PG8_BAR; PG8_SCHED;
.LBB0_374:
	ds_read_b128 v[128:131], v230
	ds_read_b128 v[132:135], v230 offset:1024
	ds_read_b128 v[158:161], v230 offset:2048
	ds_read_b128 v[162:165], v230 offset:3072
	ds_read_b128 v[166:169], v231
	ds_read_b128 v[170:173], v231 offset:1024
	ds_read_b128 v[174:177], v231 offset:2048
	ds_read_b128 v[178:181], v231 offset:3072
	s_add_u32 s52, s76, 0xfff80080
	s_addc_u32 s53, s77, -1
	s_cmp_eq_u32 vcc_hi, 28
	s_cselect_b32 s81, s11, s53
	s_cselect_b32 s80, s55, s52
	s_cselect_b32 s79, s51, vcc_lo
	s_cselect_b32 s78, s73, s75
	v_lshl_add_u64 v[214:215], s[76:77], 0, v[150:151]
	s_add_i32 m0, s28, 0xc000
	ds_read_b128 v[182:185], v232
	ds_read_b128 v[186:189], v232 offset:1024
	ds_read_b128 v[190:193], v232 offset:2048
	ds_read_b128 v[194:197], v232 offset:3072
	ds_read_b128 v[198:201], v232 offset:4096
	ds_read_b128 v[202:205], v232 offset:5120
	ds_read_b128 v[206:209], v232 offset:6144
	ds_read_b128 v[210:213], v232 offset:7168
	global_load_lds_dwordx4 v[214:215], off
	v_lshl_add_u64 v[214:215], s[76:77], 0, v[152:153]
	s_add_i32 m0, s28, 0xe000
	s_nop 0
	global_load_lds_dwordx4 v[214:215], off
	s_waitcnt vmcnt(8)
	s_waitcnt lgkmcnt(0)
	s_barrier
	s_setprio 1
	s_waitcnt lgkmcnt(0)
	v_mfma_f32_16x16x32_bf16 v[124:127], v[128:131], v[182:185], v[124:127]
	v_mfma_f32_16x16x32_bf16 v[120:123], v[158:161], v[182:185], v[120:123]
	v_mfma_f32_16x16x32_bf16 v[116:119], v[128:131], v[190:193], v[116:119]
	v_mfma_f32_16x16x32_bf16 v[112:115], v[158:161], v[190:193], v[112:115]
	v_mfma_f32_16x16x32_bf16 v[108:111], v[128:131], v[198:201], v[108:111]
	v_mfma_f32_16x16x32_bf16 v[104:107], v[158:161], v[198:201], v[104:107]
	v_mfma_f32_16x16x32_bf16 v[100:103], v[128:131], v[206:209], v[100:103]
	v_mfma_f32_16x16x32_bf16 v[96:99], v[158:161], v[206:209], v[96:99]
	v_mfma_f32_16x16x32_bf16 v[124:127], v[132:135], v[186:189], v[124:127]
	v_mfma_f32_16x16x32_bf16 v[120:123], v[162:165], v[186:189], v[120:123]
	v_mfma_f32_16x16x32_bf16 v[116:119], v[132:135], v[194:197], v[116:119]
	v_mfma_f32_16x16x32_bf16 v[112:115], v[162:165], v[194:197], v[112:115]
	v_mfma_f32_16x16x32_bf16 v[108:111], v[132:135], v[202:205], v[108:111]
	v_mfma_f32_16x16x32_bf16 v[104:107], v[162:165], v[202:205], v[104:107]
	v_mfma_f32_16x16x32_bf16 v[100:103], v[132:135], v[210:213], v[100:103]
	v_mfma_f32_16x16x32_bf16 v[96:99], v[162:165], v[210:213], v[96:99]
	s_setprio 0
	s_setprio 1
	v_mfma_f32_16x16x32_bf16 v[60:63], v[166:169], v[182:185], v[60:63]
	v_mfma_f32_16x16x32_bf16 v[56:59], v[174:177], v[182:185], v[56:59]
	v_mfma_f32_16x16x32_bf16 v[52:55], v[166:169], v[190:193], v[52:55]
	v_mfma_f32_16x16x32_bf16 v[48:51], v[174:177], v[190:193], v[48:51]
	v_mfma_f32_16x16x32_bf16 v[44:47], v[166:169], v[198:201], v[44:47]
	v_mfma_f32_16x16x32_bf16 v[40:43], v[174:177], v[198:201], v[40:43]
	v_mfma_f32_16x16x32_bf16 v[36:39], v[166:169], v[206:209], v[36:39]
	v_mfma_f32_16x16x32_bf16 v[32:35], v[174:177], v[206:209], v[32:35]
	v_mfma_f32_16x16x32_bf16 v[60:63], v[170:173], v[186:189], v[60:63]
	v_mfma_f32_16x16x32_bf16 v[56:59], v[178:181], v[186:189], v[56:59]
	v_mfma_f32_16x16x32_bf16 v[52:55], v[170:173], v[194:197], v[52:55]
	v_mfma_f32_16x16x32_bf16 v[48:51], v[178:181], v[194:197], v[48:51]
	s_setprio 2
	s_barrier
	v_mfma_f32_16x16x32_bf16 v[44:47], v[170:173], v[202:205], v[44:47]
	v_mfma_f32_16x16x32_bf16 v[40:43], v[178:181], v[202:205], v[40:43]
	v_mfma_f32_16x16x32_bf16 v[36:39], v[170:173], v[210:213], v[36:39]
	v_mfma_f32_16x16x32_bf16 v[32:35], v[178:181], v[210:213], v[32:35]
	s_setprio 0
	s_add_i32 s52, s93, s3
	v_lshl_add_u64 v[214:215], s[78:79], 0, v[138:139]
	s_mov_b32 m0, s52
	ds_read_b128 v[182:185], v232 offset:16384
	ds_read_b128 v[186:189], v232 offset:17408
	ds_read_b128 v[190:193], v232 offset:18432
	ds_read_b128 v[194:197], v232 offset:19456
	ds_read_b128 v[198:201], v232 offset:20480
	ds_read_b128 v[202:205], v232 offset:21504
	ds_read_b128 v[206:209], v232 offset:22528
	ds_read_b128 v[210:213], v232 offset:23552
	global_load_lds_dwordx4 v[214:215], off
	s_add_i32 m0, s52, 0x2000
	s_add_u32 s52, s78, 0x80000
	v_lshl_add_u64 v[216:217], s[78:79], 0, v[142:143]
	s_addc_u32 s53, s79, 0
	s_add_i32 s56, s10, s3
	global_load_lds_dwordx4 v[216:217], off
	v_lshl_add_u64 v[218:219], s[52:53], 0, v[138:139]
	s_mov_b32 m0, s56
	v_lshl_add_u64 v[220:221], s[80:81], 0, v[140:141]
	global_load_lds_dwordx4 v[218:219], off
	v_lshl_add_u64 v[218:219], s[52:53], 0, v[142:143]
	s_add_i32 m0, s56, 0x2000
	s_nop 0
	global_load_lds_dwordx4 v[218:219], off
	v_lshl_add_u64 v[218:219], s[80:81], 0, v[136:137]
	s_mov_b32 m0, s28
	s_nop 0
	global_load_lds_dwordx4 v[218:219], off
	s_mov_b32 m0, s29
	s_nop 0
	global_load_lds_dwordx4 v[220:221], off
	s_waitcnt vmcnt(8)
	s_waitcnt lgkmcnt(0)
	s_barrier
; #define PG8_STAGE(bufoff, gbase, voff) do { _Pragma("unroll") for (int _i = 0; _i < 2; ++_i) \
;         __builtin_amdgcn_global_load_lds((const unsigned*)((const char*)(gbase) + (voff)[_i]), (PG8_LAS unsigned*)(lds + (bufoff) + ldsw + _i * 8192), 16, 0, 0); } while (0)
; #define PG8_LDA(dst, b, h) do { _Pragma("unroll") for (int m = 0; m < 4; ++m) _Pragma("unroll") for (int k = 0; k < 2; ++k) dst[m][k] = *(const PG8_LAS bf16x8*)(lds + PG8_SA(b, h) + aoff + m * 2048 + k * 1024); } while (0)
; #define PG8_LDB(dst, b, h) do { _Pragma("unroll") for (int n = 0; n < 2; ++n) _Pragma("unroll") for (int k = 0; k < 2; ++k) dst[n][k] = *(const PG8_LAS bf16x8*)(lds + PG8_SB(b, h) + boff + n * 2048 + k * 1024); } while (0)
; #define PG8_MMA(ai, bj, At, Bt) do { __builtin_amdgcn_s_setprio(1); _Pragma("unroll") for (int m = 0; m < 4; ++m) _Pragma("unroll") for (int n = 0; n < 2; ++n) _Pragma("unroll") for (int k = 0; k < 2; ++k) \
;         acc[ai][bj][m][n] = __builtin_amdgcn_mfma_f32_16x16x32_bf16(Bt[n][k], At[m][k], acc[ai][bj][m][n], 0, 0, 0); __builtin_amdgcn_s_setprio(0); } while (0)
; #define PG8_WAIT_V(n) asm volatile("s_waitcnt vmcnt(" #n ")" ::: "memory")
; #define PG8_WAIT_L(n) asm volatile("s_waitcnt lgkmcnt(" #n ")" ::: "memory")
; #define PG8_BAR __builtin_amdgcn_s_barrier()
; #define PG8_SCHED __builtin_amdgcn_sched_barrier(0)
; template <class Epi, class Sched, bool ALIGN_EPI = false, bool SP2 = false>
; __device__ __forceinline__ void gemm_phase(PG8_LAS unsigned char* lds, const Gemm g, const Sched& S, const Epi& E) {
;     ...
;             PG8_WAIT_V(8); PG8_WAIT_L(0); PG8_BAR; PG8_MMA(1, 0, At, B0); PG8_MMA(1, 1, At, B1); PG8_BAR; PG8_SCHED;
;             PG8_LDB(B0, 1, 0); PG8_LDB(B1, 1, 1); PG8_SCHED; PG8_LDA(At, 1, 0); PG8_STAGE(PG8_SA(0, 1), a2 + hstep, voffA);
;             PG8_WAIT_V(8); PG8_WAIT_L(0); PG8_BAR; PG8_MMA(0, 0, At, B0); PG8_MMA(0, 1, At, B1); PG8_BAR; PG8_SCHED;
;             PG8_LDA(At, 1, 1); PG8_STAGE(PG8_SB(1, 0), b3, voffB); PG8_STAGE(PG8_SB(1, 1), b3 + hstep, voffB); PG8_STAGE(PG8_SA(1, 0), a3, voffA);
;             PG8_WAIT_V(8); PG8_WAIT_L(0); PG8_BAR; PG8_MMA(1, 0, At, B0); PG8_MMA(1, 1, At, B1); PG8_BAR; PG8_SCHED;
	s_setprio 1
	s_waitcnt lgkmcnt(0)
	v_mfma_f32_16x16x32_bf16 v[92:95], v[128:131], v[182:185], v[92:95]
	v_mfma_f32_16x16x32_bf16 v[88:91], v[158:161], v[182:185], v[88:91]
	v_mfma_f32_16x16x32_bf16 v[84:87], v[128:131], v[190:193], v[84:87]
	v_mfma_f32_16x16x32_bf16 v[80:83], v[158:161], v[190:193], v[80:83]
	v_mfma_f32_16x16x32_bf16 v[76:79], v[128:131], v[198:201], v[76:79]
	v_mfma_f32_16x16x32_bf16 v[72:75], v[158:161], v[198:201], v[72:75]
	v_mfma_f32_16x16x32_bf16 v[68:71], v[128:131], v[206:209], v[68:71]
	v_mfma_f32_16x16x32_bf16 v[64:67], v[158:161], v[206:209], v[64:67]
	v_mfma_f32_16x16x32_bf16 v[92:95], v[132:135], v[186:189], v[92:95]
	v_mfma_f32_16x16x32_bf16 v[88:91], v[162:165], v[186:189], v[88:91]
	v_mfma_f32_16x16x32_bf16 v[84:87], v[132:135], v[194:197], v[84:87]
	v_mfma_f32_16x16x32_bf16 v[80:83], v[162:165], v[194:197], v[80:83]
	v_mfma_f32_16x16x32_bf16 v[76:79], v[132:135], v[202:205], v[76:79]
	v_mfma_f32_16x16x32_bf16 v[72:75], v[162:165], v[202:205], v[72:75]
	v_mfma_f32_16x16x32_bf16 v[68:71], v[132:135], v[210:213], v[68:71]
	v_mfma_f32_16x16x32_bf16 v[64:67], v[162:165], v[210:213], v[64:67]
	s_setprio 0
	s_setprio 1
	v_mfma_f32_16x16x32_bf16 v[28:31], v[166:169], v[182:185], v[28:31]
	v_mfma_f32_16x16x32_bf16 v[24:27], v[174:177], v[182:185], v[24:27]
	v_mfma_f32_16x16x32_bf16 v[20:23], v[166:169], v[190:193], v[20:23]
	v_mfma_f32_16x16x32_bf16 v[16:19], v[174:177], v[190:193], v[16:19]
	v_mfma_f32_16x16x32_bf16 v[12:15], v[166:169], v[198:201], v[12:15]
	v_mfma_f32_16x16x32_bf16 v[8:11], v[174:177], v[198:201], v[8:11]
	v_mfma_f32_16x16x32_bf16 v[4:7], v[166:169], v[206:209], v[4:7]
	v_mfma_f32_16x16x32_bf16 v[0:3], v[174:177], v[206:209], v[0:3]
	v_mfma_f32_16x16x32_bf16 v[28:31], v[170:173], v[186:189], v[28:31]
	v_mfma_f32_16x16x32_bf16 v[24:27], v[178:181], v[186:189], v[24:27]
	v_mfma_f32_16x16x32_bf16 v[20:23], v[170:173], v[194:197], v[20:23]
	v_mfma_f32_16x16x32_bf16 v[16:19], v[178:181], v[194:197], v[16:19]
	s_setprio 2
	s_barrier
	v_mfma_f32_16x16x32_bf16 v[12:15], v[170:173], v[202:205], v[12:15]
	v_mfma_f32_16x16x32_bf16 v[8:11], v[178:181], v[202:205], v[8:11]
	v_mfma_f32_16x16x32_bf16 v[4:7], v[170:173], v[210:213], v[4:7]
	v_mfma_f32_16x16x32_bf16 v[0:3], v[178:181], v[210:213], v[0:3]
	s_setprio 0
	s_add_i32 s56, 0, 0x18000
	s_add_i32 s57, 0, 0x1c000
	v_add_u32_e32 v162, s56, v228
	v_add_u32_e32 v178, s57, v228
	ds_read_b128 v[128:131], v162
	ds_read_b128 v[132:135], v162 offset:1024
	ds_read_b128 v[158:161], v162 offset:2048
	ds_read_b128 v[162:165], v162 offset:3072
	ds_read_b128 v[166:169], v178
	ds_read_b128 v[170:173], v178 offset:1024
	ds_read_b128 v[174:177], v178 offset:2048
	ds_read_b128 v[178:181], v178 offset:3072
	s_add_u32 s52, s80, 0x80000
	s_addc_u32 s53, s81, 0
	s_mov_b32 m0, s33
	v_lshl_add_u64 v[234:235], s[52:53], 0, v[136:137]
	ds_read_b128 v[182:185], v232 offset:32768
	ds_read_b128 v[186:189], v232 offset:33792
	ds_read_b128 v[190:193], v232 offset:34816
	ds_read_b128 v[194:197], v232 offset:35840
	ds_read_b128 v[198:201], v232 offset:36864
	ds_read_b128 v[202:205], v232 offset:37888
	ds_read_b128 v[206:209], v232 offset:38912
	ds_read_b128 v[210:213], v232 offset:39936
	global_load_lds_dwordx4 v[234:235], off
	v_lshl_add_u64 v[234:235], s[52:53], 0, v[140:141]
	s_mov_b32 m0, s38
	s_nop 0
	global_load_lds_dwordx4 v[234:235], off
	s_waitcnt vmcnt(8)
	s_waitcnt lgkmcnt(0)
	s_barrier
	s_setprio 1
	s_waitcnt lgkmcnt(0)
	v_mfma_f32_16x16x32_bf16 v[124:127], v[128:131], v[182:185], v[124:127]
	v_mfma_f32_16x16x32_bf16 v[120:123], v[158:161], v[182:185], v[120:123]
	v_mfma_f32_16x16x32_bf16 v[116:119], v[128:131], v[190:193], v[116:119]
	v_mfma_f32_16x16x32_bf16 v[112:115], v[158:161], v[190:193], v[112:115]
	v_mfma_f32_16x16x32_bf16 v[108:111], v[128:131], v[198:201], v[108:111]
	v_mfma_f32_16x16x32_bf16 v[104:107], v[158:161], v[198:201], v[104:107]
	v_mfma_f32_16x16x32_bf16 v[100:103], v[128:131], v[206:209], v[100:103]
	v_mfma_f32_16x16x32_bf16 v[96:99], v[158:161], v[206:209], v[96:99]
	v_mfma_f32_16x16x32_bf16 v[124:127], v[132:135], v[186:189], v[124:127]
	v_mfma_f32_16x16x32_bf16 v[120:123], v[162:165], v[186:189], v[120:123]
	v_mfma_f32_16x16x32_bf16 v[116:119], v[132:135], v[194:197], v[116:119]
	v_mfma_f32_16x16x32_bf16 v[112:115], v[162:165], v[194:197], v[112:115]
	v_mfma_f32_16x16x32_bf16 v[108:111], v[132:135], v[202:205], v[108:111]
	v_mfma_f32_16x16x32_bf16 v[104:107], v[162:165], v[202:205], v[104:107]
	v_mfma_f32_16x16x32_bf16 v[100:103], v[132:135], v[210:213], v[100:103]
	v_mfma_f32_16x16x32_bf16 v[96:99], v[162:165], v[210:213], v[96:99]
	s_setprio 0
	s_setprio 1
	v_mfma_f32_16x16x32_bf16 v[60:63], v[166:169], v[182:185], v[60:63]
	v_mfma_f32_16x16x32_bf16 v[56:59], v[174:177], v[182:185], v[56:59]
	v_mfma_f32_16x16x32_bf16 v[52:55], v[166:169], v[190:193], v[52:55]
	v_mfma_f32_16x16x32_bf16 v[48:51], v[174:177], v[190:193], v[48:51]
	v_mfma_f32_16x16x32_bf16 v[44:47], v[166:169], v[198:201], v[44:47]
	v_mfma_f32_16x16x32_bf16 v[40:43], v[174:177], v[198:201], v[40:43]
	v_mfma_f32_16x16x32_bf16 v[36:39], v[166:169], v[206:209], v[36:39]
	v_mfma_f32_16x16x32_bf16 v[32:35], v[174:177], v[206:209], v[32:35]
	v_mfma_f32_16x16x32_bf16 v[60:63], v[170:173], v[186:189], v[60:63]
	v_mfma_f32_16x16x32_bf16 v[56:59], v[178:181], v[186:189], v[56:59]
	v_mfma_f32_16x16x32_bf16 v[52:55], v[170:173], v[194:197], v[52:55]
	v_mfma_f32_16x16x32_bf16 v[48:51], v[178:181], v[194:197], v[48:51]
	s_setprio 2
	s_barrier
; #define PG8_STAGE(bufoff, gbase, voff) do { _Pragma("unroll") for (int _i = 0; _i < 2; ++_i) \
;         __builtin_amdgcn_global_load_lds((const unsigned*)((const char*)(gbase) + (voff)[_i]), (PG8_LAS unsigned*)(lds + (bufoff) + ldsw + _i * 8192), 16, 0, 0); } while (0)
; #define PG8_LDA(dst, b, h) do { _Pragma("unroll") for (int m = 0; m < 4; ++m) _Pragma("unroll") for (int k = 0; k < 2; ++k) dst[m][k] = *(const PG8_LAS bf16x8*)(lds + PG8_SA(b, h) + aoff + m * 2048 + k * 1024); } while (0)
; #define PG8_MMA(ai, bj, At, Bt) do { __builtin_amdgcn_s_setprio(1); _Pragma("unroll") for (int m = 0; m < 4; ++m) _Pragma("unroll") for (int n = 0; n < 2; ++n) _Pragma("unroll") for (int k = 0; k < 2; ++k) \
;         acc[ai][bj][m][n] = __builtin_amdgcn_mfma_f32_16x16x32_bf16(Bt[n][k], At[m][k], acc[ai][bj][m][n], 0, 0, 0); __builtin_amdgcn_s_setprio(0); } while (0)
; #define PG8_WAIT_V(n) asm volatile("s_waitcnt vmcnt(" #n ")" ::: "memory")
; #define PG8_WAIT_L(n) asm volatile("s_waitcnt lgkmcnt(" #n ")" ::: "memory")
; #define PG8_BAR __builtin_amdgcn_s_barrier()
; #define PG8_SCHED __builtin_amdgcn_sched_barrier(0)
; template <class Epi, class Sched, bool ALIGN_EPI = false, bool SP2 = false>
; __device__ __forceinline__ void gemm_phase(PG8_LAS unsigned char* lds, const Gemm g, const Sched& S, const Epi& E) {
;     ...
;         for (int t = 0; t < nt; t += 2) {
;             const bool last = (t == nt - 2);
;             const char* a1 = cA + (size_t)(t + 1) * kstep;
;             const char* a2 = last ? nA : cA + (size_t)(t + 2) * kstep; const char* b2 = last ? nB : cB + (size_t)(t + 2) * kstep;
;             const char* a3 = a2 + kstep; const char* b3 = b2 + kstep;
;     ...
;             PG8_WAIT_V(8); PG8_WAIT_L(0); PG8_BAR; PG8_MMA(0, 0, At, B0); PG8_MMA(0, 1, At, B1); PG8_BAR; PG8_SCHED;
;             PG8_LDA(At, 1, 1); PG8_STAGE(PG8_SB(1, 0), b3, voffB); PG8_STAGE(PG8_SB(1, 1), b3 + hstep, voffB); PG8_STAGE(PG8_SA(1, 0), a3, voffA);
;             PG8_WAIT_V(8); PG8_WAIT_L(0); PG8_BAR; PG8_MMA(1, 0, At, B0); PG8_MMA(1, 1, At, B1); PG8_BAR; PG8_SCHED;
	v_mfma_f32_16x16x32_bf16 v[44:47], v[170:173], v[202:205], v[44:47]
	v_mfma_f32_16x16x32_bf16 v[40:43], v[178:181], v[202:205], v[40:43]
	v_mfma_f32_16x16x32_bf16 v[36:39], v[170:173], v[210:213], v[36:39]
	v_mfma_f32_16x16x32_bf16 v[32:35], v[178:181], v[210:213], v[32:35]
	s_setprio 0
	s_add_i32 s52, s56, s3
	v_lshl_add_u64 v[214:215], v[214:215], 0, s[14:15]
	s_mov_b32 m0, s52
	ds_read_b128 v[182:185], v232 offset:49152
	ds_read_b128 v[186:189], v232 offset:50176
	ds_read_b128 v[190:193], v232 offset:51200
	ds_read_b128 v[194:197], v232 offset:52224
	ds_read_b128 v[198:201], v232 offset:53248
	ds_read_b128 v[202:205], v232 offset:54272
	ds_read_b128 v[206:209], v232 offset:55296
	ds_read_b128 v[210:213], v232 offset:56320
	global_load_lds_dwordx4 v[214:215], off
	s_add_i32 m0, s52, 0x2000
	s_add_u32 s52, s78, 0x80080
	v_lshl_add_u64 v[214:215], v[216:217], 0, s[14:15]
	s_addc_u32 s53, s79, 0
	s_add_i32 s56, s57, s3
	global_load_lds_dwordx4 v[214:215], off
	v_lshl_add_u64 v[214:215], s[52:53], 0, v[138:139]
	s_mov_b32 m0, s56
	s_nop 0
	global_load_lds_dwordx4 v[214:215], off
	v_lshl_add_u64 v[214:215], s[52:53], 0, v[142:143]
	s_add_i32 m0, s56, 0x2000
	s_nop 0
	global_load_lds_dwordx4 v[214:215], off
	v_lshl_add_u64 v[214:215], v[218:219], 0, s[14:15]
	s_mov_b32 m0, s88
	s_nop 0
	global_load_lds_dwordx4 v[214:215], off
	v_lshl_add_u64 v[214:215], v[220:221], 0, s[14:15]
	s_mov_b32 m0, s89
	s_nop 0
	global_load_lds_dwordx4 v[214:215], off
	s_waitcnt vmcnt(8)
	s_waitcnt lgkmcnt(0)
	s_barrier
	s_setprio 1
	s_waitcnt lgkmcnt(0)
	v_mfma_f32_16x16x32_bf16 v[92:95], v[128:131], v[182:185], v[92:95]
	v_mfma_f32_16x16x32_bf16 v[88:91], v[158:161], v[182:185], v[88:91]
	v_mfma_f32_16x16x32_bf16 v[84:87], v[128:131], v[190:193], v[84:87]
	v_mfma_f32_16x16x32_bf16 v[80:83], v[158:161], v[190:193], v[80:83]
	v_mfma_f32_16x16x32_bf16 v[76:79], v[128:131], v[198:201], v[76:79]
	v_mfma_f32_16x16x32_bf16 v[72:75], v[158:161], v[198:201], v[72:75]
	v_mfma_f32_16x16x32_bf16 v[68:71], v[128:131], v[206:209], v[68:71]
	v_mfma_f32_16x16x32_bf16 v[64:67], v[158:161], v[206:209], v[64:67]
	v_mfma_f32_16x16x32_bf16 v[92:95], v[132:135], v[186:189], v[92:95]
	v_mfma_f32_16x16x32_bf16 v[88:91], v[162:165], v[186:189], v[88:91]
	v_mfma_f32_16x16x32_bf16 v[84:87], v[132:135], v[194:197], v[84:87]
	v_mfma_f32_16x16x32_bf16 v[80:83], v[162:165], v[194:197], v[80:83]
	v_mfma_f32_16x16x32_bf16 v[76:79], v[132:135], v[202:205], v[76:79]
	v_mfma_f32_16x16x32_bf16 v[72:75], v[162:165], v[202:205], v[72:75]
	v_mfma_f32_16x16x32_bf16 v[68:71], v[132:135], v[210:213], v[68:71]
	v_mfma_f32_16x16x32_bf16 v[64:67], v[162:165], v[210:213], v[64:67]
	s_setprio 0
	s_setprio 1
	v_mfma_f32_16x16x32_bf16 v[28:31], v[166:169], v[182:185], v[28:31]
	v_mfma_f32_16x16x32_bf16 v[24:27], v[174:177], v[182:185], v[24:27]
	v_mfma_f32_16x16x32_bf16 v[20:23], v[166:169], v[190:193], v[20:23]
	v_mfma_f32_16x16x32_bf16 v[16:19], v[174:177], v[190:193], v[16:19]
	v_mfma_f32_16x16x32_bf16 v[12:15], v[166:169], v[198:201], v[12:15]
	v_mfma_f32_16x16x32_bf16 v[8:11], v[174:177], v[198:201], v[8:11]
	v_mfma_f32_16x16x32_bf16 v[4:7], v[166:169], v[206:209], v[4:7]
	v_mfma_f32_16x16x32_bf16 v[0:3], v[174:177], v[206:209], v[0:3]
	v_mfma_f32_16x16x32_bf16 v[28:31], v[170:173], v[186:189], v[28:31]
	v_mfma_f32_16x16x32_bf16 v[24:27], v[178:181], v[186:189], v[24:27]
	v_mfma_f32_16x16x32_bf16 v[20:23], v[170:173], v[194:197], v[20:23]
	v_mfma_f32_16x16x32_bf16 v[16:19], v[178:181], v[194:197], v[16:19]
	s_setprio 2
	s_barrier
	v_mfma_f32_16x16x32_bf16 v[12:15], v[170:173], v[202:205], v[12:15]
	v_mfma_f32_16x16x32_bf16 v[8:11], v[178:181], v[202:205], v[8:11]
	v_mfma_f32_16x16x32_bf16 v[4:7], v[170:173], v[210:213], v[4:7]
	v_mfma_f32_16x16x32_bf16 v[0:3], v[178:181], v[210:213], v[0:3]
	s_setprio 0
	s_add_i32 vcc_hi, vcc_hi, 2
	s_add_u32 s76, s76, 0x100
	s_addc_u32 s77, s77, 0
	s_add_u32 s75, s75, 0x100
	s_addc_u32 vcc_lo, vcc_lo, 0
	s_cmp_gt_u32 vcc_hi, 29
	s_cbranch_scc0 .LBB0_374
	s_and_b64 vcc, exec, s[48:49]
	s_cbranch_vccz .LBB0_377
	s_barrier

; #define PG8_STAGE(bufoff, gbase, voff) do { _Pragma("unroll") for (int _i = 0; _i < 2; ++_i) \
;         __builtin_amdgcn_global_load_lds((const unsigned*)((const char*)(gbase) + (voff)[_i]), (PG8_LAS unsigned*)(lds + (bufoff) + ldsw + _i * 8192), 16, 0, 0); } while (0)
; #define PG8_LDA(dst, b, h) do { _Pragma("unroll") for (int m = 0; m < 4; ++m) _Pragma("unroll") for (int k = 0; k < 2; ++k) dst[m][k] = *(const PG8_LAS bf16x8*)(lds + PG8_SA(b, h) + aoff + m * 2048 + k * 1024); } while (0)
; #define PG8_LDB(dst, b, h) do { _Pragma("unroll") for (int n = 0; n < 2; ++n) _Pragma("unroll") for (int k = 0; k < 2; ++k) dst[n][k] = *(const PG8_LAS bf16x8*)(lds + PG8_SB(b, h) + boff + n * 2048 + k * 1024); } while (0)
; #define PG8_MMA(ai, bj, At, Bt) do { __builtin_amdgcn_s_setprio(1); _Pragma("unroll") for (int m = 0; m < 4; ++m) _Pragma("unroll") for (int n = 0; n < 2; ++n) _Pragma("unroll") for (int k = 0; k < 2; ++k) \
;         acc[ai][bj][m][n] = __builtin_amdgcn_mfma_f32_16x16x32_bf16(Bt[n][k], At[m][k], acc[ai][bj][m][n], 0, 0, 0); __builtin_amdgcn_s_setprio(0); } while (0)
; #define PG8_WAIT_V(n) asm volatile("s_waitcnt vmcnt(" #n ")" ::: "memory")
; #define PG8_WAIT_L(n) asm volatile("s_waitcnt lgkmcnt(" #n ")" ::: "memory")
; #define PG8_BAR __builtin_amdgcn_s_barrier()
; template <class Epi, class Sched, bool ALIGN_EPI = false, bool SP2 = false>
; __device__ __forceinline__ void gemm_phase(PG8_LAS unsigned char* lds, const Gemm g, const Sched& S, const Epi& E) {
;     ...
;             const bool last = (t == nt - 2);
;             const char* a1 = cA + (size_t)(t + 1) * kstep;
;             const char* a2 = last ? nA : cA + (size_t)(t + 2) * kstep; const char* b2 = last ? nB : cB + (size_t)(t + 2) * kstep;
;             const char* a3 = a2 + kstep; const char* b3 = b2 + kstep;
;             if constexpr (SP2) {
;             PG8_LDB(B0, 0, 0); PG8_LDB(B1, 0, 1); PG8_SCHED; PG8_LDA(At, 0, 0); PG8_STAGE(PG8_SA(1, 1), a1 + hstep, voffA);
;             PG8_WAIT_V(8); PG8_WAIT_L(0); PG8_BAR; PG8_MMA(0, 0, At, B0); PG8_MMA(0, 1, At, B1); PG8_BAR; PG8_SCHED;
;             PG8_LDA(At, 0, 1); PG8_STAGE(PG8_SB(0, 0), b2, voffB); PG8_STAGE(PG8_SB(0, 1), b2 + hstep, voffB); PG8_STAGE(PG8_SA(0, 0), a2, voffA);
;             PG8_WAIT_V(8); PG8_WAIT_L(0); PG8_BAR; PG8_MMA(1, 0, At, B0); PG8_MMA(1, 1, At, B1); PG8_BAR; PG8_SCHED;
.LBB0_410:
	ds_read_b128 v[166:169], v145
	ds_read_b128 v[170:173], v145 offset:1024
	ds_read_b128 v[174:177], v145 offset:2048
	ds_read_b128 v[178:181], v145 offset:3072
	ds_read_b128 v[182:185], v149
	ds_read_b128 v[186:189], v149 offset:1024
	ds_read_b128 v[190:193], v149 offset:2048
	ds_read_b128 v[194:197], v149 offset:3072
	s_add_u32 s52, s74, 0xfff80080
	s_addc_u32 s53, s75, -1
	s_cmp_eq_u32 s51, 4
	s_cselect_b32 s79, s55, s53
	s_cselect_b32 s78, s54, s52
	s_cselect_b32 s77, s69, s49
	s_cselect_b32 s76, s68, s37
	s_mov_b32 m0, s80
	v_lshl_add_u64 v[230:231], s[74:75], 0, v[160:161]
	ds_read_b128 v[198:201], v164
	ds_read_b128 v[202:205], v164 offset:1024
	ds_read_b128 v[206:209], v164 offset:2048
	ds_read_b128 v[210:213], v164 offset:3072
	ds_read_b128 v[214:217], v164 offset:4096
	ds_read_b128 v[218:221], v164 offset:5120
	ds_read_b128 v[222:225], v164 offset:6144
	ds_read_b128 v[226:229], v164 offset:7168
	global_load_lds_dwordx4 v[230:231], off
	v_lshl_add_u64 v[230:231], s[74:75], 0, v[162:163]
	s_mov_b32 m0, s81
	s_nop 0
	global_load_lds_dwordx4 v[230:231], off
	s_waitcnt vmcnt(8)
	s_waitcnt lgkmcnt(0)
	s_barrier
	s_setprio 1
	s_waitcnt lgkmcnt(0)
	v_mfma_f32_16x16x32_bf16 v[124:127], v[166:169], v[198:201], v[124:127]
	v_mfma_f32_16x16x32_bf16 v[120:123], v[174:177], v[198:201], v[120:123]
	v_mfma_f32_16x16x32_bf16 v[116:119], v[166:169], v[206:209], v[116:119]
	v_mfma_f32_16x16x32_bf16 v[108:111], v[174:177], v[206:209], v[108:111]
	v_mfma_f32_16x16x32_bf16 v[100:103], v[166:169], v[214:217], v[100:103]
	v_mfma_f32_16x16x32_bf16 v[92:95], v[174:177], v[214:217], v[92:95]
	v_mfma_f32_16x16x32_bf16 v[84:87], v[166:169], v[222:225], v[84:87]
	v_mfma_f32_16x16x32_bf16 v[76:79], v[174:177], v[222:225], v[76:79]
	v_mfma_f32_16x16x32_bf16 v[124:127], v[170:173], v[202:205], v[124:127]
	v_mfma_f32_16x16x32_bf16 v[120:123], v[178:181], v[202:205], v[120:123]
	v_mfma_f32_16x16x32_bf16 v[116:119], v[170:173], v[210:213], v[116:119]
	v_mfma_f32_16x16x32_bf16 v[108:111], v[178:181], v[210:213], v[108:111]
	v_mfma_f32_16x16x32_bf16 v[100:103], v[170:173], v[218:221], v[100:103]
	v_mfma_f32_16x16x32_bf16 v[92:95], v[178:181], v[218:221], v[92:95]
	v_mfma_f32_16x16x32_bf16 v[84:87], v[170:173], v[226:229], v[84:87]
	v_mfma_f32_16x16x32_bf16 v[76:79], v[178:181], v[226:229], v[76:79]
	s_setprio 0
	s_setprio 1
	v_mfma_f32_16x16x32_bf16 v[112:115], v[182:185], v[198:201], v[112:115]
	v_mfma_f32_16x16x32_bf16 v[104:107], v[190:193], v[198:201], v[104:107]
	v_mfma_f32_16x16x32_bf16 v[96:99], v[182:185], v[206:209], v[96:99]
	v_mfma_f32_16x16x32_bf16 v[88:91], v[190:193], v[206:209], v[88:91]
	v_mfma_f32_16x16x32_bf16 v[80:83], v[182:185], v[214:217], v[80:83]
	v_mfma_f32_16x16x32_bf16 v[72:75], v[190:193], v[214:217], v[72:75]
	v_mfma_f32_16x16x32_bf16 v[68:71], v[182:185], v[222:225], v[68:71]
	v_mfma_f32_16x16x32_bf16 v[64:67], v[190:193], v[222:225], v[64:67]
	v_mfma_f32_16x16x32_bf16 v[112:115], v[186:189], v[202:205], v[112:115]
	v_mfma_f32_16x16x32_bf16 v[104:107], v[194:197], v[202:205], v[104:107]
	v_mfma_f32_16x16x32_bf16 v[96:99], v[186:189], v[210:213], v[96:99]
	v_mfma_f32_16x16x32_bf16 v[88:91], v[194:197], v[210:213], v[88:91]
	s_setprio 2
	s_barrier
	v_mfma_f32_16x16x32_bf16 v[80:83], v[186:189], v[218:221], v[80:83]
	v_mfma_f32_16x16x32_bf16 v[72:75], v[194:197], v[218:221], v[72:75]
	v_mfma_f32_16x16x32_bf16 v[68:71], v[186:189], v[226:229], v[68:71]
	v_mfma_f32_16x16x32_bf16 v[64:67], v[194:197], v[226:229], v[64:67]
	s_setprio 0
	s_mov_b32 m0, s84
	v_lshl_add_u64 v[230:231], s[76:77], 0, v[138:139]
	s_add_u32 s52, s76, 0x80000
	ds_read_b128 v[198:201], v164 offset:16384
	ds_read_b128 v[202:205], v164 offset:17408
	ds_read_b128 v[206:209], v164 offset:18432
	ds_read_b128 v[210:213], v164 offset:19456
	ds_read_b128 v[214:217], v164 offset:20480
	ds_read_b128 v[218:221], v164 offset:21504
	ds_read_b128 v[222:225], v164 offset:22528
	ds_read_b128 v[226:229], v164 offset:23552
	global_load_lds_dwordx4 v[230:231], off
	v_lshl_add_u64 v[232:233], s[76:77], 0, v[142:143]
	s_mov_b32 m0, s85
	s_addc_u32 s53, s77, 0
	global_load_lds_dwordx4 v[232:233], off
	v_lshl_add_u64 v[234:235], s[52:53], 0, v[138:139]
	s_mov_b32 m0, s86
	v_lshl_add_u64 v[236:237], s[78:79], 0, v[140:141]
	global_load_lds_dwordx4 v[234:235], off
	v_lshl_add_u64 v[234:235], s[52:53], 0, v[142:143]
	s_mov_b32 m0, s87
	s_nop 0
	global_load_lds_dwordx4 v[234:235], off
	v_lshl_add_u64 v[234:235], s[78:79], 0, v[136:137]
	s_mov_b32 m0, s10
	s_nop 0
	global_load_lds_dwordx4 v[234:235], off
	s_mov_b32 m0, s11
	s_nop 0
	global_load_lds_dwordx4 v[236:237], off
	s_waitcnt vmcnt(8)
	s_waitcnt lgkmcnt(0)
	s_barrier
; #define PG8_STAGE(bufoff, gbase, voff) do { _Pragma("unroll") for (int _i = 0; _i < 2; ++_i) \
;         __builtin_amdgcn_global_load_lds((const unsigned*)((const char*)(gbase) + (voff)[_i]), (PG8_LAS unsigned*)(lds + (bufoff) + ldsw + _i * 8192), 16, 0, 0); } while (0)
; #define PG8_LDA(dst, b, h) do { _Pragma("unroll") for (int m = 0; m < 4; ++m) _Pragma("unroll") for (int k = 0; k < 2; ++k) dst[m][k] = *(const PG8_LAS bf16x8*)(lds + PG8_SA(b, h) + aoff + m * 2048 + k * 1024); } while (0)
; #define PG8_LDB(dst, b, h) do { _Pragma("unroll") for (int n = 0; n < 2; ++n) _Pragma("unroll") for (int k = 0; k < 2; ++k) dst[n][k] = *(const PG8_LAS bf16x8*)(lds + PG8_SB(b, h) + boff + n * 2048 + k * 1024); } while (0)
; #define PG8_MMA(ai, bj, At, Bt) do { __builtin_amdgcn_s_setprio(1); _Pragma("unroll") for (int m = 0; m < 4; ++m) _Pragma("unroll") for (int n = 0; n < 2; ++n) _Pragma("unroll") for (int k = 0; k < 2; ++k) \
;         acc[ai][bj][m][n] = __builtin_amdgcn_mfma_f32_16x16x32_bf16(Bt[n][k], At[m][k], acc[ai][bj][m][n], 0, 0, 0); __builtin_amdgcn_s_setprio(0); } while (0)
; #define PG8_WAIT_V(n) asm volatile("s_waitcnt vmcnt(" #n ")" ::: "memory")
; #define PG8_WAIT_L(n) asm volatile("s_waitcnt lgkmcnt(" #n ")" ::: "memory")
; #define PG8_BAR __builtin_amdgcn_s_barrier()
; #define PG8_SCHED __builtin_amdgcn_sched_barrier(0)
; template <class Epi, class Sched, bool ALIGN_EPI = false, bool SP2 = false>
; __device__ __forceinline__ void gemm_phase(PG8_LAS unsigned char* lds, const Gemm g, const Sched& S, const Epi& E) {
;     ...
;             PG8_WAIT_V(8); PG8_WAIT_L(0); PG8_BAR; PG8_MMA(1, 0, At, B0); PG8_MMA(1, 1, At, B1); PG8_BAR; PG8_SCHED;
;             PG8_LDB(B0, 1, 0); PG8_LDB(B1, 1, 1); PG8_SCHED; PG8_LDA(At, 1, 0); PG8_STAGE(PG8_SA(0, 1), a2 + hstep, voffA);
;             PG8_WAIT_V(8); PG8_WAIT_L(0); PG8_BAR; PG8_MMA(0, 0, At, B0); PG8_MMA(0, 1, At, B1); PG8_BAR; PG8_SCHED;
;             PG8_LDA(At, 1, 1); PG8_STAGE(PG8_SB(1, 0), b3, voffB); PG8_STAGE(PG8_SB(1, 1), b3 + hstep, voffB); PG8_STAGE(PG8_SA(1, 0), a3, voffA);
;             PG8_WAIT_V(8); PG8_WAIT_L(0); PG8_BAR; PG8_MMA(1, 0, At, B0); PG8_MMA(1, 1, At, B1); PG8_BAR; PG8_SCHED;
	s_setprio 1
	s_waitcnt lgkmcnt(0)
	v_mfma_f32_16x16x32_bf16 v[60:63], v[166:169], v[198:201], v[60:63]
	v_mfma_f32_16x16x32_bf16 v[56:59], v[174:177], v[198:201], v[56:59]
	v_mfma_f32_16x16x32_bf16 v[52:55], v[166:169], v[206:209], v[52:55]
	v_mfma_f32_16x16x32_bf16 v[44:47], v[174:177], v[206:209], v[44:47]
	v_mfma_f32_16x16x32_bf16 v[36:39], v[166:169], v[214:217], v[36:39]
	v_mfma_f32_16x16x32_bf16 v[28:31], v[174:177], v[214:217], v[28:31]
	v_mfma_f32_16x16x32_bf16 v[20:23], v[166:169], v[222:225], v[20:23]
	v_mfma_f32_16x16x32_bf16 v[12:15], v[174:177], v[222:225], v[12:15]
	v_mfma_f32_16x16x32_bf16 v[60:63], v[170:173], v[202:205], v[60:63]
	v_mfma_f32_16x16x32_bf16 v[56:59], v[178:181], v[202:205], v[56:59]
	v_mfma_f32_16x16x32_bf16 v[52:55], v[170:173], v[210:213], v[52:55]
	v_mfma_f32_16x16x32_bf16 v[44:47], v[178:181], v[210:213], v[44:47]
	v_mfma_f32_16x16x32_bf16 v[36:39], v[170:173], v[218:221], v[36:39]
	v_mfma_f32_16x16x32_bf16 v[28:31], v[178:181], v[218:221], v[28:31]
	v_mfma_f32_16x16x32_bf16 v[20:23], v[170:173], v[226:229], v[20:23]
	v_mfma_f32_16x16x32_bf16 v[12:15], v[178:181], v[226:229], v[12:15]
	s_setprio 0
	s_setprio 1
	v_mfma_f32_16x16x32_bf16 v[48:51], v[182:185], v[198:201], v[48:51]
	v_mfma_f32_16x16x32_bf16 v[40:43], v[190:193], v[198:201], v[40:43]
	v_mfma_f32_16x16x32_bf16 v[32:35], v[182:185], v[206:209], v[32:35]
	v_mfma_f32_16x16x32_bf16 v[24:27], v[190:193], v[206:209], v[24:27]
	v_mfma_f32_16x16x32_bf16 v[16:19], v[182:185], v[214:217], v[16:19]
	v_mfma_f32_16x16x32_bf16 v[8:11], v[190:193], v[214:217], v[8:11]
	v_mfma_f32_16x16x32_bf16 v[4:7], v[182:185], v[222:225], v[4:7]
	v_mfma_f32_16x16x32_bf16 v[0:3], v[190:193], v[222:225], v[0:3]
	v_mfma_f32_16x16x32_bf16 v[48:51], v[186:189], v[202:205], v[48:51]
	v_mfma_f32_16x16x32_bf16 v[40:43], v[194:197], v[202:205], v[40:43]
	v_mfma_f32_16x16x32_bf16 v[32:35], v[186:189], v[210:213], v[32:35]
	v_mfma_f32_16x16x32_bf16 v[24:27], v[194:197], v[210:213], v[24:27]
	s_setprio 2
	s_barrier
	v_mfma_f32_16x16x32_bf16 v[16:19], v[186:189], v[218:221], v[16:19]
	v_mfma_f32_16x16x32_bf16 v[8:11], v[194:197], v[218:221], v[8:11]
	v_mfma_f32_16x16x32_bf16 v[4:7], v[186:189], v[226:229], v[4:7]
	v_mfma_f32_16x16x32_bf16 v[0:3], v[194:197], v[226:229], v[0:3]
	s_setprio 0
	ds_read_b128 v[166:169], v148
	ds_read_b128 v[170:173], v148 offset:1024
	ds_read_b128 v[174:177], v148 offset:2048
	ds_read_b128 v[178:181], v148 offset:3072
	ds_read_b128 v[182:185], v165
	ds_read_b128 v[186:189], v165 offset:1024
	ds_read_b128 v[190:193], v165 offset:2048
	ds_read_b128 v[194:197], v165 offset:3072
	s_add_u32 s52, s78, 0x80000
	s_addc_u32 s53, s79, 0
	s_mov_b32 m0, s28
	v_lshl_add_u64 v[238:239], s[52:53], 0, v[136:137]
	ds_read_b128 v[198:201], v164 offset:32768
	ds_read_b128 v[202:205], v164 offset:33792
	ds_read_b128 v[206:209], v164 offset:34816
	ds_read_b128 v[210:213], v164 offset:35840
	ds_read_b128 v[214:217], v164 offset:36864
	ds_read_b128 v[218:221], v164 offset:37888
	ds_read_b128 v[222:225], v164 offset:38912
	ds_read_b128 v[226:229], v164 offset:39936
	global_load_lds_dwordx4 v[238:239], off
	v_lshl_add_u64 v[238:239], s[52:53], 0, v[140:141]
	s_mov_b32 m0, s29
	s_nop 0
	global_load_lds_dwordx4 v[238:239], off
	s_waitcnt vmcnt(8)
	s_waitcnt lgkmcnt(0)
	s_barrier
	s_setprio 1
	s_waitcnt lgkmcnt(0)
	v_mfma_f32_16x16x32_bf16 v[124:127], v[166:169], v[198:201], v[124:127]
	v_mfma_f32_16x16x32_bf16 v[120:123], v[174:177], v[198:201], v[120:123]
	v_mfma_f32_16x16x32_bf16 v[116:119], v[166:169], v[206:209], v[116:119]
	v_mfma_f32_16x16x32_bf16 v[108:111], v[174:177], v[206:209], v[108:111]
	v_mfma_f32_16x16x32_bf16 v[100:103], v[166:169], v[214:217], v[100:103]
	v_mfma_f32_16x16x32_bf16 v[92:95], v[174:177], v[214:217], v[92:95]
	v_mfma_f32_16x16x32_bf16 v[84:87], v[166:169], v[222:225], v[84:87]
	v_mfma_f32_16x16x32_bf16 v[76:79], v[174:177], v[222:225], v[76:79]
	v_mfma_f32_16x16x32_bf16 v[124:127], v[170:173], v[202:205], v[124:127]
	v_mfma_f32_16x16x32_bf16 v[120:123], v[178:181], v[202:205], v[120:123]
	v_mfma_f32_16x16x32_bf16 v[116:119], v[170:173], v[210:213], v[116:119]
	v_mfma_f32_16x16x32_bf16 v[108:111], v[178:181], v[210:213], v[108:111]
	v_mfma_f32_16x16x32_bf16 v[100:103], v[170:173], v[218:221], v[100:103]
	v_mfma_f32_16x16x32_bf16 v[92:95], v[178:181], v[218:221], v[92:95]
	v_mfma_f32_16x16x32_bf16 v[84:87], v[170:173], v[226:229], v[84:87]
	v_mfma_f32_16x16x32_bf16 v[76:79], v[178:181], v[226:229], v[76:79]
	s_setprio 0
	s_setprio 1
	v_mfma_f32_16x16x32_bf16 v[112:115], v[182:185], v[198:201], v[112:115]
	v_mfma_f32_16x16x32_bf16 v[104:107], v[190:193], v[198:201], v[104:107]
	v_mfma_f32_16x16x32_bf16 v[96:99], v[182:185], v[206:209], v[96:99]
	v_mfma_f32_16x16x32_bf16 v[88:91], v[190:193], v[206:209], v[88:91]
	v_mfma_f32_16x16x32_bf16 v[80:83], v[182:185], v[214:217], v[80:83]
	v_mfma_f32_16x16x32_bf16 v[72:75], v[190:193], v[214:217], v[72:75]
	v_mfma_f32_16x16x32_bf16 v[68:71], v[182:185], v[222:225], v[68:71]
	v_mfma_f32_16x16x32_bf16 v[64:67], v[190:193], v[222:225], v[64:67]
	v_mfma_f32_16x16x32_bf16 v[112:115], v[186:189], v[202:205], v[112:115]
	v_mfma_f32_16x16x32_bf16 v[104:107], v[194:197], v[202:205], v[104:107]
	v_mfma_f32_16x16x32_bf16 v[96:99], v[186:189], v[210:213], v[96:99]
	v_mfma_f32_16x16x32_bf16 v[88:91], v[194:197], v[210:213], v[88:91]
	s_setprio 2
	s_barrier
; #define PG8_STAGE(bufoff, gbase, voff) do { _Pragma("unroll") for (int _i = 0; _i < 2; ++_i) \
;         __builtin_amdgcn_global_load_lds((const unsigned*)((const char*)(gbase) + (voff)[_i]), (PG8_LAS unsigned*)(lds + (bufoff) + ldsw + _i * 8192), 16, 0, 0); } while (0)
; #define PG8_LDA(dst, b, h) do { _Pragma("unroll") for (int m = 0; m < 4; ++m) _Pragma("unroll") for (int k = 0; k < 2; ++k) dst[m][k] = *(const PG8_LAS bf16x8*)(lds + PG8_SA(b, h) + aoff + m * 2048 + k * 1024); } while (0)
; #define PG8_MMA(ai, bj, At, Bt) do { __builtin_amdgcn_s_setprio(1); _Pragma("unroll") for (int m = 0; m < 4; ++m) _Pragma("unroll") for (int n = 0; n < 2; ++n) _Pragma("unroll") for (int k = 0; k < 2; ++k) \
;         acc[ai][bj][m][n] = __builtin_amdgcn_mfma_f32_16x16x32_bf16(Bt[n][k], At[m][k], acc[ai][bj][m][n], 0, 0, 0); __builtin_amdgcn_s_setprio(0); } while (0)
; #define PG8_WAIT_V(n) asm volatile("s_waitcnt vmcnt(" #n ")" ::: "memory")
; #define PG8_WAIT_L(n) asm volatile("s_waitcnt lgkmcnt(" #n ")" ::: "memory")
; #define PG8_BAR __builtin_amdgcn_s_barrier()
; #define PG8_SCHED __builtin_amdgcn_sched_barrier(0)
; template <class Epi, class Sched, bool ALIGN_EPI = false, bool SP2 = false>
; __device__ __forceinline__ void gemm_phase(PG8_LAS unsigned char* lds, const Gemm g, const Sched& S, const Epi& E) {
;     ...
;         for (int t = 0; t < nt; t += 2) {
;             const bool last = (t == nt - 2);
;             const char* a1 = cA + (size_t)(t + 1) * kstep;
;             const char* a2 = last ? nA : cA + (size_t)(t + 2) * kstep; const char* b2 = last ? nB : cB + (size_t)(t + 2) * kstep;
;             const char* a3 = a2 + kstep; const char* b3 = b2 + kstep;
;     ...
;             PG8_WAIT_V(8); PG8_WAIT_L(0); PG8_BAR; PG8_MMA(0, 0, At, B0); PG8_MMA(0, 1, At, B1); PG8_BAR; PG8_SCHED;
;             PG8_LDA(At, 1, 1); PG8_STAGE(PG8_SB(1, 0), b3, voffB); PG8_STAGE(PG8_SB(1, 1), b3 + hstep, voffB); PG8_STAGE(PG8_SA(1, 0), a3, voffA);
;             PG8_WAIT_V(8); PG8_WAIT_L(0); PG8_BAR; PG8_MMA(1, 0, At, B0); PG8_MMA(1, 1, At, B1); PG8_BAR; PG8_SCHED;
	v_mfma_f32_16x16x32_bf16 v[80:83], v[186:189], v[218:221], v[80:83]
	v_mfma_f32_16x16x32_bf16 v[72:75], v[194:197], v[218:221], v[72:75]
	v_mfma_f32_16x16x32_bf16 v[68:71], v[186:189], v[226:229], v[68:71]
	v_mfma_f32_16x16x32_bf16 v[64:67], v[194:197], v[226:229], v[64:67]
	s_setprio 0
	s_mov_b32 m0, s89
	v_lshl_add_u64 v[230:231], v[230:231], 0, s[12:13]
	ds_read_b128 v[198:201], v164 offset:49152
	ds_read_b128 v[202:205], v164 offset:50176
	ds_read_b128 v[206:209], v164 offset:51200
	ds_read_b128 v[210:213], v164 offset:52224
	ds_read_b128 v[214:217], v164 offset:53248
	ds_read_b128 v[218:221], v164 offset:54272
	ds_read_b128 v[222:225], v164 offset:55296
	ds_read_b128 v[226:229], v164 offset:56320
	global_load_lds_dwordx4 v[230:231], off
	s_add_i32 m0, s89, 0x2000
	s_add_u32 s52, s76, 0x80080
	v_lshl_add_u64 v[230:231], v[232:233], 0, s[12:13]
	s_addc_u32 s53, s77, 0
	s_add_i32 s56, s88, s3
	global_load_lds_dwordx4 v[230:231], off
	v_lshl_add_u64 v[230:231], s[52:53], 0, v[138:139]
	s_mov_b32 m0, s56
	s_nop 0
	global_load_lds_dwordx4 v[230:231], off
	v_lshl_add_u64 v[230:231], s[52:53], 0, v[142:143]
	s_add_i32 m0, s56, 0x2000
	s_nop 0
	global_load_lds_dwordx4 v[230:231], off
	v_lshl_add_u64 v[230:231], v[234:235], 0, s[12:13]
	s_mov_b32 m0, s38
	s_nop 0
	global_load_lds_dwordx4 v[230:231], off
	v_lshl_add_u64 v[230:231], v[236:237], 0, s[12:13]
	s_mov_b32 m0, s39
	s_nop 0
	global_load_lds_dwordx4 v[230:231], off
	s_waitcnt vmcnt(8)
	s_waitcnt lgkmcnt(0)
	s_barrier
	s_setprio 1
	s_waitcnt lgkmcnt(0)
	v_mfma_f32_16x16x32_bf16 v[60:63], v[166:169], v[198:201], v[60:63]
	v_mfma_f32_16x16x32_bf16 v[56:59], v[174:177], v[198:201], v[56:59]
	v_mfma_f32_16x16x32_bf16 v[52:55], v[166:169], v[206:209], v[52:55]
	v_mfma_f32_16x16x32_bf16 v[44:47], v[174:177], v[206:209], v[44:47]
	v_mfma_f32_16x16x32_bf16 v[36:39], v[166:169], v[214:217], v[36:39]
	v_mfma_f32_16x16x32_bf16 v[28:31], v[174:177], v[214:217], v[28:31]
	v_mfma_f32_16x16x32_bf16 v[20:23], v[166:169], v[222:225], v[20:23]
	v_mfma_f32_16x16x32_bf16 v[12:15], v[174:177], v[222:225], v[12:15]
	v_mfma_f32_16x16x32_bf16 v[60:63], v[170:173], v[202:205], v[60:63]
	v_mfma_f32_16x16x32_bf16 v[56:59], v[178:181], v[202:205], v[56:59]
	v_mfma_f32_16x16x32_bf16 v[52:55], v[170:173], v[210:213], v[52:55]
	v_mfma_f32_16x16x32_bf16 v[44:47], v[178:181], v[210:213], v[44:47]
	v_mfma_f32_16x16x32_bf16 v[36:39], v[170:173], v[218:221], v[36:39]
	v_mfma_f32_16x16x32_bf16 v[28:31], v[178:181], v[218:221], v[28:31]
	v_mfma_f32_16x16x32_bf16 v[20:23], v[170:173], v[226:229], v[20:23]
	v_mfma_f32_16x16x32_bf16 v[12:15], v[178:181], v[226:229], v[12:15]
	s_setprio 0
	s_setprio 1
	v_mfma_f32_16x16x32_bf16 v[48:51], v[182:185], v[198:201], v[48:51]
	v_mfma_f32_16x16x32_bf16 v[40:43], v[190:193], v[198:201], v[40:43]
	v_mfma_f32_16x16x32_bf16 v[32:35], v[182:185], v[206:209], v[32:35]
	v_mfma_f32_16x16x32_bf16 v[24:27], v[190:193], v[206:209], v[24:27]
	v_mfma_f32_16x16x32_bf16 v[16:19], v[182:185], v[214:217], v[16:19]
	v_mfma_f32_16x16x32_bf16 v[8:11], v[190:193], v[214:217], v[8:11]
	v_mfma_f32_16x16x32_bf16 v[4:7], v[182:185], v[222:225], v[4:7]
	v_mfma_f32_16x16x32_bf16 v[0:3], v[190:193], v[222:225], v[0:3]
	v_mfma_f32_16x16x32_bf16 v[48:51], v[186:189], v[202:205], v[48:51]
	v_mfma_f32_16x16x32_bf16 v[40:43], v[194:197], v[202:205], v[40:43]
	v_mfma_f32_16x16x32_bf16 v[32:35], v[186:189], v[210:213], v[32:35]
	v_mfma_f32_16x16x32_bf16 v[24:27], v[194:197], v[210:213], v[24:27]
	s_setprio 2
	s_barrier
	v_mfma_f32_16x16x32_bf16 v[16:19], v[186:189], v[218:221], v[16:19]
	v_mfma_f32_16x16x32_bf16 v[8:11], v[194:197], v[218:221], v[8:11]
	v_mfma_f32_16x16x32_bf16 v[4:7], v[186:189], v[226:229], v[4:7]
	v_mfma_f32_16x16x32_bf16 v[0:3], v[194:197], v[226:229], v[0:3]
	s_setprio 0
	s_add_i32 s51, s51, 2
	s_add_u32 s74, s74, 0x100
	s_addc_u32 s75, s75, 0
	s_add_u32 s37, s37, 0x100
	s_addc_u32 s49, s49, 0
	s_cmp_gt_u32 s51, 5
	s_cbranch_scc0 .LBB0_410
	s_and_b64 vcc, exec, s[14:15]
	s_cbranch_vccz .LBB0_413
	s_barrier

; #define PG8_STAGE(bufoff, gbase, voff) do { _Pragma("unroll") for (int _i = 0; _i < 2; ++_i) \
;         __builtin_amdgcn_global_load_lds((const unsigned*)((const char*)(gbase) + (voff)[_i]), (PG8_LAS unsigned*)(lds + (bufoff) + ldsw + _i * 8192), 16, 0, 0); } while (0)
; #define PG8_LDA(dst, b, h) do { _Pragma("unroll") for (int m = 0; m < 4; ++m) _Pragma("unroll") for (int k = 0; k < 2; ++k) dst[m][k] = *(const PG8_LAS bf16x8*)(lds + PG8_SA(b, h) + aoff + m * 2048 + k * 1024); } while (0)
; #define PG8_LDB(dst, b, h) do { _Pragma("unroll") for (int n = 0; n < 2; ++n) _Pragma("unroll") for (int k = 0; k < 2; ++k) dst[n][k] = *(const PG8_LAS bf16x8*)(lds + PG8_SB(b, h) + boff + n * 2048 + k * 1024); } while (0)
; #define PG8_MMA(ai, bj, At, Bt) do { __builtin_amdgcn_s_setprio(1); _Pragma("unroll") for (int m = 0; m < 4; ++m) _Pragma("unroll") for (int n = 0; n < 2; ++n) _Pragma("unroll") for (int k = 0; k < 2; ++k) \
;         acc[ai][bj][m][n] = __builtin_amdgcn_mfma_f32_16x16x32_bf16(Bt[n][k], At[m][k], acc[ai][bj][m][n], 0, 0, 0); __builtin_amdgcn_s_setprio(0); } while (0)
; #define PG8_WAIT_V(n) asm volatile("s_waitcnt vmcnt(" #n ")" ::: "memory")
; #define PG8_WAIT_L(n) asm volatile("s_waitcnt lgkmcnt(" #n ")" ::: "memory")
; #define PG8_BAR __builtin_amdgcn_s_barrier()
; template <class Epi, class Sched, bool ALIGN_EPI = false, bool SP2 = false>
; __device__ __forceinline__ void gemm_phase(PG8_LAS unsigned char* lds, const Gemm g, const Sched& S, const Epi& E) {
;     ...
;             const bool last = (t == nt - 2);
;             const char* a1 = cA + (size_t)(t + 1) * kstep;
;             const char* a2 = last ? nA : cA + (size_t)(t + 2) * kstep; const char* b2 = last ? nB : cB + (size_t)(t + 2) * kstep;
;             const char* a3 = a2 + kstep; const char* b3 = b2 + kstep;
;             if constexpr (SP2) {
;             PG8_LDB(B0, 0, 0); PG8_LDB(B1, 0, 1); PG8_SCHED; PG8_LDA(At, 0, 0); PG8_STAGE(PG8_SA(1, 1), a1 + hstep, voffA);
;             PG8_WAIT_V(8); PG8_WAIT_L(0); PG8_BAR; PG8_MMA(0, 0, At, B0); PG8_MMA(0, 1, At, B1); PG8_BAR; PG8_SCHED;
;             PG8_LDA(At, 0, 1); PG8_STAGE(PG8_SB(0, 0), b2, voffB); PG8_STAGE(PG8_SB(0, 1), b2 + hstep, voffB); PG8_STAGE(PG8_SA(0, 0), a2, voffA);
;             PG8_WAIT_V(8); PG8_WAIT_L(0); PG8_BAR; PG8_MMA(1, 0, At, B0); PG8_MMA(1, 1, At, B1); PG8_BAR; PG8_SCHED;
.LBB0_545:
	ds_read_b128 v[112:115], v174
	ds_read_b128 v[116:119], v174 offset:1024
	ds_read_b128 v[120:123], v174 offset:2048
	ds_read_b128 v[124:127], v174 offset:3072
	ds_read_b128 v[164:167], v175
	ds_read_b128 v[168:171], v175 offset:1024
	ds_read_b128 v[178:181], v175 offset:2048
	ds_read_b128 v[182:185], v175 offset:3072
	s_add_u32 s52, s68, 0xfff80080
	s_addc_u32 s53, s69, -1
	s_cmp_eq_u32 s88, 28
	s_cselect_b32 s73, s41, s53
	s_cselect_b32 s72, s84, s52
	s_cselect_b32 s71, s37, s87
	s_cselect_b32 s70, s85, s86
	v_lshl_add_u64 v[218:219], s[68:69], 0, v[156:157]
	s_add_i32 m0, s39, 0xc000
	ds_read_b128 v[186:189], v176
	ds_read_b128 v[190:193], v176 offset:1024
	ds_read_b128 v[194:197], v176 offset:2048
	ds_read_b128 v[198:201], v176 offset:3072
	ds_read_b128 v[202:205], v176 offset:4096
	ds_read_b128 v[206:209], v176 offset:5120
	ds_read_b128 v[210:213], v176 offset:6144
	ds_read_b128 v[214:217], v176 offset:7168
	global_load_lds_dwordx4 v[218:219], off
	v_lshl_add_u64 v[218:219], s[68:69], 0, v[158:159]
	s_add_i32 m0, s39, 0xe000
	s_nop 0
	global_load_lds_dwordx4 v[218:219], off
	s_waitcnt vmcnt(8)
	s_waitcnt lgkmcnt(0)
	s_barrier
	s_setprio 1
	s_waitcnt lgkmcnt(0)
	v_mfma_f32_16x16x32_bf16 v[140:143], v[112:115], v[186:189], v[140:143]
	v_mfma_f32_16x16x32_bf16 v[136:139], v[120:123], v[186:189], v[136:139]
	v_mfma_f32_16x16x32_bf16 v[108:111], v[112:115], v[194:197], v[108:111]
	v_mfma_f32_16x16x32_bf16 v[104:107], v[120:123], v[194:197], v[104:107]
	v_mfma_f32_16x16x32_bf16 v[92:95], v[112:115], v[202:205], v[92:95]
	v_mfma_f32_16x16x32_bf16 v[88:91], v[120:123], v[202:205], v[88:91]
	v_mfma_f32_16x16x32_bf16 v[76:79], v[112:115], v[210:213], v[76:79]
	v_mfma_f32_16x16x32_bf16 v[72:75], v[120:123], v[210:213], v[72:75]
	v_mfma_f32_16x16x32_bf16 v[140:143], v[116:119], v[190:193], v[140:143]
	v_mfma_f32_16x16x32_bf16 v[136:139], v[124:127], v[190:193], v[136:139]
	v_mfma_f32_16x16x32_bf16 v[108:111], v[116:119], v[198:201], v[108:111]
	v_mfma_f32_16x16x32_bf16 v[104:107], v[124:127], v[198:201], v[104:107]
	v_mfma_f32_16x16x32_bf16 v[92:95], v[116:119], v[206:209], v[92:95]
	v_mfma_f32_16x16x32_bf16 v[88:91], v[124:127], v[206:209], v[88:91]
	v_mfma_f32_16x16x32_bf16 v[76:79], v[116:119], v[214:217], v[76:79]
	v_mfma_f32_16x16x32_bf16 v[72:75], v[124:127], v[214:217], v[72:75]
	s_setprio 0
	s_setprio 1
	v_mfma_f32_16x16x32_bf16 v[132:135], v[164:167], v[186:189], v[132:135]
	v_mfma_f32_16x16x32_bf16 v[128:131], v[178:181], v[186:189], v[128:131]
	v_mfma_f32_16x16x32_bf16 v[100:103], v[164:167], v[194:197], v[100:103]
	v_mfma_f32_16x16x32_bf16 v[96:99], v[178:181], v[194:197], v[96:99]
	v_mfma_f32_16x16x32_bf16 v[84:87], v[164:167], v[202:205], v[84:87]
	v_mfma_f32_16x16x32_bf16 v[80:83], v[178:181], v[202:205], v[80:83]
	v_mfma_f32_16x16x32_bf16 v[68:71], v[164:167], v[210:213], v[68:71]
	v_mfma_f32_16x16x32_bf16 v[64:67], v[178:181], v[210:213], v[64:67]
	v_mfma_f32_16x16x32_bf16 v[132:135], v[168:171], v[190:193], v[132:135]
	v_mfma_f32_16x16x32_bf16 v[128:131], v[182:185], v[190:193], v[128:131]
	v_mfma_f32_16x16x32_bf16 v[100:103], v[168:171], v[198:201], v[100:103]
	v_mfma_f32_16x16x32_bf16 v[96:99], v[182:185], v[198:201], v[96:99]
	s_setprio 2
	s_barrier
	v_mfma_f32_16x16x32_bf16 v[84:87], v[168:171], v[206:209], v[84:87]
	v_mfma_f32_16x16x32_bf16 v[80:83], v[182:185], v[206:209], v[80:83]
	v_mfma_f32_16x16x32_bf16 v[68:71], v[168:171], v[214:217], v[68:71]
	v_mfma_f32_16x16x32_bf16 v[64:67], v[182:185], v[214:217], v[64:67]
	s_setprio 0
	s_add_i32 s52, s81, s29
	v_lshl_add_u64 v[218:219], s[70:71], 0, v[152:153]
	s_mov_b32 m0, s52
	ds_read_b128 v[186:189], v176 offset:16384
	ds_read_b128 v[190:193], v176 offset:17408
	ds_read_b128 v[194:197], v176 offset:18432
	ds_read_b128 v[198:201], v176 offset:19456
	ds_read_b128 v[202:205], v176 offset:20480
	ds_read_b128 v[206:209], v176 offset:21504
	ds_read_b128 v[210:213], v176 offset:22528
	ds_read_b128 v[214:217], v176 offset:23552
	global_load_lds_dwordx4 v[218:219], off
	s_add_i32 m0, s52, 0x2000
	s_add_u32 s52, s70, 0x80000
	v_lshl_add_u64 v[220:221], s[70:71], 0, v[148:149]
	s_addc_u32 s53, s71, 0
	s_add_i32 s56, s82, s29
	global_load_lds_dwordx4 v[220:221], off
	v_lshl_add_u64 v[222:223], s[52:53], 0, v[152:153]
	s_mov_b32 m0, s56
	v_lshl_add_u64 v[224:225], s[72:73], 0, v[150:151]
	global_load_lds_dwordx4 v[222:223], off
	v_lshl_add_u64 v[222:223], s[52:53], 0, v[148:149]
	s_add_i32 m0, s56, 0x2000
	s_nop 0
	global_load_lds_dwordx4 v[222:223], off
	v_lshl_add_u64 v[222:223], s[72:73], 0, v[154:155]
	s_mov_b32 m0, s39
	s_nop 0
	global_load_lds_dwordx4 v[222:223], off
	s_mov_b32 m0, s55
	s_nop 0
	global_load_lds_dwordx4 v[224:225], off
	s_waitcnt vmcnt(8)
	s_waitcnt lgkmcnt(0)
	s_barrier
; #define PG8_STAGE(bufoff, gbase, voff) do { _Pragma("unroll") for (int _i = 0; _i < 2; ++_i) \
;         __builtin_amdgcn_global_load_lds((const unsigned*)((const char*)(gbase) + (voff)[_i]), (PG8_LAS unsigned*)(lds + (bufoff) + ldsw + _i * 8192), 16, 0, 0); } while (0)
; #define PG8_LDA(dst, b, h) do { _Pragma("unroll") for (int m = 0; m < 4; ++m) _Pragma("unroll") for (int k = 0; k < 2; ++k) dst[m][k] = *(const PG8_LAS bf16x8*)(lds + PG8_SA(b, h) + aoff + m * 2048 + k * 1024); } while (0)
; #define PG8_LDB(dst, b, h) do { _Pragma("unroll") for (int n = 0; n < 2; ++n) _Pragma("unroll") for (int k = 0; k < 2; ++k) dst[n][k] = *(const PG8_LAS bf16x8*)(lds + PG8_SB(b, h) + boff + n * 2048 + k * 1024); } while (0)
; #define PG8_MMA(ai, bj, At, Bt) do { __builtin_amdgcn_s_setprio(1); _Pragma("unroll") for (int m = 0; m < 4; ++m) _Pragma("unroll") for (int n = 0; n < 2; ++n) _Pragma("unroll") for (int k = 0; k < 2; ++k) \
;         acc[ai][bj][m][n] = __builtin_amdgcn_mfma_f32_16x16x32_bf16(Bt[n][k], At[m][k], acc[ai][bj][m][n], 0, 0, 0); __builtin_amdgcn_s_setprio(0); } while (0)
; #define PG8_WAIT_V(n) asm volatile("s_waitcnt vmcnt(" #n ")" ::: "memory")
; #define PG8_WAIT_L(n) asm volatile("s_waitcnt lgkmcnt(" #n ")" ::: "memory")
; #define PG8_BAR __builtin_amdgcn_s_barrier()
; #define PG8_SCHED __builtin_amdgcn_sched_barrier(0)
; template <class Epi, class Sched, bool ALIGN_EPI = false, bool SP2 = false>
; __device__ __forceinline__ void gemm_phase(PG8_LAS unsigned char* lds, const Gemm g, const Sched& S, const Epi& E) {
;     ...
;             PG8_WAIT_V(8); PG8_WAIT_L(0); PG8_BAR; PG8_MMA(1, 0, At, B0); PG8_MMA(1, 1, At, B1); PG8_BAR; PG8_SCHED;
;             PG8_LDB(B0, 1, 0); PG8_LDB(B1, 1, 1); PG8_SCHED; PG8_LDA(At, 1, 0); PG8_STAGE(PG8_SA(0, 1), a2 + hstep, voffA);
;             PG8_WAIT_V(8); PG8_WAIT_L(0); PG8_BAR; PG8_MMA(0, 0, At, B0); PG8_MMA(0, 1, At, B1); PG8_BAR; PG8_SCHED;
;             PG8_LDA(At, 1, 1); PG8_STAGE(PG8_SB(1, 0), b3, voffB); PG8_STAGE(PG8_SB(1, 1), b3 + hstep, voffB); PG8_STAGE(PG8_SA(1, 0), a3, voffA);
;             PG8_WAIT_V(8); PG8_WAIT_L(0); PG8_BAR; PG8_MMA(1, 0, At, B0); PG8_MMA(1, 1, At, B1); PG8_BAR; PG8_SCHED;
	s_setprio 1
	s_waitcnt lgkmcnt(0)
	v_mfma_f32_16x16x32_bf16 v[60:63], v[112:115], v[186:189], v[60:63]
	v_mfma_f32_16x16x32_bf16 v[56:59], v[120:123], v[186:189], v[56:59]
	v_mfma_f32_16x16x32_bf16 v[44:47], v[112:115], v[194:197], v[44:47]
	v_mfma_f32_16x16x32_bf16 v[40:43], v[120:123], v[194:197], v[40:43]
	v_mfma_f32_16x16x32_bf16 v[28:31], v[112:115], v[202:205], v[28:31]
	v_mfma_f32_16x16x32_bf16 v[24:27], v[120:123], v[202:205], v[24:27]
	v_mfma_f32_16x16x32_bf16 v[12:15], v[112:115], v[210:213], v[12:15]
	v_mfma_f32_16x16x32_bf16 v[8:11], v[120:123], v[210:213], v[8:11]
	v_mfma_f32_16x16x32_bf16 v[60:63], v[116:119], v[190:193], v[60:63]
	v_mfma_f32_16x16x32_bf16 v[56:59], v[124:127], v[190:193], v[56:59]
	v_mfma_f32_16x16x32_bf16 v[44:47], v[116:119], v[198:201], v[44:47]
	v_mfma_f32_16x16x32_bf16 v[40:43], v[124:127], v[198:201], v[40:43]
	v_mfma_f32_16x16x32_bf16 v[28:31], v[116:119], v[206:209], v[28:31]
	v_mfma_f32_16x16x32_bf16 v[24:27], v[124:127], v[206:209], v[24:27]
	v_mfma_f32_16x16x32_bf16 v[12:15], v[116:119], v[214:217], v[12:15]
	v_mfma_f32_16x16x32_bf16 v[8:11], v[124:127], v[214:217], v[8:11]
	s_setprio 0
	s_setprio 1
	v_mfma_f32_16x16x32_bf16 v[52:55], v[164:167], v[186:189], v[52:55]
	v_mfma_f32_16x16x32_bf16 v[48:51], v[178:181], v[186:189], v[48:51]
	v_mfma_f32_16x16x32_bf16 v[36:39], v[164:167], v[194:197], v[36:39]
	v_mfma_f32_16x16x32_bf16 v[32:35], v[178:181], v[194:197], v[32:35]
	v_mfma_f32_16x16x32_bf16 v[20:23], v[164:167], v[202:205], v[20:23]
	v_mfma_f32_16x16x32_bf16 v[16:19], v[178:181], v[202:205], v[16:19]
	v_mfma_f32_16x16x32_bf16 v[4:7], v[164:167], v[210:213], v[4:7]
	v_mfma_f32_16x16x32_bf16 v[0:3], v[178:181], v[210:213], v[0:3]
	v_mfma_f32_16x16x32_bf16 v[52:55], v[168:171], v[190:193], v[52:55]
	v_mfma_f32_16x16x32_bf16 v[48:51], v[182:185], v[190:193], v[48:51]
	v_mfma_f32_16x16x32_bf16 v[36:39], v[168:171], v[198:201], v[36:39]
	v_mfma_f32_16x16x32_bf16 v[32:35], v[182:185], v[198:201], v[32:35]
	s_setprio 2
	s_barrier
	v_mfma_f32_16x16x32_bf16 v[20:23], v[168:171], v[206:209], v[20:23]
	v_mfma_f32_16x16x32_bf16 v[16:19], v[182:185], v[206:209], v[16:19]
	v_mfma_f32_16x16x32_bf16 v[4:7], v[168:171], v[214:217], v[4:7]
	v_mfma_f32_16x16x32_bf16 v[0:3], v[182:185], v[214:217], v[0:3]
	s_setprio 0
	s_add_i32 s56, 0, 0x18000
	s_add_i32 s57, 0, 0x1c000
	v_add_u32_e32 v124, s56, v172
	v_add_u32_e32 v177, s57, v172
	ds_read_b128 v[112:115], v124
	ds_read_b128 v[116:119], v124 offset:1024
	ds_read_b128 v[120:123], v124 offset:2048
	ds_read_b128 v[124:127], v124 offset:3072
	ds_read_b128 v[164:167], v177
	ds_read_b128 v[168:171], v177 offset:1024
	ds_read_b128 v[178:181], v177 offset:2048
	ds_read_b128 v[182:185], v177 offset:3072
	s_add_u32 s52, s72, 0x80000
	s_addc_u32 s53, s73, 0
	s_mov_b32 m0, s74
	v_lshl_add_u64 v[226:227], s[52:53], 0, v[154:155]
	ds_read_b128 v[186:189], v176 offset:32768
	ds_read_b128 v[190:193], v176 offset:33792
	ds_read_b128 v[194:197], v176 offset:34816
	ds_read_b128 v[198:201], v176 offset:35840
	ds_read_b128 v[202:205], v176 offset:36864
	ds_read_b128 v[206:209], v176 offset:37888
	ds_read_b128 v[210:213], v176 offset:38912
	ds_read_b128 v[214:217], v176 offset:39936
	global_load_lds_dwordx4 v[226:227], off
	v_lshl_add_u64 v[226:227], s[52:53], 0, v[150:151]
	s_mov_b32 m0, s75
	s_nop 0
	global_load_lds_dwordx4 v[226:227], off
	s_waitcnt vmcnt(8)
	s_waitcnt lgkmcnt(0)
	s_barrier
	s_setprio 1
	s_waitcnt lgkmcnt(0)
	v_mfma_f32_16x16x32_bf16 v[140:143], v[112:115], v[186:189], v[140:143]
	v_mfma_f32_16x16x32_bf16 v[136:139], v[120:123], v[186:189], v[136:139]
	v_mfma_f32_16x16x32_bf16 v[108:111], v[112:115], v[194:197], v[108:111]
	v_mfma_f32_16x16x32_bf16 v[104:107], v[120:123], v[194:197], v[104:107]
	v_mfma_f32_16x16x32_bf16 v[92:95], v[112:115], v[202:205], v[92:95]
	v_mfma_f32_16x16x32_bf16 v[88:91], v[120:123], v[202:205], v[88:91]
	v_mfma_f32_16x16x32_bf16 v[76:79], v[112:115], v[210:213], v[76:79]
	v_mfma_f32_16x16x32_bf16 v[72:75], v[120:123], v[210:213], v[72:75]
	v_mfma_f32_16x16x32_bf16 v[140:143], v[116:119], v[190:193], v[140:143]
	v_mfma_f32_16x16x32_bf16 v[136:139], v[124:127], v[190:193], v[136:139]
	v_mfma_f32_16x16x32_bf16 v[108:111], v[116:119], v[198:201], v[108:111]
	v_mfma_f32_16x16x32_bf16 v[104:107], v[124:127], v[198:201], v[104:107]
	v_mfma_f32_16x16x32_bf16 v[92:95], v[116:119], v[206:209], v[92:95]
	v_mfma_f32_16x16x32_bf16 v[88:91], v[124:127], v[206:209], v[88:91]
	v_mfma_f32_16x16x32_bf16 v[76:79], v[116:119], v[214:217], v[76:79]
	v_mfma_f32_16x16x32_bf16 v[72:75], v[124:127], v[214:217], v[72:75]
	s_setprio 0
	s_setprio 1
	v_mfma_f32_16x16x32_bf16 v[132:135], v[164:167], v[186:189], v[132:135]
	v_mfma_f32_16x16x32_bf16 v[128:131], v[178:181], v[186:189], v[128:131]
	v_mfma_f32_16x16x32_bf16 v[100:103], v[164:167], v[194:197], v[100:103]
	v_mfma_f32_16x16x32_bf16 v[96:99], v[178:181], v[194:197], v[96:99]
	v_mfma_f32_16x16x32_bf16 v[84:87], v[164:167], v[202:205], v[84:87]
	v_mfma_f32_16x16x32_bf16 v[80:83], v[178:181], v[202:205], v[80:83]
	v_mfma_f32_16x16x32_bf16 v[68:71], v[164:167], v[210:213], v[68:71]
	v_mfma_f32_16x16x32_bf16 v[64:67], v[178:181], v[210:213], v[64:67]
	v_mfma_f32_16x16x32_bf16 v[132:135], v[168:171], v[190:193], v[132:135]
	v_mfma_f32_16x16x32_bf16 v[128:131], v[182:185], v[190:193], v[128:131]
	v_mfma_f32_16x16x32_bf16 v[100:103], v[168:171], v[198:201], v[100:103]
	v_mfma_f32_16x16x32_bf16 v[96:99], v[182:185], v[198:201], v[96:99]
	s_setprio 2
	s_barrier
; #define PG8_STAGE(bufoff, gbase, voff) do { _Pragma("unroll") for (int _i = 0; _i < 2; ++_i) \
;         __builtin_amdgcn_global_load_lds((const unsigned*)((const char*)(gbase) + (voff)[_i]), (PG8_LAS unsigned*)(lds + (bufoff) + ldsw + _i * 8192), 16, 0, 0); } while (0)
; #define PG8_LDA(dst, b, h) do { _Pragma("unroll") for (int m = 0; m < 4; ++m) _Pragma("unroll") for (int k = 0; k < 2; ++k) dst[m][k] = *(const PG8_LAS bf16x8*)(lds + PG8_SA(b, h) + aoff + m * 2048 + k * 1024); } while (0)
; #define PG8_MMA(ai, bj, At, Bt) do { __builtin_amdgcn_s_setprio(1); _Pragma("unroll") for (int m = 0; m < 4; ++m) _Pragma("unroll") for (int n = 0; n < 2; ++n) _Pragma("unroll") for (int k = 0; k < 2; ++k) \
;         acc[ai][bj][m][n] = __builtin_amdgcn_mfma_f32_16x16x32_bf16(Bt[n][k], At[m][k], acc[ai][bj][m][n], 0, 0, 0); __builtin_amdgcn_s_setprio(0); } while (0)
; #define PG8_WAIT_V(n) asm volatile("s_waitcnt vmcnt(" #n ")" ::: "memory")
; #define PG8_WAIT_L(n) asm volatile("s_waitcnt lgkmcnt(" #n ")" ::: "memory")
; #define PG8_BAR __builtin_amdgcn_s_barrier()
; #define PG8_SCHED __builtin_amdgcn_sched_barrier(0)
; template <class Epi, class Sched, bool ALIGN_EPI = false, bool SP2 = false>
; __device__ __forceinline__ void gemm_phase(PG8_LAS unsigned char* lds, const Gemm g, const Sched& S, const Epi& E) {
;     ...
;         for (int t = 0; t < nt; t += 2) {
;             const bool last = (t == nt - 2);
;             const char* a1 = cA + (size_t)(t + 1) * kstep;
;             const char* a2 = last ? nA : cA + (size_t)(t + 2) * kstep; const char* b2 = last ? nB : cB + (size_t)(t + 2) * kstep;
;             const char* a3 = a2 + kstep; const char* b3 = b2 + kstep;
;     ...
;             PG8_WAIT_V(8); PG8_WAIT_L(0); PG8_BAR; PG8_MMA(0, 0, At, B0); PG8_MMA(0, 1, At, B1); PG8_BAR; PG8_SCHED;
;             PG8_LDA(At, 1, 1); PG8_STAGE(PG8_SB(1, 0), b3, voffB); PG8_STAGE(PG8_SB(1, 1), b3 + hstep, voffB); PG8_STAGE(PG8_SA(1, 0), a3, voffA);
;             PG8_WAIT_V(8); PG8_WAIT_L(0); PG8_BAR; PG8_MMA(1, 0, At, B0); PG8_MMA(1, 1, At, B1); PG8_BAR; PG8_SCHED;
	v_mfma_f32_16x16x32_bf16 v[84:87], v[168:171], v[206:209], v[84:87]
	v_mfma_f32_16x16x32_bf16 v[80:83], v[182:185], v[206:209], v[80:83]
	v_mfma_f32_16x16x32_bf16 v[68:71], v[168:171], v[214:217], v[68:71]
	v_mfma_f32_16x16x32_bf16 v[64:67], v[182:185], v[214:217], v[64:67]
	s_setprio 0
	s_add_i32 s52, s56, s29
	v_lshl_add_u64 v[218:219], v[218:219], 0, s[12:13]
	s_mov_b32 m0, s52
	ds_read_b128 v[186:189], v176 offset:49152
	ds_read_b128 v[190:193], v176 offset:50176
	ds_read_b128 v[194:197], v176 offset:51200
	ds_read_b128 v[198:201], v176 offset:52224
	ds_read_b128 v[202:205], v176 offset:53248
	ds_read_b128 v[206:209], v176 offset:54272
	ds_read_b128 v[210:213], v176 offset:55296
	ds_read_b128 v[214:217], v176 offset:56320
	global_load_lds_dwordx4 v[218:219], off
	s_add_i32 m0, s52, 0x2000
	s_add_u32 s52, s70, 0x80080
	v_lshl_add_u64 v[218:219], v[220:221], 0, s[12:13]
	s_addc_u32 s53, s71, 0
	s_add_i32 s56, s57, s29
	global_load_lds_dwordx4 v[218:219], off
	v_lshl_add_u64 v[218:219], s[52:53], 0, v[152:153]
	s_mov_b32 m0, s56
	s_nop 0
	global_load_lds_dwordx4 v[218:219], off
	v_lshl_add_u64 v[218:219], s[52:53], 0, v[148:149]
	s_add_i32 m0, s56, 0x2000
	s_nop 0
	global_load_lds_dwordx4 v[218:219], off
	v_lshl_add_u64 v[218:219], v[222:223], 0, s[12:13]
	s_mov_b32 m0, s77
	s_nop 0
	global_load_lds_dwordx4 v[218:219], off
	v_lshl_add_u64 v[218:219], v[224:225], 0, s[12:13]
	s_mov_b32 m0, s78
	s_nop 0
	global_load_lds_dwordx4 v[218:219], off
	s_waitcnt vmcnt(8)
	s_waitcnt lgkmcnt(0)
	s_barrier
	s_setprio 1
	s_waitcnt lgkmcnt(0)
	v_mfma_f32_16x16x32_bf16 v[60:63], v[112:115], v[186:189], v[60:63]
	v_mfma_f32_16x16x32_bf16 v[56:59], v[120:123], v[186:189], v[56:59]
	v_mfma_f32_16x16x32_bf16 v[44:47], v[112:115], v[194:197], v[44:47]
	v_mfma_f32_16x16x32_bf16 v[40:43], v[120:123], v[194:197], v[40:43]
	v_mfma_f32_16x16x32_bf16 v[28:31], v[112:115], v[202:205], v[28:31]
	v_mfma_f32_16x16x32_bf16 v[24:27], v[120:123], v[202:205], v[24:27]
	v_mfma_f32_16x16x32_bf16 v[12:15], v[112:115], v[210:213], v[12:15]
	v_mfma_f32_16x16x32_bf16 v[8:11], v[120:123], v[210:213], v[8:11]
	v_mfma_f32_16x16x32_bf16 v[60:63], v[116:119], v[190:193], v[60:63]
	v_mfma_f32_16x16x32_bf16 v[56:59], v[124:127], v[190:193], v[56:59]
	v_mfma_f32_16x16x32_bf16 v[44:47], v[116:119], v[198:201], v[44:47]
	v_mfma_f32_16x16x32_bf16 v[40:43], v[124:127], v[198:201], v[40:43]
	v_mfma_f32_16x16x32_bf16 v[28:31], v[116:119], v[206:209], v[28:31]
	v_mfma_f32_16x16x32_bf16 v[24:27], v[124:127], v[206:209], v[24:27]
	v_mfma_f32_16x16x32_bf16 v[12:15], v[116:119], v[214:217], v[12:15]
	v_mfma_f32_16x16x32_bf16 v[8:11], v[124:127], v[214:217], v[8:11]
	s_setprio 0
	s_setprio 1
	v_mfma_f32_16x16x32_bf16 v[52:55], v[164:167], v[186:189], v[52:55]
	v_mfma_f32_16x16x32_bf16 v[48:51], v[178:181], v[186:189], v[48:51]
	v_mfma_f32_16x16x32_bf16 v[36:39], v[164:167], v[194:197], v[36:39]
	v_mfma_f32_16x16x32_bf16 v[32:35], v[178:181], v[194:197], v[32:35]
	v_mfma_f32_16x16x32_bf16 v[20:23], v[164:167], v[202:205], v[20:23]
	v_mfma_f32_16x16x32_bf16 v[16:19], v[178:181], v[202:205], v[16:19]
	v_mfma_f32_16x16x32_bf16 v[4:7], v[164:167], v[210:213], v[4:7]
	v_mfma_f32_16x16x32_bf16 v[0:3], v[178:181], v[210:213], v[0:3]
	v_mfma_f32_16x16x32_bf16 v[52:55], v[168:171], v[190:193], v[52:55]
	v_mfma_f32_16x16x32_bf16 v[48:51], v[182:185], v[190:193], v[48:51]
	v_mfma_f32_16x16x32_bf16 v[36:39], v[168:171], v[198:201], v[36:39]
	v_mfma_f32_16x16x32_bf16 v[32:35], v[182:185], v[198:201], v[32:35]
	s_setprio 2
	s_barrier
	v_mfma_f32_16x16x32_bf16 v[20:23], v[168:171], v[206:209], v[20:23]
	v_mfma_f32_16x16x32_bf16 v[16:19], v[182:185], v[206:209], v[16:19]
	v_mfma_f32_16x16x32_bf16 v[4:7], v[168:171], v[214:217], v[4:7]
	v_mfma_f32_16x16x32_bf16 v[0:3], v[182:185], v[214:217], v[0:3]
	s_setprio 0
	s_add_i32 s88, s88, 2
	s_add_u32 s68, s68, 0x100
	s_addc_u32 s69, s69, 0
	s_add_u32 s86, s86, 0x100
	s_addc_u32 s87, s87, 0
	s_cmp_gt_u32 s88, 29
	s_cbranch_scc0 .LBB0_545
	s_and_b64 vcc, exec, s[14:15]
	s_cbranch_vccz .LBB0_548
	s_barrier

; #define PG8_STAGE(bufoff, gbase, voff) do { _Pragma("unroll") for (int _i = 0; _i < 2; ++_i) \
;         __builtin_amdgcn_global_load_lds((const unsigned*)((const char*)(gbase) + (voff)[_i]), (PG8_LAS unsigned*)(lds + (bufoff) + ldsw + _i * 8192), 16, 0, 0); } while (0)
; #define PG8_LDA(dst, b, h) do { _Pragma("unroll") for (int m = 0; m < 4; ++m) _Pragma("unroll") for (int k = 0; k < 2; ++k) dst[m][k] = *(const PG8_LAS bf16x8*)(lds + PG8_SA(b, h) + aoff + m * 2048 + k * 1024); } while (0)
; #define PG8_LDB(dst, b, h) do { _Pragma("unroll") for (int n = 0; n < 2; ++n) _Pragma("unroll") for (int k = 0; k < 2; ++k) dst[n][k] = *(const PG8_LAS bf16x8*)(lds + PG8_SB(b, h) + boff + n * 2048 + k * 1024); } while (0)
; #define PG8_MMA(ai, bj, At, Bt) do { __builtin_amdgcn_s_setprio(1); _Pragma("unroll") for (int m = 0; m < 4; ++m) _Pragma("unroll") for (int n = 0; n < 2; ++n) _Pragma("unroll") for (int k = 0; k < 2; ++k) \
;         acc[ai][bj][m][n] = __builtin_amdgcn_mfma_f32_16x16x32_bf16(Bt[n][k], At[m][k], acc[ai][bj][m][n], 0, 0, 0); __builtin_amdgcn_s_setprio(0); } while (0)
; #define PG8_WAIT_V(n) asm volatile("s_waitcnt vmcnt(" #n ")" ::: "memory")
; #define PG8_WAIT_L(n) asm volatile("s_waitcnt lgkmcnt(" #n ")" ::: "memory")
; #define PG8_BAR __builtin_amdgcn_s_barrier()
; template <class Epi, class Sched, bool ALIGN_EPI = false, bool SP2 = false>
; __device__ __forceinline__ void gemm_phase(PG8_LAS unsigned char* lds, const Gemm g, const Sched& S, const Epi& E) {
;     ...
;             const bool last = (t == nt - 2);
;             const char* a1 = cA + (size_t)(t + 1) * kstep;
;             const char* a2 = last ? nA : cA + (size_t)(t + 2) * kstep; const char* b2 = last ? nB : cB + (size_t)(t + 2) * kstep;
;             const char* a3 = a2 + kstep; const char* b3 = b2 + kstep;
;             if constexpr (SP2) {
;             PG8_LDB(B0, 0, 0); PG8_LDB(B1, 0, 1); PG8_SCHED; PG8_LDA(At, 0, 0); PG8_STAGE(PG8_SA(1, 1), a1 + hstep, voffA);
;             PG8_WAIT_V(8); PG8_WAIT_L(0); PG8_BAR; PG8_MMA(0, 0, At, B0); PG8_MMA(0, 1, At, B1); PG8_BAR; PG8_SCHED;
;             PG8_LDA(At, 0, 1); PG8_STAGE(PG8_SB(0, 0), b2, voffB); PG8_STAGE(PG8_SB(0, 1), b2 + hstep, voffB); PG8_STAGE(PG8_SA(0, 0), a2, voffA);
;             PG8_WAIT_V(8); PG8_WAIT_L(0); PG8_BAR; PG8_MMA(1, 0, At, B0); PG8_MMA(1, 1, At, B1); PG8_BAR; PG8_SCHED;
.LBB0_624:
	ds_read_b128 v[128:131], v214
	ds_read_b128 v[132:135], v214 offset:1024
	ds_read_b128 v[158:161], v214 offset:2048
	ds_read_b128 v[162:165], v214 offset:3072
	ds_read_b128 v[166:169], v215
	ds_read_b128 v[170:173], v215 offset:1024
	ds_read_b128 v[174:177], v215 offset:2048
	ds_read_b128 v[178:181], v215 offset:3072
	s_add_u32 s52, s74, 0xffe00080
	s_addc_u32 s53, s75, -1
	s_cmpk_eq_i32 vcc_hi, 0x7c
	s_cselect_b32 s79, s51, s53
	s_cselect_b32 s78, s71, s52
	s_cselect_b32 s77, s49, vcc_lo
	s_cselect_b32 s76, s73, s93
	v_lshl_add_u64 v[226:227], s[74:75], 0, v[150:151]
	s_add_i32 m0, s83, 0xc000
	ds_read_b128 v[182:185], v216
	ds_read_b128 v[186:189], v216 offset:1024
	ds_read_b128 v[190:193], v216 offset:2048
	ds_read_b128 v[194:197], v216 offset:3072
	ds_read_b128 v[198:201], v216 offset:4096
	ds_read_b128 v[202:205], v216 offset:5120
	ds_read_b128 v[218:221], v216 offset:6144
	ds_read_b128 v[222:225], v216 offset:7168
	global_load_lds_dwordx4 v[226:227], off
	v_lshl_add_u64 v[226:227], s[74:75], 0, v[152:153]
	s_add_i32 m0, s83, 0xe000
	s_nop 0
	global_load_lds_dwordx4 v[226:227], off
	s_waitcnt vmcnt(8)
	s_waitcnt lgkmcnt(0)
	s_barrier
	s_setprio 1
	s_waitcnt lgkmcnt(0)
	v_mfma_f32_16x16x32_bf16 v[124:127], v[128:131], v[182:185], v[124:127]
	v_mfma_f32_16x16x32_bf16 v[120:123], v[158:161], v[182:185], v[120:123]
	v_mfma_f32_16x16x32_bf16 v[116:119], v[128:131], v[190:193], v[116:119]
	v_mfma_f32_16x16x32_bf16 v[112:115], v[158:161], v[190:193], v[112:115]
	v_mfma_f32_16x16x32_bf16 v[108:111], v[128:131], v[198:201], v[108:111]
	v_mfma_f32_16x16x32_bf16 v[104:107], v[158:161], v[198:201], v[104:107]
	v_mfma_f32_16x16x32_bf16 v[100:103], v[128:131], v[218:221], v[100:103]
	v_mfma_f32_16x16x32_bf16 v[96:99], v[158:161], v[218:221], v[96:99]
	v_mfma_f32_16x16x32_bf16 v[124:127], v[132:135], v[186:189], v[124:127]
	v_mfma_f32_16x16x32_bf16 v[120:123], v[162:165], v[186:189], v[120:123]
	v_mfma_f32_16x16x32_bf16 v[116:119], v[132:135], v[194:197], v[116:119]
	v_mfma_f32_16x16x32_bf16 v[112:115], v[162:165], v[194:197], v[112:115]
	v_mfma_f32_16x16x32_bf16 v[108:111], v[132:135], v[202:205], v[108:111]
	v_mfma_f32_16x16x32_bf16 v[104:107], v[162:165], v[202:205], v[104:107]
	v_mfma_f32_16x16x32_bf16 v[100:103], v[132:135], v[222:225], v[100:103]
	v_mfma_f32_16x16x32_bf16 v[96:99], v[162:165], v[222:225], v[96:99]
	s_setprio 0
	s_setprio 1
	v_mfma_f32_16x16x32_bf16 v[60:63], v[166:169], v[182:185], v[60:63]
	v_mfma_f32_16x16x32_bf16 v[56:59], v[174:177], v[182:185], v[56:59]
	v_mfma_f32_16x16x32_bf16 v[52:55], v[166:169], v[190:193], v[52:55]
	v_mfma_f32_16x16x32_bf16 v[48:51], v[174:177], v[190:193], v[48:51]
	v_mfma_f32_16x16x32_bf16 v[44:47], v[166:169], v[198:201], v[44:47]
	v_mfma_f32_16x16x32_bf16 v[40:43], v[174:177], v[198:201], v[40:43]
	v_mfma_f32_16x16x32_bf16 v[36:39], v[166:169], v[218:221], v[36:39]
	v_mfma_f32_16x16x32_bf16 v[32:35], v[174:177], v[218:221], v[32:35]
	v_mfma_f32_16x16x32_bf16 v[60:63], v[170:173], v[186:189], v[60:63]
	v_mfma_f32_16x16x32_bf16 v[56:59], v[178:181], v[186:189], v[56:59]
	v_mfma_f32_16x16x32_bf16 v[52:55], v[170:173], v[194:197], v[52:55]
	v_mfma_f32_16x16x32_bf16 v[48:51], v[178:181], v[194:197], v[48:51]
	s_setprio 2
	s_barrier
	v_mfma_f32_16x16x32_bf16 v[44:47], v[170:173], v[202:205], v[44:47]
	v_mfma_f32_16x16x32_bf16 v[40:43], v[178:181], v[202:205], v[40:43]
	v_mfma_f32_16x16x32_bf16 v[36:39], v[170:173], v[222:225], v[36:39]
	v_mfma_f32_16x16x32_bf16 v[32:35], v[178:181], v[222:225], v[32:35]
	s_setprio 0
	s_add_i32 s52, s33, s82
	v_lshl_add_u64 v[226:227], s[76:77], 0, v[138:139]
	s_mov_b32 m0, s52
	ds_read_b128 v[182:185], v216 offset:16384
	ds_read_b128 v[186:189], v216 offset:17408
	ds_read_b128 v[190:193], v216 offset:18432
	ds_read_b128 v[194:197], v216 offset:19456
	ds_read_b128 v[198:201], v216 offset:20480
	ds_read_b128 v[202:205], v216 offset:21504
	ds_read_b128 v[218:221], v216 offset:22528
	ds_read_b128 v[222:225], v216 offset:23552
	global_load_lds_dwordx4 v[226:227], off
	s_add_i32 m0, s52, 0x2000
	s_add_u32 s52, s76, 0x200000
	v_lshl_add_u64 v[228:229], s[76:77], 0, v[142:143]
	s_addc_u32 s53, s77, 0
	s_add_i32 s56, s92, s82
	global_load_lds_dwordx4 v[228:229], off
	v_lshl_add_u64 v[230:231], s[52:53], 0, v[138:139]
	s_mov_b32 m0, s56
	v_lshl_add_u64 v[232:233], s[78:79], 0, v[140:141]
	global_load_lds_dwordx4 v[230:231], off
	v_lshl_add_u64 v[230:231], s[52:53], 0, v[142:143]
	s_add_i32 m0, s56, 0x2000
	s_nop 0
	global_load_lds_dwordx4 v[230:231], off
	v_lshl_add_u64 v[230:231], s[78:79], 0, v[136:137]
	s_mov_b32 m0, s83
	s_nop 0
	global_load_lds_dwordx4 v[230:231], off
	s_mov_b32 m0, s84
	s_nop 0
	global_load_lds_dwordx4 v[232:233], off
	s_waitcnt vmcnt(8)
	s_waitcnt lgkmcnt(0)
	s_barrier
; #define PG8_STAGE(bufoff, gbase, voff) do { _Pragma("unroll") for (int _i = 0; _i < 2; ++_i) \
;         __builtin_amdgcn_global_load_lds((const unsigned*)((const char*)(gbase) + (voff)[_i]), (PG8_LAS unsigned*)(lds + (bufoff) + ldsw + _i * 8192), 16, 0, 0); } while (0)
; #define PG8_LDA(dst, b, h) do { _Pragma("unroll") for (int m = 0; m < 4; ++m) _Pragma("unroll") for (int k = 0; k < 2; ++k) dst[m][k] = *(const PG8_LAS bf16x8*)(lds + PG8_SA(b, h) + aoff + m * 2048 + k * 1024); } while (0)
; #define PG8_LDB(dst, b, h) do { _Pragma("unroll") for (int n = 0; n < 2; ++n) _Pragma("unroll") for (int k = 0; k < 2; ++k) dst[n][k] = *(const PG8_LAS bf16x8*)(lds + PG8_SB(b, h) + boff + n * 2048 + k * 1024); } while (0)
; #define PG8_MMA(ai, bj, At, Bt) do { __builtin_amdgcn_s_setprio(1); _Pragma("unroll") for (int m = 0; m < 4; ++m) _Pragma("unroll") for (int n = 0; n < 2; ++n) _Pragma("unroll") for (int k = 0; k < 2; ++k) \
;         acc[ai][bj][m][n] = __builtin_amdgcn_mfma_f32_16x16x32_bf16(Bt[n][k], At[m][k], acc[ai][bj][m][n], 0, 0, 0); __builtin_amdgcn_s_setprio(0); } while (0)
; #define PG8_WAIT_V(n) asm volatile("s_waitcnt vmcnt(" #n ")" ::: "memory")
; #define PG8_WAIT_L(n) asm volatile("s_waitcnt lgkmcnt(" #n ")" ::: "memory")
; #define PG8_BAR __builtin_amdgcn_s_barrier()
; #define PG8_SCHED __builtin_amdgcn_sched_barrier(0)
; template <class Epi, class Sched, bool ALIGN_EPI = false, bool SP2 = false>
; __device__ __forceinline__ void gemm_phase(PG8_LAS unsigned char* lds, const Gemm g, const Sched& S, const Epi& E) {
;     ...
;             PG8_WAIT_V(8); PG8_WAIT_L(0); PG8_BAR; PG8_MMA(1, 0, At, B0); PG8_MMA(1, 1, At, B1); PG8_BAR; PG8_SCHED;
;             PG8_LDB(B0, 1, 0); PG8_LDB(B1, 1, 1); PG8_SCHED; PG8_LDA(At, 1, 0); PG8_STAGE(PG8_SA(0, 1), a2 + hstep, voffA);
;             PG8_WAIT_V(8); PG8_WAIT_L(0); PG8_BAR; PG8_MMA(0, 0, At, B0); PG8_MMA(0, 1, At, B1); PG8_BAR; PG8_SCHED;
;             PG8_LDA(At, 1, 1); PG8_STAGE(PG8_SB(1, 0), b3, voffB); PG8_STAGE(PG8_SB(1, 1), b3 + hstep, voffB); PG8_STAGE(PG8_SA(1, 0), a3, voffA);
;             PG8_WAIT_V(8); PG8_WAIT_L(0); PG8_BAR; PG8_MMA(1, 0, At, B0); PG8_MMA(1, 1, At, B1); PG8_BAR; PG8_SCHED;
	s_setprio 1
	s_waitcnt lgkmcnt(0)
	v_mfma_f32_16x16x32_bf16 v[92:95], v[128:131], v[182:185], v[92:95]
	v_mfma_f32_16x16x32_bf16 v[88:91], v[158:161], v[182:185], v[88:91]
	v_mfma_f32_16x16x32_bf16 v[84:87], v[128:131], v[190:193], v[84:87]
	v_mfma_f32_16x16x32_bf16 v[80:83], v[158:161], v[190:193], v[80:83]
	v_mfma_f32_16x16x32_bf16 v[76:79], v[128:131], v[198:201], v[76:79]
	v_mfma_f32_16x16x32_bf16 v[72:75], v[158:161], v[198:201], v[72:75]
	v_mfma_f32_16x16x32_bf16 v[68:71], v[128:131], v[218:221], v[68:71]
	v_mfma_f32_16x16x32_bf16 v[64:67], v[158:161], v[218:221], v[64:67]
	v_mfma_f32_16x16x32_bf16 v[92:95], v[132:135], v[186:189], v[92:95]
	v_mfma_f32_16x16x32_bf16 v[88:91], v[162:165], v[186:189], v[88:91]
	v_mfma_f32_16x16x32_bf16 v[84:87], v[132:135], v[194:197], v[84:87]
	v_mfma_f32_16x16x32_bf16 v[80:83], v[162:165], v[194:197], v[80:83]
	v_mfma_f32_16x16x32_bf16 v[76:79], v[132:135], v[202:205], v[76:79]
	v_mfma_f32_16x16x32_bf16 v[72:75], v[162:165], v[202:205], v[72:75]
	v_mfma_f32_16x16x32_bf16 v[68:71], v[132:135], v[222:225], v[68:71]
	v_mfma_f32_16x16x32_bf16 v[64:67], v[162:165], v[222:225], v[64:67]
	s_setprio 0
	s_setprio 1
	v_mfma_f32_16x16x32_bf16 v[28:31], v[166:169], v[182:185], v[28:31]
	v_mfma_f32_16x16x32_bf16 v[24:27], v[174:177], v[182:185], v[24:27]
	v_mfma_f32_16x16x32_bf16 v[20:23], v[166:169], v[190:193], v[20:23]
	v_mfma_f32_16x16x32_bf16 v[16:19], v[174:177], v[190:193], v[16:19]
	v_mfma_f32_16x16x32_bf16 v[12:15], v[166:169], v[198:201], v[12:15]
	v_mfma_f32_16x16x32_bf16 v[8:11], v[174:177], v[198:201], v[8:11]
	v_mfma_f32_16x16x32_bf16 v[4:7], v[166:169], v[218:221], v[4:7]
	v_mfma_f32_16x16x32_bf16 v[0:3], v[174:177], v[218:221], v[0:3]
	v_mfma_f32_16x16x32_bf16 v[28:31], v[170:173], v[186:189], v[28:31]
	v_mfma_f32_16x16x32_bf16 v[24:27], v[178:181], v[186:189], v[24:27]
	v_mfma_f32_16x16x32_bf16 v[20:23], v[170:173], v[194:197], v[20:23]
	v_mfma_f32_16x16x32_bf16 v[16:19], v[178:181], v[194:197], v[16:19]
	s_setprio 2
	s_barrier
	v_mfma_f32_16x16x32_bf16 v[12:15], v[170:173], v[202:205], v[12:15]
	v_mfma_f32_16x16x32_bf16 v[8:11], v[178:181], v[202:205], v[8:11]
	v_mfma_f32_16x16x32_bf16 v[4:7], v[170:173], v[222:225], v[4:7]
	v_mfma_f32_16x16x32_bf16 v[0:3], v[178:181], v[222:225], v[0:3]
	s_setprio 0
	s_add_i32 s56, 0, 0x18000
	s_add_i32 s57, 0, 0x1c000
	v_add_u32_e32 v162, s56, v212
	v_add_u32_e32 v178, s57, v212
	ds_read_b128 v[128:131], v162
	ds_read_b128 v[132:135], v162 offset:1024
	ds_read_b128 v[158:161], v162 offset:2048
	ds_read_b128 v[162:165], v162 offset:3072
	ds_read_b128 v[166:169], v178
	ds_read_b128 v[170:173], v178 offset:1024
	ds_read_b128 v[174:177], v178 offset:2048
	ds_read_b128 v[178:181], v178 offset:3072
	s_add_u32 s52, s78, 0x200000
	s_addc_u32 s53, s79, 0
	s_mov_b32 m0, s85
	v_lshl_add_u64 v[234:235], s[52:53], 0, v[136:137]
	ds_read_b128 v[182:185], v216 offset:32768
	ds_read_b128 v[186:189], v216 offset:33792
	ds_read_b128 v[190:193], v216 offset:34816
	ds_read_b128 v[194:197], v216 offset:35840
	ds_read_b128 v[198:201], v216 offset:36864
	ds_read_b128 v[202:205], v216 offset:37888
	ds_read_b128 v[218:221], v216 offset:38912
	ds_read_b128 v[222:225], v216 offset:39936
	global_load_lds_dwordx4 v[234:235], off
	v_lshl_add_u64 v[234:235], s[52:53], 0, v[140:141]
	s_mov_b32 m0, s86
	s_nop 0
	global_load_lds_dwordx4 v[234:235], off
	s_waitcnt vmcnt(8)
	s_waitcnt lgkmcnt(0)
	s_barrier
	s_setprio 1
	s_waitcnt lgkmcnt(0)
	v_mfma_f32_16x16x32_bf16 v[124:127], v[128:131], v[182:185], v[124:127]
	v_mfma_f32_16x16x32_bf16 v[120:123], v[158:161], v[182:185], v[120:123]
	v_mfma_f32_16x16x32_bf16 v[116:119], v[128:131], v[190:193], v[116:119]
	v_mfma_f32_16x16x32_bf16 v[112:115], v[158:161], v[190:193], v[112:115]
	v_mfma_f32_16x16x32_bf16 v[108:111], v[128:131], v[198:201], v[108:111]
	v_mfma_f32_16x16x32_bf16 v[104:107], v[158:161], v[198:201], v[104:107]
	v_mfma_f32_16x16x32_bf16 v[100:103], v[128:131], v[218:221], v[100:103]
	v_mfma_f32_16x16x32_bf16 v[96:99], v[158:161], v[218:221], v[96:99]
	v_mfma_f32_16x16x32_bf16 v[124:127], v[132:135], v[186:189], v[124:127]
	v_mfma_f32_16x16x32_bf16 v[120:123], v[162:165], v[186:189], v[120:123]
	v_mfma_f32_16x16x32_bf16 v[116:119], v[132:135], v[194:197], v[116:119]
	v_mfma_f32_16x16x32_bf16 v[112:115], v[162:165], v[194:197], v[112:115]
	v_mfma_f32_16x16x32_bf16 v[108:111], v[132:135], v[202:205], v[108:111]
	v_mfma_f32_16x16x32_bf16 v[104:107], v[162:165], v[202:205], v[104:107]
	v_mfma_f32_16x16x32_bf16 v[100:103], v[132:135], v[222:225], v[100:103]
	v_mfma_f32_16x16x32_bf16 v[96:99], v[162:165], v[222:225], v[96:99]
	s_setprio 0
	s_setprio 1
	v_mfma_f32_16x16x32_bf16 v[60:63], v[166:169], v[182:185], v[60:63]
	v_mfma_f32_16x16x32_bf16 v[56:59], v[174:177], v[182:185], v[56:59]
	v_mfma_f32_16x16x32_bf16 v[52:55], v[166:169], v[190:193], v[52:55]
	v_mfma_f32_16x16x32_bf16 v[48:51], v[174:177], v[190:193], v[48:51]
	v_mfma_f32_16x16x32_bf16 v[44:47], v[166:169], v[198:201], v[44:47]
	v_mfma_f32_16x16x32_bf16 v[40:43], v[174:177], v[198:201], v[40:43]
	v_mfma_f32_16x16x32_bf16 v[36:39], v[166:169], v[218:221], v[36:39]
	v_mfma_f32_16x16x32_bf16 v[32:35], v[174:177], v[218:221], v[32:35]
	v_mfma_f32_16x16x32_bf16 v[60:63], v[170:173], v[186:189], v[60:63]
	v_mfma_f32_16x16x32_bf16 v[56:59], v[178:181], v[186:189], v[56:59]
	v_mfma_f32_16x16x32_bf16 v[52:55], v[170:173], v[194:197], v[52:55]
	v_mfma_f32_16x16x32_bf16 v[48:51], v[178:181], v[194:197], v[48:51]
	s_setprio 2
	s_barrier
; #define PG8_STAGE(bufoff, gbase, voff) do { _Pragma("unroll") for (int _i = 0; _i < 2; ++_i) \
;         __builtin_amdgcn_global_load_lds((const unsigned*)((const char*)(gbase) + (voff)[_i]), (PG8_LAS unsigned*)(lds + (bufoff) + ldsw + _i * 8192), 16, 0, 0); } while (0)
; #define PG8_LDA(dst, b, h) do { _Pragma("unroll") for (int m = 0; m < 4; ++m) _Pragma("unroll") for (int k = 0; k < 2; ++k) dst[m][k] = *(const PG8_LAS bf16x8*)(lds + PG8_SA(b, h) + aoff + m * 2048 + k * 1024); } while (0)
; #define PG8_MMA(ai, bj, At, Bt) do { __builtin_amdgcn_s_setprio(1); _Pragma("unroll") for (int m = 0; m < 4; ++m) _Pragma("unroll") for (int n = 0; n < 2; ++n) _Pragma("unroll") for (int k = 0; k < 2; ++k) \
;         acc[ai][bj][m][n] = __builtin_amdgcn_mfma_f32_16x16x32_bf16(Bt[n][k], At[m][k], acc[ai][bj][m][n], 0, 0, 0); __builtin_amdgcn_s_setprio(0); } while (0)
; #define PG8_WAIT_V(n) asm volatile("s_waitcnt vmcnt(" #n ")" ::: "memory")
; #define PG8_WAIT_L(n) asm volatile("s_waitcnt lgkmcnt(" #n ")" ::: "memory")
; #define PG8_BAR __builtin_amdgcn_s_barrier()
; #define PG8_SCHED __builtin_amdgcn_sched_barrier(0)
; template <class Epi, class Sched, bool ALIGN_EPI = false, bool SP2 = false>
; __device__ __forceinline__ void gemm_phase(PG8_LAS unsigned char* lds, const Gemm g, const Sched& S, const Epi& E) {
;     ...
;         for (int t = 0; t < nt; t += 2) {
;             const bool last = (t == nt - 2);
;             const char* a1 = cA + (size_t)(t + 1) * kstep;
;             const char* a2 = last ? nA : cA + (size_t)(t + 2) * kstep; const char* b2 = last ? nB : cB + (size_t)(t + 2) * kstep;
;             const char* a3 = a2 + kstep; const char* b3 = b2 + kstep;
;     ...
;             PG8_WAIT_V(8); PG8_WAIT_L(0); PG8_BAR; PG8_MMA(0, 0, At, B0); PG8_MMA(0, 1, At, B1); PG8_BAR; PG8_SCHED;
;             PG8_LDA(At, 1, 1); PG8_STAGE(PG8_SB(1, 0), b3, voffB); PG8_STAGE(PG8_SB(1, 1), b3 + hstep, voffB); PG8_STAGE(PG8_SA(1, 0), a3, voffA);
;             PG8_WAIT_V(8); PG8_WAIT_L(0); PG8_BAR; PG8_MMA(1, 0, At, B0); PG8_MMA(1, 1, At, B1); PG8_BAR; PG8_SCHED;
	v_mfma_f32_16x16x32_bf16 v[44:47], v[170:173], v[202:205], v[44:47]
	v_mfma_f32_16x16x32_bf16 v[40:43], v[178:181], v[202:205], v[40:43]
	v_mfma_f32_16x16x32_bf16 v[36:39], v[170:173], v[222:225], v[36:39]
	v_mfma_f32_16x16x32_bf16 v[32:35], v[178:181], v[222:225], v[32:35]
	s_setprio 0
	s_add_i32 s52, s56, s82
	v_lshl_add_u64 v[226:227], v[226:227], 0, s[36:37]
	s_mov_b32 m0, s52
	ds_read_b128 v[182:185], v216 offset:49152
	ds_read_b128 v[186:189], v216 offset:50176
	ds_read_b128 v[190:193], v216 offset:51200
	ds_read_b128 v[194:197], v216 offset:52224
	ds_read_b128 v[198:201], v216 offset:53248
	ds_read_b128 v[202:205], v216 offset:54272
	ds_read_b128 v[218:221], v216 offset:55296
	ds_read_b128 v[222:225], v216 offset:56320
	global_load_lds_dwordx4 v[226:227], off
	s_add_i32 m0, s52, 0x2000
	s_add_u32 s52, s76, 0x200080
	v_lshl_add_u64 v[226:227], v[228:229], 0, s[36:37]
	s_addc_u32 s53, s77, 0
	s_add_i32 s56, s57, s82
	global_load_lds_dwordx4 v[226:227], off
	v_lshl_add_u64 v[226:227], s[52:53], 0, v[138:139]
	s_mov_b32 m0, s56
	s_nop 0
	global_load_lds_dwordx4 v[226:227], off
	v_lshl_add_u64 v[226:227], s[52:53], 0, v[142:143]
	s_add_i32 m0, s56, 0x2000
	s_nop 0
	global_load_lds_dwordx4 v[226:227], off
	v_lshl_add_u64 v[226:227], v[230:231], 0, s[36:37]
	s_mov_b32 m0, s94
	s_nop 0
	global_load_lds_dwordx4 v[226:227], off
	v_lshl_add_u64 v[226:227], v[232:233], 0, s[36:37]
	s_mov_b32 m0, s95
	s_nop 0
	global_load_lds_dwordx4 v[226:227], off
	s_waitcnt vmcnt(8)
	s_waitcnt lgkmcnt(0)
	s_barrier
	s_setprio 1
	s_waitcnt lgkmcnt(0)
	v_mfma_f32_16x16x32_bf16 v[92:95], v[128:131], v[182:185], v[92:95]
	v_mfma_f32_16x16x32_bf16 v[88:91], v[158:161], v[182:185], v[88:91]
	v_mfma_f32_16x16x32_bf16 v[84:87], v[128:131], v[190:193], v[84:87]
	v_mfma_f32_16x16x32_bf16 v[80:83], v[158:161], v[190:193], v[80:83]
	v_mfma_f32_16x16x32_bf16 v[76:79], v[128:131], v[198:201], v[76:79]
	v_mfma_f32_16x16x32_bf16 v[72:75], v[158:161], v[198:201], v[72:75]
	v_mfma_f32_16x16x32_bf16 v[68:71], v[128:131], v[218:221], v[68:71]
	v_mfma_f32_16x16x32_bf16 v[64:67], v[158:161], v[218:221], v[64:67]
	v_mfma_f32_16x16x32_bf16 v[92:95], v[132:135], v[186:189], v[92:95]
	v_mfma_f32_16x16x32_bf16 v[88:91], v[162:165], v[186:189], v[88:91]
	v_mfma_f32_16x16x32_bf16 v[84:87], v[132:135], v[194:197], v[84:87]
	v_mfma_f32_16x16x32_bf16 v[80:83], v[162:165], v[194:197], v[80:83]
	v_mfma_f32_16x16x32_bf16 v[76:79], v[132:135], v[202:205], v[76:79]
	v_mfma_f32_16x16x32_bf16 v[72:75], v[162:165], v[202:205], v[72:75]
	v_mfma_f32_16x16x32_bf16 v[68:71], v[132:135], v[222:225], v[68:71]
	v_mfma_f32_16x16x32_bf16 v[64:67], v[162:165], v[222:225], v[64:67]
	s_setprio 0
	s_setprio 1
	v_mfma_f32_16x16x32_bf16 v[28:31], v[166:169], v[182:185], v[28:31]
	v_mfma_f32_16x16x32_bf16 v[24:27], v[174:177], v[182:185], v[24:27]
	v_mfma_f32_16x16x32_bf16 v[20:23], v[166:169], v[190:193], v[20:23]
	v_mfma_f32_16x16x32_bf16 v[16:19], v[174:177], v[190:193], v[16:19]
	v_mfma_f32_16x16x32_bf16 v[12:15], v[166:169], v[198:201], v[12:15]
	v_mfma_f32_16x16x32_bf16 v[8:11], v[174:177], v[198:201], v[8:11]
	v_mfma_f32_16x16x32_bf16 v[4:7], v[166:169], v[218:221], v[4:7]
	v_mfma_f32_16x16x32_bf16 v[0:3], v[174:177], v[218:221], v[0:3]
	v_mfma_f32_16x16x32_bf16 v[28:31], v[170:173], v[186:189], v[28:31]
	v_mfma_f32_16x16x32_bf16 v[24:27], v[178:181], v[186:189], v[24:27]
	v_mfma_f32_16x16x32_bf16 v[20:23], v[170:173], v[194:197], v[20:23]
	v_mfma_f32_16x16x32_bf16 v[16:19], v[178:181], v[194:197], v[16:19]
	s_setprio 2
	s_barrier
	v_mfma_f32_16x16x32_bf16 v[12:15], v[170:173], v[202:205], v[12:15]
	v_mfma_f32_16x16x32_bf16 v[8:11], v[178:181], v[202:205], v[8:11]
	v_mfma_f32_16x16x32_bf16 v[4:7], v[170:173], v[222:225], v[4:7]
	v_mfma_f32_16x16x32_bf16 v[0:3], v[178:181], v[222:225], v[0:3]
	s_setprio 0
	s_add_i32 vcc_hi, vcc_hi, 2
	s_add_u32 s74, s74, 0x100
	s_addc_u32 s75, s75, 0
	s_add_u32 s93, s93, 0x100
	s_addc_u32 vcc_lo, vcc_lo, 0
	s_cmpk_gt_u32 vcc_hi, 0x7d
	s_cbranch_scc0 .LBB0_624
	s_and_b64 vcc, exec, s[40:41]
	s_cbranch_vccz .LBB0_627
	s_barrier

; #define PG8_STAGE(bufoff, gbase, voff) do { _Pragma("unroll") for (int _i = 0; _i < 2; ++_i) \
;         __builtin_amdgcn_global_load_lds((const unsigned*)((const char*)(gbase) + (voff)[_i]), (PG8_LAS unsigned*)(lds + (bufoff) + ldsw + _i * 8192), 16, 0, 0); } while (0)
; #define PG8_LDA(dst, b, h) do { _Pragma("unroll") for (int m = 0; m < 4; ++m) _Pragma("unroll") for (int k = 0; k < 2; ++k) dst[m][k] = *(const PG8_LAS bf16x8*)(lds + PG8_SA(b, h) + aoff + m * 2048 + k * 1024); } while (0)
; #define PG8_LDB(dst, b, h) do { _Pragma("unroll") for (int n = 0; n < 2; ++n) _Pragma("unroll") for (int k = 0; k < 2; ++k) dst[n][k] = *(const PG8_LAS bf16x8*)(lds + PG8_SB(b, h) + boff + n * 2048 + k * 1024); } while (0)
; #define PG8_MMA(ai, bj, At, Bt) do { __builtin_amdgcn_s_setprio(1); _Pragma("unroll") for (int m = 0; m < 4; ++m) _Pragma("unroll") for (int n = 0; n < 2; ++n) _Pragma("unroll") for (int k = 0; k < 2; ++k) \
;         acc[ai][bj][m][n] = __builtin_amdgcn_mfma_f32_16x16x32_bf16(Bt[n][k], At[m][k], acc[ai][bj][m][n], 0, 0, 0); __builtin_amdgcn_s_setprio(0); } while (0)
; #define PG8_WAIT_V(n) asm volatile("s_waitcnt vmcnt(" #n ")" ::: "memory")
; #define PG8_WAIT_L(n) asm volatile("s_waitcnt lgkmcnt(" #n ")" ::: "memory")
; #define PG8_BAR __builtin_amdgcn_s_barrier()
; template <class Epi, class Sched, bool ALIGN_EPI = false, bool SP2 = false>
; __device__ __forceinline__ void gemm_phase(PG8_LAS unsigned char* lds, const Gemm g, const Sched& S, const Epi& E) {
;     ...
;             const bool last = (t == nt - 2);
;             const char* a1 = cA + (size_t)(t + 1) * kstep;
;             const char* a2 = last ? nA : cA + (size_t)(t + 2) * kstep; const char* b2 = last ? nB : cB + (size_t)(t + 2) * kstep;
;             const char* a3 = a2 + kstep; const char* b3 = b2 + kstep;
;             if constexpr (SP2) {
;             PG8_LDB(B0, 0, 0); PG8_LDB(B1, 0, 1); PG8_SCHED; PG8_LDA(At, 0, 0); PG8_STAGE(PG8_SA(1, 1), a1 + hstep, voffA);
;             PG8_WAIT_V(8); PG8_WAIT_L(0); PG8_BAR; PG8_MMA(0, 0, At, B0); PG8_MMA(0, 1, At, B1); PG8_BAR; PG8_SCHED;
;             PG8_LDA(At, 0, 1); PG8_STAGE(PG8_SB(0, 0), b2, voffB); PG8_STAGE(PG8_SB(0, 1), b2 + hstep, voffB); PG8_STAGE(PG8_SA(0, 0), a2, voffA);
;             PG8_WAIT_V(8); PG8_WAIT_L(0); PG8_BAR; PG8_MMA(1, 0, At, B0); PG8_MMA(1, 1, At, B1); PG8_BAR; PG8_SCHED;
.LBB0_660:
	ds_read_b128 v[166:169], v145
	ds_read_b128 v[170:173], v145 offset:1024
	ds_read_b128 v[174:177], v145 offset:2048
	ds_read_b128 v[178:181], v145 offset:3072
	ds_read_b128 v[182:185], v149
	ds_read_b128 v[186:189], v149 offset:1024
	ds_read_b128 v[190:193], v149 offset:2048
	ds_read_b128 v[194:197], v149 offset:3072
	s_add_u32 s52, s72, 0xffe00080
	s_addc_u32 s53, s73, -1
	s_cmp_eq_u32 s49, 28
	s_cselect_b32 s77, s51, s53
	s_cselect_b32 s76, s50, s52
	s_cselect_b32 s75, s55, s41
	s_cselect_b32 s74, s54, s37
	s_mov_b32 m0, s82
	v_lshl_add_u64 v[230:231], s[72:73], 0, v[160:161]
	ds_read_b128 v[198:201], v164
	ds_read_b128 v[202:205], v164 offset:1024
	ds_read_b128 v[206:209], v164 offset:2048
	ds_read_b128 v[210:213], v164 offset:3072
	ds_read_b128 v[214:217], v164 offset:4096
	ds_read_b128 v[218:221], v164 offset:5120
	ds_read_b128 v[222:225], v164 offset:6144
	ds_read_b128 v[226:229], v164 offset:7168
	global_load_lds_dwordx4 v[230:231], off
	v_lshl_add_u64 v[230:231], s[72:73], 0, v[162:163]
	s_mov_b32 m0, s83
	s_nop 0
	global_load_lds_dwordx4 v[230:231], off
	s_waitcnt vmcnt(8)
	s_waitcnt lgkmcnt(0)
	s_barrier
	s_setprio 1
	s_waitcnt lgkmcnt(0)
	v_mfma_f32_16x16x32_bf16 v[124:127], v[166:169], v[198:201], v[124:127]
	v_mfma_f32_16x16x32_bf16 v[120:123], v[174:177], v[198:201], v[120:123]
	v_mfma_f32_16x16x32_bf16 v[116:119], v[166:169], v[206:209], v[116:119]
	v_mfma_f32_16x16x32_bf16 v[108:111], v[174:177], v[206:209], v[108:111]
	v_mfma_f32_16x16x32_bf16 v[100:103], v[166:169], v[214:217], v[100:103]
	v_mfma_f32_16x16x32_bf16 v[92:95], v[174:177], v[214:217], v[92:95]
	v_mfma_f32_16x16x32_bf16 v[84:87], v[166:169], v[222:225], v[84:87]
	v_mfma_f32_16x16x32_bf16 v[76:79], v[174:177], v[222:225], v[76:79]
	v_mfma_f32_16x16x32_bf16 v[124:127], v[170:173], v[202:205], v[124:127]
	v_mfma_f32_16x16x32_bf16 v[120:123], v[178:181], v[202:205], v[120:123]
	v_mfma_f32_16x16x32_bf16 v[116:119], v[170:173], v[210:213], v[116:119]
	v_mfma_f32_16x16x32_bf16 v[108:111], v[178:181], v[210:213], v[108:111]
	v_mfma_f32_16x16x32_bf16 v[100:103], v[170:173], v[218:221], v[100:103]
	v_mfma_f32_16x16x32_bf16 v[92:95], v[178:181], v[218:221], v[92:95]
	v_mfma_f32_16x16x32_bf16 v[84:87], v[170:173], v[226:229], v[84:87]
	v_mfma_f32_16x16x32_bf16 v[76:79], v[178:181], v[226:229], v[76:79]
	s_setprio 0
	s_setprio 1
	v_mfma_f32_16x16x32_bf16 v[112:115], v[182:185], v[198:201], v[112:115]
	v_mfma_f32_16x16x32_bf16 v[104:107], v[190:193], v[198:201], v[104:107]
	v_mfma_f32_16x16x32_bf16 v[96:99], v[182:185], v[206:209], v[96:99]
	v_mfma_f32_16x16x32_bf16 v[88:91], v[190:193], v[206:209], v[88:91]
	v_mfma_f32_16x16x32_bf16 v[80:83], v[182:185], v[214:217], v[80:83]
	v_mfma_f32_16x16x32_bf16 v[72:75], v[190:193], v[214:217], v[72:75]
	v_mfma_f32_16x16x32_bf16 v[68:71], v[182:185], v[222:225], v[68:71]
	v_mfma_f32_16x16x32_bf16 v[64:67], v[190:193], v[222:225], v[64:67]
	v_mfma_f32_16x16x32_bf16 v[112:115], v[186:189], v[202:205], v[112:115]
	v_mfma_f32_16x16x32_bf16 v[104:107], v[194:197], v[202:205], v[104:107]
	v_mfma_f32_16x16x32_bf16 v[96:99], v[186:189], v[210:213], v[96:99]
	v_mfma_f32_16x16x32_bf16 v[88:91], v[194:197], v[210:213], v[88:91]
	s_setprio 2
	s_barrier
	v_mfma_f32_16x16x32_bf16 v[80:83], v[186:189], v[218:221], v[80:83]
	v_mfma_f32_16x16x32_bf16 v[72:75], v[194:197], v[218:221], v[72:75]
	v_mfma_f32_16x16x32_bf16 v[68:71], v[186:189], v[226:229], v[68:71]
	v_mfma_f32_16x16x32_bf16 v[64:67], v[194:197], v[226:229], v[64:67]
	s_setprio 0
	s_mov_b32 m0, s84
	v_lshl_add_u64 v[230:231], s[74:75], 0, v[138:139]
	s_add_u32 s52, s74, 0x200000
	ds_read_b128 v[198:201], v164 offset:16384
	ds_read_b128 v[202:205], v164 offset:17408
	ds_read_b128 v[206:209], v164 offset:18432
	ds_read_b128 v[210:213], v164 offset:19456
	ds_read_b128 v[214:217], v164 offset:20480
	ds_read_b128 v[218:221], v164 offset:21504
	ds_read_b128 v[222:225], v164 offset:22528
	ds_read_b128 v[226:229], v164 offset:23552
	global_load_lds_dwordx4 v[230:231], off
	v_lshl_add_u64 v[232:233], s[74:75], 0, v[142:143]
	s_mov_b32 m0, s85
	s_addc_u32 s53, s75, 0
	global_load_lds_dwordx4 v[232:233], off
	v_lshl_add_u64 v[234:235], s[52:53], 0, v[138:139]
	s_mov_b32 m0, s86
	v_lshl_add_u64 v[236:237], s[76:77], 0, v[140:141]
	global_load_lds_dwordx4 v[234:235], off
	v_lshl_add_u64 v[234:235], s[52:53], 0, v[142:143]
	s_mov_b32 m0, s87
	s_nop 0
	global_load_lds_dwordx4 v[234:235], off
	v_lshl_add_u64 v[234:235], s[76:77], 0, v[136:137]
	s_mov_b32 m0, s28
	s_nop 0
	global_load_lds_dwordx4 v[234:235], off
	s_mov_b32 m0, s29
	s_nop 0
	global_load_lds_dwordx4 v[236:237], off
	s_waitcnt vmcnt(8)
	s_waitcnt lgkmcnt(0)
	s_barrier
; #define PG8_STAGE(bufoff, gbase, voff) do { _Pragma("unroll") for (int _i = 0; _i < 2; ++_i) \
;         __builtin_amdgcn_global_load_lds((const unsigned*)((const char*)(gbase) + (voff)[_i]), (PG8_LAS unsigned*)(lds + (bufoff) + ldsw + _i * 8192), 16, 0, 0); } while (0)
; #define PG8_LDA(dst, b, h) do { _Pragma("unroll") for (int m = 0; m < 4; ++m) _Pragma("unroll") for (int k = 0; k < 2; ++k) dst[m][k] = *(const PG8_LAS bf16x8*)(lds + PG8_SA(b, h) + aoff + m * 2048 + k * 1024); } while (0)
; #define PG8_LDB(dst, b, h) do { _Pragma("unroll") for (int n = 0; n < 2; ++n) _Pragma("unroll") for (int k = 0; k < 2; ++k) dst[n][k] = *(const PG8_LAS bf16x8*)(lds + PG8_SB(b, h) + boff + n * 2048 + k * 1024); } while (0)
; #define PG8_MMA(ai, bj, At, Bt) do { __builtin_amdgcn_s_setprio(1); _Pragma("unroll") for (int m = 0; m < 4; ++m) _Pragma("unroll") for (int n = 0; n < 2; ++n) _Pragma("unroll") for (int k = 0; k < 2; ++k) \
;         acc[ai][bj][m][n] = __builtin_amdgcn_mfma_f32_16x16x32_bf16(Bt[n][k], At[m][k], acc[ai][bj][m][n], 0, 0, 0); __builtin_amdgcn_s_setprio(0); } while (0)
; #define PG8_WAIT_V(n) asm volatile("s_waitcnt vmcnt(" #n ")" ::: "memory")
; #define PG8_WAIT_L(n) asm volatile("s_waitcnt lgkmcnt(" #n ")" ::: "memory")
; #define PG8_BAR __builtin_amdgcn_s_barrier()
; #define PG8_SCHED __builtin_amdgcn_sched_barrier(0)
; template <class Epi, class Sched, bool ALIGN_EPI = false, bool SP2 = false>
; __device__ __forceinline__ void gemm_phase(PG8_LAS unsigned char* lds, const Gemm g, const Sched& S, const Epi& E) {
;     ...
;             PG8_WAIT_V(8); PG8_WAIT_L(0); PG8_BAR; PG8_MMA(1, 0, At, B0); PG8_MMA(1, 1, At, B1); PG8_BAR; PG8_SCHED;
;             PG8_LDB(B0, 1, 0); PG8_LDB(B1, 1, 1); PG8_SCHED; PG8_LDA(At, 1, 0); PG8_STAGE(PG8_SA(0, 1), a2 + hstep, voffA);
;             PG8_WAIT_V(8); PG8_WAIT_L(0); PG8_BAR; PG8_MMA(0, 0, At, B0); PG8_MMA(0, 1, At, B1); PG8_BAR; PG8_SCHED;
	s_setprio 1
	s_waitcnt lgkmcnt(0)
	v_mfma_f32_16x16x32_bf16 v[60:63], v[166:169], v[198:201], v[60:63]
	v_mfma_f32_16x16x32_bf16 v[56:59], v[174:177], v[198:201], v[56:59]
	v_mfma_f32_16x16x32_bf16 v[52:55], v[166:169], v[206:209], v[52:55]
	v_mfma_f32_16x16x32_bf16 v[44:47], v[174:177], v[206:209], v[44:47]
	v_mfma_f32_16x16x32_bf16 v[36:39], v[166:169], v[214:217], v[36:39]
	v_mfma_f32_16x16x32_bf16 v[28:31], v[174:177], v[214:217], v[28:31]
	v_mfma_f32_16x16x32_bf16 v[20:23], v[166:169], v[222:225], v[20:23]
	v_mfma_f32_16x16x32_bf16 v[12:15], v[174:177], v[222:225], v[12:15]
	v_mfma_f32_16x16x32_bf16 v[60:63], v[170:173], v[202:205], v[60:63]
	v_mfma_f32_16x16x32_bf16 v[56:59], v[178:181], v[202:205], v[56:59]
	v_mfma_f32_16x16x32_bf16 v[52:55], v[170:173], v[210:213], v[52:55]
	v_mfma_f32_16x16x32_bf16 v[44:47], v[178:181], v[210:213], v[44:47]
	v_mfma_f32_16x16x32_bf16 v[36:39], v[170:173], v[218:221], v[36:39]
	v_mfma_f32_16x16x32_bf16 v[28:31], v[178:181], v[218:221], v[28:31]
	v_mfma_f32_16x16x32_bf16 v[20:23], v[170:173], v[226:229], v[20:23]
	v_mfma_f32_16x16x32_bf16 v[12:15], v[178:181], v[226:229], v[12:15]
	s_setprio 0
	s_setprio 1
	v_mfma_f32_16x16x32_bf16 v[48:51], v[182:185], v[198:201], v[48:51]
	v_mfma_f32_16x16x32_bf16 v[40:43], v[190:193], v[198:201], v[40:43]
	v_mfma_f32_16x16x32_bf16 v[32:35], v[182:185], v[206:209], v[32:35]
	v_mfma_f32_16x16x32_bf16 v[24:27], v[190:193], v[206:209], v[24:27]
	v_mfma_f32_16x16x32_bf16 v[16:19], v[182:185], v[214:217], v[16:19]
	v_mfma_f32_16x16x32_bf16 v[8:11], v[190:193], v[214:217], v[8:11]
	v_mfma_f32_16x16x32_bf16 v[4:7], v[182:185], v[222:225], v[4:7]
	v_mfma_f32_16x16x32_bf16 v[0:3], v[190:193], v[222:225], v[0:3]
	v_mfma_f32_16x16x32_bf16 v[48:51], v[186:189], v[202:205], v[48:51]
	v_mfma_f32_16x16x32_bf16 v[40:43], v[194:197], v[202:205], v[40:43]
	v_mfma_f32_16x16x32_bf16 v[32:35], v[186:189], v[210:213], v[32:35]
	v_mfma_f32_16x16x32_bf16 v[24:27], v[194:197], v[210:213], v[24:27]
	s_setprio 2
	s_barrier
	v_mfma_f32_16x16x32_bf16 v[16:19], v[186:189], v[218:221], v[16:19]
	v_mfma_f32_16x16x32_bf16 v[8:11], v[194:197], v[218:221], v[8:11]
	v_mfma_f32_16x16x32_bf16 v[4:7], v[186:189], v[226:229], v[4:7]
	v_mfma_f32_16x16x32_bf16 v[0:3], v[194:197], v[226:229], v[0:3]
	s_setprio 0
	ds_read_b128 v[166:169], v148
	ds_read_b128 v[170:173], v148 offset:1024
	ds_read_b128 v[174:177], v148 offset:2048
	ds_read_b128 v[178:181], v148 offset:3072
	ds_read_b128 v[182:185], v165
	ds_read_b128 v[186:189], v165 offset:1024
	ds_read_b128 v[190:193], v165 offset:2048
	ds_read_b128 v[194:197], v165 offset:3072
	s_add_u32 s52, s76, 0x200000
	s_addc_u32 s53, s77, 0
	s_mov_b32 m0, s33
	v_lshl_add_u64 v[238:239], s[52:53], 0, v[136:137]
	ds_read_b128 v[198:201], v164 offset:32768
	ds_read_b128 v[202:205], v164 offset:33792
	ds_read_b128 v[206:209], v164 offset:34816
	ds_read_b128 v[210:213], v164 offset:35840
	ds_read_b128 v[214:217], v164 offset:36864
	ds_read_b128 v[218:221], v164 offset:37888
	ds_read_b128 v[222:225], v164 offset:38912
	ds_read_b128 v[226:229], v164 offset:39936
	global_load_lds_dwordx4 v[238:239], off
	v_lshl_add_u64 v[238:239], s[52:53], 0, v[140:141]
	s_mov_b32 m0, s38
	s_nop 0
	global_load_lds_dwordx4 v[238:239], off
	s_waitcnt vmcnt(8)
	s_waitcnt lgkmcnt(0)
	s_barrier
	s_setprio 1
	s_waitcnt lgkmcnt(0)
	v_mfma_f32_16x16x32_bf16 v[124:127], v[166:169], v[198:201], v[124:127]
	v_mfma_f32_16x16x32_bf16 v[120:123], v[174:177], v[198:201], v[120:123]
	v_mfma_f32_16x16x32_bf16 v[116:119], v[166:169], v[206:209], v[116:119]
	v_mfma_f32_16x16x32_bf16 v[108:111], v[174:177], v[206:209], v[108:111]
	v_mfma_f32_16x16x32_bf16 v[100:103], v[166:169], v[214:217], v[100:103]
	v_mfma_f32_16x16x32_bf16 v[92:95], v[174:177], v[214:217], v[92:95]
	v_mfma_f32_16x16x32_bf16 v[84:87], v[166:169], v[222:225], v[84:87]
	v_mfma_f32_16x16x32_bf16 v[76:79], v[174:177], v[222:225], v[76:79]
	v_mfma_f32_16x16x32_bf16 v[124:127], v[170:173], v[202:205], v[124:127]
	v_mfma_f32_16x16x32_bf16 v[120:123], v[178:181], v[202:205], v[120:123]
	v_mfma_f32_16x16x32_bf16 v[116:119], v[170:173], v[210:213], v[116:119]
	v_mfma_f32_16x16x32_bf16 v[108:111], v[178:181], v[210:213], v[108:111]
	v_mfma_f32_16x16x32_bf16 v[100:103], v[170:173], v[218:221], v[100:103]
	v_mfma_f32_16x16x32_bf16 v[92:95], v[178:181], v[218:221], v[92:95]
	v_mfma_f32_16x16x32_bf16 v[84:87], v[170:173], v[226:229], v[84:87]
	v_mfma_f32_16x16x32_bf16 v[76:79], v[178:181], v[226:229], v[76:79]
	s_setprio 0
	s_setprio 1
	v_mfma_f32_16x16x32_bf16 v[112:115], v[182:185], v[198:201], v[112:115]
	v_mfma_f32_16x16x32_bf16 v[104:107], v[190:193], v[198:201], v[104:107]
	v_mfma_f32_16x16x32_bf16 v[96:99], v[182:185], v[206:209], v[96:99]
	v_mfma_f32_16x16x32_bf16 v[88:91], v[190:193], v[206:209], v[88:91]
	v_mfma_f32_16x16x32_bf16 v[80:83], v[182:185], v[214:217], v[80:83]
	v_mfma_f32_16x16x32_bf16 v[72:75], v[190:193], v[214:217], v[72:75]
	v_mfma_f32_16x16x32_bf16 v[68:71], v[182:185], v[222:225], v[68:71]
	v_mfma_f32_16x16x32_bf16 v[64:67], v[190:193], v[222:225], v[64:67]
	v_mfma_f32_16x16x32_bf16 v[112:115], v[186:189], v[202:205], v[112:115]
	v_mfma_f32_16x16x32_bf16 v[104:107], v[194:197], v[202:205], v[104:107]
	v_mfma_f32_16x16x32_bf16 v[96:99], v[186:189], v[210:213], v[96:99]
	v_mfma_f32_16x16x32_bf16 v[88:91], v[194:197], v[210:213], v[88:91]
	s_setprio 2
	s_barrier
; #define PG8_STAGE(bufoff, gbase, voff) do { _Pragma("unroll") for (int _i = 0; _i < 2; ++_i) \
;         __builtin_amdgcn_global_load_lds((const unsigned*)((const char*)(gbase) + (voff)[_i]), (PG8_LAS unsigned*)(lds + (bufoff) + ldsw + _i * 8192), 16, 0, 0); } while (0)
; #define PG8_LDA(dst, b, h) do { _Pragma("unroll") for (int m = 0; m < 4; ++m) _Pragma("unroll") for (int k = 0; k < 2; ++k) dst[m][k] = *(const PG8_LAS bf16x8*)(lds + PG8_SA(b, h) + aoff + m * 2048 + k * 1024); } while (0)
; #define PG8_MMA(ai, bj, At, Bt) do { __builtin_amdgcn_s_setprio(1); _Pragma("unroll") for (int m = 0; m < 4; ++m) _Pragma("unroll") for (int n = 0; n < 2; ++n) _Pragma("unroll") for (int k = 0; k < 2; ++k) \
;         acc[ai][bj][m][n] = __builtin_amdgcn_mfma_f32_16x16x32_bf16(Bt[n][k], At[m][k], acc[ai][bj][m][n], 0, 0, 0); __builtin_amdgcn_s_setprio(0); } while (0)
; #define PG8_WAIT_V(n) asm volatile("s_waitcnt vmcnt(" #n ")" ::: "memory")
; #define PG8_WAIT_L(n) asm volatile("s_waitcnt lgkmcnt(" #n ")" ::: "memory")
; #define PG8_BAR __builtin_amdgcn_s_barrier()
; #define PG8_SCHED __builtin_amdgcn_sched_barrier(0)
; template <class Epi, class Sched, bool ALIGN_EPI = false, bool SP2 = false>
; __device__ __forceinline__ void gemm_phase(PG8_LAS unsigned char* lds, const Gemm g, const Sched& S, const Epi& E) {
;     ...
;             PG8_WAIT_V(8); PG8_WAIT_L(0); PG8_BAR; PG8_MMA(0, 0, At, B0); PG8_MMA(0, 1, At, B1); PG8_BAR; PG8_SCHED;
;             PG8_LDA(At, 1, 1); PG8_STAGE(PG8_SB(1, 0), b3, voffB); PG8_STAGE(PG8_SB(1, 1), b3 + hstep, voffB); PG8_STAGE(PG8_SA(1, 0), a3, voffA);
;             PG8_WAIT_V(8); PG8_WAIT_L(0); PG8_BAR; PG8_MMA(1, 0, At, B0); PG8_MMA(1, 1, At, B1); PG8_BAR; PG8_SCHED;
	v_mfma_f32_16x16x32_bf16 v[80:83], v[186:189], v[218:221], v[80:83]
	v_mfma_f32_16x16x32_bf16 v[72:75], v[194:197], v[218:221], v[72:75]
	v_mfma_f32_16x16x32_bf16 v[68:71], v[186:189], v[226:229], v[68:71]
	v_mfma_f32_16x16x32_bf16 v[64:67], v[194:197], v[226:229], v[64:67]
	s_setprio 0
	s_mov_b32 m0, s89
	v_lshl_add_u64 v[230:231], v[230:231], 0, s[12:13]
	ds_read_b128 v[198:201], v164 offset:49152
	ds_read_b128 v[202:205], v164 offset:50176
	ds_read_b128 v[206:209], v164 offset:51200
	ds_read_b128 v[210:213], v164 offset:52224
	ds_read_b128 v[214:217], v164 offset:53248
	ds_read_b128 v[218:221], v164 offset:54272
	ds_read_b128 v[222:225], v164 offset:55296
	ds_read_b128 v[226:229], v164 offset:56320
	global_load_lds_dwordx4 v[230:231], off
	s_add_i32 m0, s89, 0x2000
	s_add_u32 s52, s74, 0x200080
	v_lshl_add_u64 v[230:231], v[232:233], 0, s[12:13]
	s_addc_u32 s53, s75, 0
	s_add_i32 s56, s88, s3
	global_load_lds_dwordx4 v[230:231], off
	v_lshl_add_u64 v[230:231], s[52:53], 0, v[138:139]
	s_mov_b32 m0, s56
	s_nop 0
	global_load_lds_dwordx4 v[230:231], off
	v_lshl_add_u64 v[230:231], s[52:53], 0, v[142:143]
	s_add_i32 m0, s56, 0x2000
	s_nop 0
	global_load_lds_dwordx4 v[230:231], off
	v_lshl_add_u64 v[230:231], v[234:235], 0, s[12:13]
	s_mov_b32 m0, s71
	s_nop 0
	global_load_lds_dwordx4 v[230:231], off
	v_lshl_add_u64 v[230:231], v[236:237], 0, s[12:13]
	s_mov_b32 m0, s78
	s_nop 0
	global_load_lds_dwordx4 v[230:231], off
	s_waitcnt vmcnt(8)
	s_waitcnt lgkmcnt(0)
	s_barrier
	s_setprio 1
	s_waitcnt lgkmcnt(0)
	v_mfma_f32_16x16x32_bf16 v[60:63], v[166:169], v[198:201], v[60:63]
	v_mfma_f32_16x16x32_bf16 v[56:59], v[174:177], v[198:201], v[56:59]
	v_mfma_f32_16x16x32_bf16 v[52:55], v[166:169], v[206:209], v[52:55]
	v_mfma_f32_16x16x32_bf16 v[44:47], v[174:177], v[206:209], v[44:47]
	v_mfma_f32_16x16x32_bf16 v[36:39], v[166:169], v[214:217], v[36:39]
	v_mfma_f32_16x16x32_bf16 v[28:31], v[174:177], v[214:217], v[28:31]
	v_mfma_f32_16x16x32_bf16 v[20:23], v[166:169], v[222:225], v[20:23]
	v_mfma_f32_16x16x32_bf16 v[12:15], v[174:177], v[222:225], v[12:15]
	v_mfma_f32_16x16x32_bf16 v[60:63], v[170:173], v[202:205], v[60:63]
	v_mfma_f32_16x16x32_bf16 v[56:59], v[178:181], v[202:205], v[56:59]
	v_mfma_f32_16x16x32_bf16 v[52:55], v[170:173], v[210:213], v[52:55]
	v_mfma_f32_16x16x32_bf16 v[44:47], v[178:181], v[210:213], v[44:47]
	v_mfma_f32_16x16x32_bf16 v[36:39], v[170:173], v[218:221], v[36:39]
	v_mfma_f32_16x16x32_bf16 v[28:31], v[178:181], v[218:221], v[28:31]
	v_mfma_f32_16x16x32_bf16 v[20:23], v[170:173], v[226:229], v[20:23]
	v_mfma_f32_16x16x32_bf16 v[12:15], v[178:181], v[226:229], v[12:15]
	s_setprio 0
	s_setprio 1
	v_mfma_f32_16x16x32_bf16 v[48:51], v[182:185], v[198:201], v[48:51]
	v_mfma_f32_16x16x32_bf16 v[40:43], v[190:193], v[198:201], v[40:43]
	v_mfma_f32_16x16x32_bf16 v[32:35], v[182:185], v[206:209], v[32:35]
	v_mfma_f32_16x16x32_bf16 v[24:27], v[190:193], v[206:209], v[24:27]
	v_mfma_f32_16x16x32_bf16 v[16:19], v[182:185], v[214:217], v[16:19]
	v_mfma_f32_16x16x32_bf16 v[8:11], v[190:193], v[214:217], v[8:11]
	v_mfma_f32_16x16x32_bf16 v[4:7], v[182:185], v[222:225], v[4:7]
	v_mfma_f32_16x16x32_bf16 v[0:3], v[190:193], v[222:225], v[0:3]
	v_mfma_f32_16x16x32_bf16 v[48:51], v[186:189], v[202:205], v[48:51]
	v_mfma_f32_16x16x32_bf16 v[40:43], v[194:197], v[202:205], v[40:43]
	v_mfma_f32_16x16x32_bf16 v[32:35], v[186:189], v[210:213], v[32:35]
	v_mfma_f32_16x16x32_bf16 v[24:27], v[194:197], v[210:213], v[24:27]
	s_setprio 2
	s_barrier
	v_mfma_f32_16x16x32_bf16 v[16:19], v[186:189], v[218:221], v[16:19]
	v_mfma_f32_16x16x32_bf16 v[8:11], v[194:197], v[218:221], v[8:11]
	v_mfma_f32_16x16x32_bf16 v[4:7], v[186:189], v[226:229], v[4:7]
	v_mfma_f32_16x16x32_bf16 v[0:3], v[194:197], v[226:229], v[0:3]
	s_setprio 0
	s_add_i32 s49, s49, 2
	s_add_u32 s72, s72, 0x100
	s_addc_u32 s73, s73, 0
	s_add_u32 s37, s37, 0x100
	s_addc_u32 s41, s41, 0
	s_cmp_gt_u32 s49, 29
	s_cbranch_scc0 .LBB0_660
	s_and_b64 vcc, exec, s[14:15]
	s_cbranch_vccz .LBB0_663
	s_barrier

; #define PG8_STAGE(bufoff, gbase, voff) do { _Pragma("unroll") for (int _i = 0; _i < 2; ++_i) \
;         __builtin_amdgcn_global_load_lds((const unsigned*)((const char*)(gbase) + (voff)[_i]), (PG8_LAS unsigned*)(lds + (bufoff) + ldsw + _i * 8192), 16, 0, 0); } while (0)
; #define PG8_LDA(dst, b, h) do { _Pragma("unroll") for (int m = 0; m < 4; ++m) _Pragma("unroll") for (int k = 0; k < 2; ++k) dst[m][k] = *(const PG8_LAS bf16x8*)(lds + PG8_SA(b, h) + aoff + m * 2048 + k * 1024); } while (0)
; #define PG8_LDB(dst, b, h) do { _Pragma("unroll") for (int n = 0; n < 2; ++n) _Pragma("unroll") for (int k = 0; k < 2; ++k) dst[n][k] = *(const PG8_LAS bf16x8*)(lds + PG8_SB(b, h) + boff + n * 2048 + k * 1024); } while (0)
; #define PG8_MMA(ai, bj, At, Bt) do { __builtin_amdgcn_s_setprio(1); _Pragma("unroll") for (int m = 0; m < 4; ++m) _Pragma("unroll") for (int n = 0; n < 2; ++n) _Pragma("unroll") for (int k = 0; k < 2; ++k) \
;         acc[ai][bj][m][n] = __builtin_amdgcn_mfma_f32_16x16x32_bf16(Bt[n][k], At[m][k], acc[ai][bj][m][n], 0, 0, 0); __builtin_amdgcn_s_setprio(0); } while (0)
; #define PG8_WAIT_V(n) asm volatile("s_waitcnt vmcnt(" #n ")" ::: "memory")
; #define PG8_WAIT_L(n) asm volatile("s_waitcnt lgkmcnt(" #n ")" ::: "memory")
; #define PG8_BAR __builtin_amdgcn_s_barrier()
; template <class Epi, class Sched, bool ALIGN_EPI = false, bool SP2 = false>
; __device__ __forceinline__ void gemm_phase(PG8_LAS unsigned char* lds, const Gemm g, const Sched& S, const Epi& E) {
;     ...
;             const bool last = (t == nt - 2);
;             const char* a1 = cA + (size_t)(t + 1) * kstep;
;             const char* a2 = last ? nA : cA + (size_t)(t + 2) * kstep; const char* b2 = last ? nB : cB + (size_t)(t + 2) * kstep;
;             const char* a3 = a2 + kstep; const char* b3 = b2 + kstep;
;             if constexpr (SP2) {
;             PG8_LDB(B0, 0, 0); PG8_LDB(B1, 0, 1); PG8_SCHED; PG8_LDA(At, 0, 0); PG8_STAGE(PG8_SA(1, 1), a1 + hstep, voffA);
;             PG8_WAIT_V(8); PG8_WAIT_L(0); PG8_BAR; PG8_MMA(0, 0, At, B0); PG8_MMA(0, 1, At, B1); PG8_BAR; PG8_SCHED;
;             PG8_LDA(At, 0, 1); PG8_STAGE(PG8_SB(0, 0), b2, voffB); PG8_STAGE(PG8_SB(0, 1), b2 + hstep, voffB); PG8_STAGE(PG8_SA(0, 0), a2, voffA);
;             PG8_WAIT_V(8); PG8_WAIT_L(0); PG8_BAR; PG8_MMA(1, 0, At, B0); PG8_MMA(1, 1, At, B1); PG8_BAR; PG8_SCHED;
.LBB0_809:
	ds_read_b128 v[128:131], v180
	ds_read_b128 v[132:135], v180 offset:1024
	ds_read_b128 v[136:139], v180 offset:2048
	ds_read_b128 v[140:143], v180 offset:3072
	ds_read_b128 v[160:163], v181
	ds_read_b128 v[164:167], v181 offset:1024
	ds_read_b128 v[184:187], v181 offset:2048
	ds_read_b128 v[188:191], v181 offset:3072
	s_add_u32 s52, s72, 0xfff80080
	s_addc_u32 s53, s73, -1
	s_cmp_eq_u32 s92, 28
	s_cselect_b32 s77, s5, s53
	s_cselect_b32 s76, s49, s52
	s_cselect_b32 s75, s45, s91
	s_cselect_b32 s74, s89, s90
	v_lshl_add_u64 v[168:169], s[72:73], 0, v[154:155]
	s_add_i32 m0, s71, 0xc000
	ds_read_b128 v[192:195], v182
	ds_read_b128 v[196:199], v182 offset:1024
	ds_read_b128 v[200:203], v182 offset:2048
	ds_read_b128 v[204:207], v182 offset:3072
	ds_read_b128 v[208:211], v182 offset:4096
	ds_read_b128 v[212:215], v182 offset:5120
	ds_read_b128 v[216:219], v182 offset:6144
	ds_read_b128 v[220:223], v182 offset:7168
	global_load_lds_dwordx4 v[168:169], off
	v_lshl_add_u64 v[168:169], s[72:73], 0, v[156:157]
	s_add_i32 m0, s71, 0xe000
	s_nop 0
	global_load_lds_dwordx4 v[168:169], off
	s_waitcnt vmcnt(8)
	s_waitcnt lgkmcnt(0)
	s_barrier
	s_setprio 1
	s_waitcnt lgkmcnt(0)
	v_mfma_f32_16x16x32_bf16 v[124:127], v[128:131], v[192:195], v[124:127]
	v_mfma_f32_16x16x32_bf16 v[120:123], v[136:139], v[192:195], v[120:123]
	v_mfma_f32_16x16x32_bf16 v[108:111], v[128:131], v[200:203], v[108:111]
	v_mfma_f32_16x16x32_bf16 v[104:107], v[136:139], v[200:203], v[104:107]
	v_mfma_f32_16x16x32_bf16 v[92:95], v[128:131], v[208:211], v[92:95]
	v_mfma_f32_16x16x32_bf16 v[88:91], v[136:139], v[208:211], v[88:91]
	v_mfma_f32_16x16x32_bf16 v[76:79], v[128:131], v[216:219], v[76:79]
	v_mfma_f32_16x16x32_bf16 v[72:75], v[136:139], v[216:219], v[72:75]
	v_mfma_f32_16x16x32_bf16 v[124:127], v[132:135], v[196:199], v[124:127]
	v_mfma_f32_16x16x32_bf16 v[120:123], v[140:143], v[196:199], v[120:123]
	v_mfma_f32_16x16x32_bf16 v[108:111], v[132:135], v[204:207], v[108:111]
	v_mfma_f32_16x16x32_bf16 v[104:107], v[140:143], v[204:207], v[104:107]
	v_mfma_f32_16x16x32_bf16 v[92:95], v[132:135], v[212:215], v[92:95]
	v_mfma_f32_16x16x32_bf16 v[88:91], v[140:143], v[212:215], v[88:91]
	v_mfma_f32_16x16x32_bf16 v[76:79], v[132:135], v[220:223], v[76:79]
	v_mfma_f32_16x16x32_bf16 v[72:75], v[140:143], v[220:223], v[72:75]
	s_setprio 0
	s_setprio 1
	v_mfma_f32_16x16x32_bf16 v[116:119], v[160:163], v[192:195], v[116:119]
	v_mfma_f32_16x16x32_bf16 v[112:115], v[184:187], v[192:195], v[112:115]
	v_mfma_f32_16x16x32_bf16 v[100:103], v[160:163], v[200:203], v[100:103]
	v_mfma_f32_16x16x32_bf16 v[96:99], v[184:187], v[200:203], v[96:99]
	v_mfma_f32_16x16x32_bf16 v[84:87], v[160:163], v[208:211], v[84:87]
	v_mfma_f32_16x16x32_bf16 v[80:83], v[184:187], v[208:211], v[80:83]
	v_mfma_f32_16x16x32_bf16 v[68:71], v[160:163], v[216:219], v[68:71]
	v_mfma_f32_16x16x32_bf16 v[64:67], v[184:187], v[216:219], v[64:67]
	v_mfma_f32_16x16x32_bf16 v[116:119], v[164:167], v[196:199], v[116:119]
	v_mfma_f32_16x16x32_bf16 v[112:115], v[188:191], v[196:199], v[112:115]
	v_mfma_f32_16x16x32_bf16 v[100:103], v[164:167], v[204:207], v[100:103]
	v_mfma_f32_16x16x32_bf16 v[96:99], v[188:191], v[204:207], v[96:99]
	s_setprio 2
	s_barrier
	v_mfma_f32_16x16x32_bf16 v[84:87], v[164:167], v[212:215], v[84:87]
	v_mfma_f32_16x16x32_bf16 v[80:83], v[188:191], v[212:215], v[80:83]
	v_mfma_f32_16x16x32_bf16 v[68:71], v[164:167], v[220:223], v[68:71]
	v_mfma_f32_16x16x32_bf16 v[64:67], v[188:191], v[220:223], v[64:67]
	s_setprio 0
	s_add_i32 s52, s83, s78
	v_lshl_add_u64 v[168:169], s[74:75], 0, v[148:149]
	s_mov_b32 m0, s52
	ds_read_b128 v[192:195], v182 offset:16384
	ds_read_b128 v[196:199], v182 offset:17408
	ds_read_b128 v[200:203], v182 offset:18432
	ds_read_b128 v[204:207], v182 offset:19456
	ds_read_b128 v[208:211], v182 offset:20480
	ds_read_b128 v[212:215], v182 offset:21504
	ds_read_b128 v[216:219], v182 offset:22528
	ds_read_b128 v[220:223], v182 offset:23552
	global_load_lds_dwordx4 v[168:169], off
	s_add_i32 m0, s52, 0x2000
	s_add_u32 s52, s74, 0x80000
	v_lshl_add_u64 v[224:225], s[74:75], 0, v[152:153]
	s_addc_u32 s53, s75, 0
	s_add_i32 s56, s84, s78
	global_load_lds_dwordx4 v[224:225], off
	v_lshl_add_u64 v[226:227], s[52:53], 0, v[148:149]
	s_mov_b32 m0, s56
	v_lshl_add_u64 v[228:229], s[76:77], 0, v[150:151]
	global_load_lds_dwordx4 v[226:227], off
	v_lshl_add_u64 v[226:227], s[52:53], 0, v[152:153]
	s_add_i32 m0, s56, 0x2000
	s_nop 0
	global_load_lds_dwordx4 v[226:227], off
	v_lshl_add_u64 v[226:227], s[76:77], 0, v[144:145]
	s_mov_b32 m0, s71
	s_nop 0
	global_load_lds_dwordx4 v[226:227], off
	s_mov_b32 m0, s79
	s_nop 0
	global_load_lds_dwordx4 v[228:229], off
	s_waitcnt vmcnt(8)
	s_waitcnt lgkmcnt(0)
	s_barrier
; #define PG8_STAGE(bufoff, gbase, voff) do { _Pragma("unroll") for (int _i = 0; _i < 2; ++_i) \
;         __builtin_amdgcn_global_load_lds((const unsigned*)((const char*)(gbase) + (voff)[_i]), (PG8_LAS unsigned*)(lds + (bufoff) + ldsw + _i * 8192), 16, 0, 0); } while (0)
; #define PG8_LDA(dst, b, h) do { _Pragma("unroll") for (int m = 0; m < 4; ++m) _Pragma("unroll") for (int k = 0; k < 2; ++k) dst[m][k] = *(const PG8_LAS bf16x8*)(lds + PG8_SA(b, h) + aoff + m * 2048 + k * 1024); } while (0)
; #define PG8_LDB(dst, b, h) do { _Pragma("unroll") for (int n = 0; n < 2; ++n) _Pragma("unroll") for (int k = 0; k < 2; ++k) dst[n][k] = *(const PG8_LAS bf16x8*)(lds + PG8_SB(b, h) + boff + n * 2048 + k * 1024); } while (0)
; #define PG8_MMA(ai, bj, At, Bt) do { __builtin_amdgcn_s_setprio(1); _Pragma("unroll") for (int m = 0; m < 4; ++m) _Pragma("unroll") for (int n = 0; n < 2; ++n) _Pragma("unroll") for (int k = 0; k < 2; ++k) \
;         acc[ai][bj][m][n] = __builtin_amdgcn_mfma_f32_16x16x32_bf16(Bt[n][k], At[m][k], acc[ai][bj][m][n], 0, 0, 0); __builtin_amdgcn_s_setprio(0); } while (0)
; #define PG8_WAIT_V(n) asm volatile("s_waitcnt vmcnt(" #n ")" ::: "memory")
; #define PG8_WAIT_L(n) asm volatile("s_waitcnt lgkmcnt(" #n ")" ::: "memory")
; #define PG8_BAR __builtin_amdgcn_s_barrier()
; #define PG8_SCHED __builtin_amdgcn_sched_barrier(0)
; template <class Epi, class Sched, bool ALIGN_EPI = false, bool SP2 = false>
; __device__ __forceinline__ void gemm_phase(PG8_LAS unsigned char* lds, const Gemm g, const Sched& S, const Epi& E) {
;     ...
;             PG8_WAIT_V(8); PG8_WAIT_L(0); PG8_BAR; PG8_MMA(1, 0, At, B0); PG8_MMA(1, 1, At, B1); PG8_BAR; PG8_SCHED;
;             PG8_LDB(B0, 1, 0); PG8_LDB(B1, 1, 1); PG8_SCHED; PG8_LDA(At, 1, 0); PG8_STAGE(PG8_SA(0, 1), a2 + hstep, voffA);
;             PG8_WAIT_V(8); PG8_WAIT_L(0); PG8_BAR; PG8_MMA(0, 0, At, B0); PG8_MMA(0, 1, At, B1); PG8_BAR; PG8_SCHED;
	s_setprio 1
	s_waitcnt lgkmcnt(0)
	v_mfma_f32_16x16x32_bf16 v[60:63], v[128:131], v[192:195], v[60:63]
	v_mfma_f32_16x16x32_bf16 v[56:59], v[136:139], v[192:195], v[56:59]
	v_mfma_f32_16x16x32_bf16 v[44:47], v[128:131], v[200:203], v[44:47]
	v_mfma_f32_16x16x32_bf16 v[40:43], v[136:139], v[200:203], v[40:43]
	v_mfma_f32_16x16x32_bf16 v[28:31], v[128:131], v[208:211], v[28:31]
	v_mfma_f32_16x16x32_bf16 v[24:27], v[136:139], v[208:211], v[24:27]
	v_mfma_f32_16x16x32_bf16 v[12:15], v[128:131], v[216:219], v[12:15]
	v_mfma_f32_16x16x32_bf16 v[8:11], v[136:139], v[216:219], v[8:11]
	v_mfma_f32_16x16x32_bf16 v[60:63], v[132:135], v[196:199], v[60:63]
	v_mfma_f32_16x16x32_bf16 v[56:59], v[140:143], v[196:199], v[56:59]
	v_mfma_f32_16x16x32_bf16 v[44:47], v[132:135], v[204:207], v[44:47]
	v_mfma_f32_16x16x32_bf16 v[40:43], v[140:143], v[204:207], v[40:43]
	v_mfma_f32_16x16x32_bf16 v[28:31], v[132:135], v[212:215], v[28:31]
	v_mfma_f32_16x16x32_bf16 v[24:27], v[140:143], v[212:215], v[24:27]
	v_mfma_f32_16x16x32_bf16 v[12:15], v[132:135], v[220:223], v[12:15]
	v_mfma_f32_16x16x32_bf16 v[8:11], v[140:143], v[220:223], v[8:11]
	s_setprio 0
	s_setprio 1
	v_mfma_f32_16x16x32_bf16 v[52:55], v[160:163], v[192:195], v[52:55]
	v_mfma_f32_16x16x32_bf16 v[48:51], v[184:187], v[192:195], v[48:51]
	v_mfma_f32_16x16x32_bf16 v[36:39], v[160:163], v[200:203], v[36:39]
	v_mfma_f32_16x16x32_bf16 v[32:35], v[184:187], v[200:203], v[32:35]
	v_mfma_f32_16x16x32_bf16 v[20:23], v[160:163], v[208:211], v[20:23]
	v_mfma_f32_16x16x32_bf16 v[16:19], v[184:187], v[208:211], v[16:19]
	v_mfma_f32_16x16x32_bf16 v[4:7], v[160:163], v[216:219], v[4:7]
	v_mfma_f32_16x16x32_bf16 v[0:3], v[184:187], v[216:219], v[0:3]
	v_mfma_f32_16x16x32_bf16 v[52:55], v[164:167], v[196:199], v[52:55]
	v_mfma_f32_16x16x32_bf16 v[48:51], v[188:191], v[196:199], v[48:51]
	v_mfma_f32_16x16x32_bf16 v[36:39], v[164:167], v[204:207], v[36:39]
	v_mfma_f32_16x16x32_bf16 v[32:35], v[188:191], v[204:207], v[32:35]
	s_setprio 2
	s_barrier
	v_mfma_f32_16x16x32_bf16 v[20:23], v[164:167], v[212:215], v[20:23]
	v_mfma_f32_16x16x32_bf16 v[16:19], v[188:191], v[212:215], v[16:19]
	v_mfma_f32_16x16x32_bf16 v[4:7], v[164:167], v[220:223], v[4:7]
	v_mfma_f32_16x16x32_bf16 v[0:3], v[188:191], v[220:223], v[0:3]
	s_setprio 0
	s_add_i32 s56, 0, 0x18000
	s_add_i32 s57, 0, 0x1c000
	v_add_u32_e32 v140, s56, v171
	v_add_u32_e32 v188, s57, v171
	ds_read_b128 v[128:131], v140
	ds_read_b128 v[132:135], v140 offset:1024
	ds_read_b128 v[136:139], v140 offset:2048
	ds_read_b128 v[140:143], v140 offset:3072
	ds_read_b128 v[160:163], v188
	ds_read_b128 v[164:167], v188 offset:1024
	ds_read_b128 v[184:187], v188 offset:2048
	ds_read_b128 v[188:191], v188 offset:3072
	s_add_u32 s52, s76, 0x80000
	s_addc_u32 s53, s77, 0
	s_mov_b32 m0, s80
	v_lshl_add_u64 v[230:231], s[52:53], 0, v[144:145]
	ds_read_b128 v[192:195], v182 offset:32768
	ds_read_b128 v[196:199], v182 offset:33792
	ds_read_b128 v[200:203], v182 offset:34816
	ds_read_b128 v[204:207], v182 offset:35840
	ds_read_b128 v[208:211], v182 offset:36864
	ds_read_b128 v[212:215], v182 offset:37888
	ds_read_b128 v[216:219], v182 offset:38912
	ds_read_b128 v[220:223], v182 offset:39936
	global_load_lds_dwordx4 v[230:231], off
	v_lshl_add_u64 v[230:231], s[52:53], 0, v[150:151]
	s_mov_b32 m0, s81
	s_nop 0
	global_load_lds_dwordx4 v[230:231], off
	s_waitcnt vmcnt(8)
	s_waitcnt lgkmcnt(0)
	s_barrier
	s_setprio 1
	s_waitcnt lgkmcnt(0)
	v_mfma_f32_16x16x32_bf16 v[124:127], v[128:131], v[192:195], v[124:127]
	v_mfma_f32_16x16x32_bf16 v[120:123], v[136:139], v[192:195], v[120:123]
	v_mfma_f32_16x16x32_bf16 v[108:111], v[128:131], v[200:203], v[108:111]
	v_mfma_f32_16x16x32_bf16 v[104:107], v[136:139], v[200:203], v[104:107]
	v_mfma_f32_16x16x32_bf16 v[92:95], v[128:131], v[208:211], v[92:95]
	v_mfma_f32_16x16x32_bf16 v[88:91], v[136:139], v[208:211], v[88:91]
	v_mfma_f32_16x16x32_bf16 v[76:79], v[128:131], v[216:219], v[76:79]
	v_mfma_f32_16x16x32_bf16 v[72:75], v[136:139], v[216:219], v[72:75]
	v_mfma_f32_16x16x32_bf16 v[124:127], v[132:135], v[196:199], v[124:127]
	v_mfma_f32_16x16x32_bf16 v[120:123], v[140:143], v[196:199], v[120:123]
	v_mfma_f32_16x16x32_bf16 v[108:111], v[132:135], v[204:207], v[108:111]
	v_mfma_f32_16x16x32_bf16 v[104:107], v[140:143], v[204:207], v[104:107]
	v_mfma_f32_16x16x32_bf16 v[92:95], v[132:135], v[212:215], v[92:95]
	v_mfma_f32_16x16x32_bf16 v[88:91], v[140:143], v[212:215], v[88:91]
	v_mfma_f32_16x16x32_bf16 v[76:79], v[132:135], v[220:223], v[76:79]
	v_mfma_f32_16x16x32_bf16 v[72:75], v[140:143], v[220:223], v[72:75]
	s_setprio 0
	s_setprio 1
	v_mfma_f32_16x16x32_bf16 v[116:119], v[160:163], v[192:195], v[116:119]
	v_mfma_f32_16x16x32_bf16 v[112:115], v[184:187], v[192:195], v[112:115]
	v_mfma_f32_16x16x32_bf16 v[100:103], v[160:163], v[200:203], v[100:103]
	v_mfma_f32_16x16x32_bf16 v[96:99], v[184:187], v[200:203], v[96:99]
	v_mfma_f32_16x16x32_bf16 v[84:87], v[160:163], v[208:211], v[84:87]
	v_mfma_f32_16x16x32_bf16 v[80:83], v[184:187], v[208:211], v[80:83]
	v_mfma_f32_16x16x32_bf16 v[68:71], v[160:163], v[216:219], v[68:71]
	v_mfma_f32_16x16x32_bf16 v[64:67], v[184:187], v[216:219], v[64:67]
	v_mfma_f32_16x16x32_bf16 v[116:119], v[164:167], v[196:199], v[116:119]
	v_mfma_f32_16x16x32_bf16 v[112:115], v[188:191], v[196:199], v[112:115]
	v_mfma_f32_16x16x32_bf16 v[100:103], v[164:167], v[204:207], v[100:103]
	v_mfma_f32_16x16x32_bf16 v[96:99], v[188:191], v[204:207], v[96:99]
	s_setprio 2
	s_barrier
; #define PG8_STAGE(bufoff, gbase, voff) do { _Pragma("unroll") for (int _i = 0; _i < 2; ++_i) \
;         __builtin_amdgcn_global_load_lds((const unsigned*)((const char*)(gbase) + (voff)[_i]), (PG8_LAS unsigned*)(lds + (bufoff) + ldsw + _i * 8192), 16, 0, 0); } while (0)
; #define PG8_LDA(dst, b, h) do { _Pragma("unroll") for (int m = 0; m < 4; ++m) _Pragma("unroll") for (int k = 0; k < 2; ++k) dst[m][k] = *(const PG8_LAS bf16x8*)(lds + PG8_SA(b, h) + aoff + m * 2048 + k * 1024); } while (0)
; #define PG8_MMA(ai, bj, At, Bt) do { __builtin_amdgcn_s_setprio(1); _Pragma("unroll") for (int m = 0; m < 4; ++m) _Pragma("unroll") for (int n = 0; n < 2; ++n) _Pragma("unroll") for (int k = 0; k < 2; ++k) \
;         acc[ai][bj][m][n] = __builtin_amdgcn_mfma_f32_16x16x32_bf16(Bt[n][k], At[m][k], acc[ai][bj][m][n], 0, 0, 0); __builtin_amdgcn_s_setprio(0); } while (0)
; #define PG8_WAIT_V(n) asm volatile("s_waitcnt vmcnt(" #n ")" ::: "memory")
; #define PG8_WAIT_L(n) asm volatile("s_waitcnt lgkmcnt(" #n ")" ::: "memory")
; #define PG8_BAR __builtin_amdgcn_s_barrier()
; #define PG8_SCHED __builtin_amdgcn_sched_barrier(0)
; template <class Epi, class Sched, bool ALIGN_EPI = false, bool SP2 = false>
; __device__ __forceinline__ void gemm_phase(PG8_LAS unsigned char* lds, const Gemm g, const Sched& S, const Epi& E) {
;     ...
;             PG8_WAIT_V(8); PG8_WAIT_L(0); PG8_BAR; PG8_MMA(0, 0, At, B0); PG8_MMA(0, 1, At, B1); PG8_BAR; PG8_SCHED;
;             PG8_LDA(At, 1, 1); PG8_STAGE(PG8_SB(1, 0), b3, voffB); PG8_STAGE(PG8_SB(1, 1), b3 + hstep, voffB); PG8_STAGE(PG8_SA(1, 0), a3, voffA);
;             PG8_WAIT_V(8); PG8_WAIT_L(0); PG8_BAR; PG8_MMA(1, 0, At, B0); PG8_MMA(1, 1, At, B1); PG8_BAR; PG8_SCHED;
	v_mfma_f32_16x16x32_bf16 v[84:87], v[164:167], v[212:215], v[84:87]
	v_mfma_f32_16x16x32_bf16 v[80:83], v[188:191], v[212:215], v[80:83]
	v_mfma_f32_16x16x32_bf16 v[68:71], v[164:167], v[220:223], v[68:71]
	v_mfma_f32_16x16x32_bf16 v[64:67], v[188:191], v[220:223], v[64:67]
	s_setprio 0
	s_add_i32 s52, s56, s78
	v_lshl_add_u64 v[168:169], v[168:169], 0, s[40:41]
	s_mov_b32 m0, s52
	ds_read_b128 v[192:195], v182 offset:49152
	ds_read_b128 v[196:199], v182 offset:50176
	ds_read_b128 v[200:203], v182 offset:51200
	ds_read_b128 v[204:207], v182 offset:52224
	ds_read_b128 v[208:211], v182 offset:53248
	ds_read_b128 v[212:215], v182 offset:54272
	ds_read_b128 v[216:219], v182 offset:55296
	ds_read_b128 v[220:223], v182 offset:56320
	global_load_lds_dwordx4 v[168:169], off
	s_add_i32 m0, s52, 0x2000
	s_add_u32 s52, s74, 0x80080
	v_lshl_add_u64 v[168:169], v[224:225], 0, s[40:41]
	s_addc_u32 s53, s75, 0
	s_add_i32 s56, s57, s78
	global_load_lds_dwordx4 v[168:169], off
	v_lshl_add_u64 v[168:169], s[52:53], 0, v[148:149]
	s_mov_b32 m0, s56
	s_nop 0
	global_load_lds_dwordx4 v[168:169], off
	v_lshl_add_u64 v[168:169], s[52:53], 0, v[152:153]
	s_add_i32 m0, s56, 0x2000
	s_nop 0
	global_load_lds_dwordx4 v[168:169], off
	v_lshl_add_u64 v[168:169], v[226:227], 0, s[40:41]
	s_mov_b32 m0, s3
	s_nop 0
	global_load_lds_dwordx4 v[168:169], off
	v_lshl_add_u64 v[168:169], v[228:229], 0, s[40:41]
	s_mov_b32 m0, s28
	s_nop 0
	global_load_lds_dwordx4 v[168:169], off
	s_waitcnt vmcnt(8)
	s_waitcnt lgkmcnt(0)
	s_barrier
	s_setprio 1
	s_waitcnt lgkmcnt(0)
	v_mfma_f32_16x16x32_bf16 v[60:63], v[128:131], v[192:195], v[60:63]
	v_mfma_f32_16x16x32_bf16 v[56:59], v[136:139], v[192:195], v[56:59]
	v_mfma_f32_16x16x32_bf16 v[44:47], v[128:131], v[200:203], v[44:47]
	v_mfma_f32_16x16x32_bf16 v[40:43], v[136:139], v[200:203], v[40:43]
	v_mfma_f32_16x16x32_bf16 v[28:31], v[128:131], v[208:211], v[28:31]
	v_mfma_f32_16x16x32_bf16 v[24:27], v[136:139], v[208:211], v[24:27]
	v_mfma_f32_16x16x32_bf16 v[12:15], v[128:131], v[216:219], v[12:15]
	v_mfma_f32_16x16x32_bf16 v[8:11], v[136:139], v[216:219], v[8:11]
	v_mfma_f32_16x16x32_bf16 v[60:63], v[132:135], v[196:199], v[60:63]
	v_mfma_f32_16x16x32_bf16 v[56:59], v[140:143], v[196:199], v[56:59]
	v_mfma_f32_16x16x32_bf16 v[44:47], v[132:135], v[204:207], v[44:47]
	v_mfma_f32_16x16x32_bf16 v[40:43], v[140:143], v[204:207], v[40:43]
	v_mfma_f32_16x16x32_bf16 v[28:31], v[132:135], v[212:215], v[28:31]
	v_mfma_f32_16x16x32_bf16 v[24:27], v[140:143], v[212:215], v[24:27]
	v_mfma_f32_16x16x32_bf16 v[12:15], v[132:135], v[220:223], v[12:15]
	v_mfma_f32_16x16x32_bf16 v[8:11], v[140:143], v[220:223], v[8:11]
	s_setprio 0
	s_setprio 1
	v_mfma_f32_16x16x32_bf16 v[52:55], v[160:163], v[192:195], v[52:55]
	v_mfma_f32_16x16x32_bf16 v[48:51], v[184:187], v[192:195], v[48:51]
	v_mfma_f32_16x16x32_bf16 v[36:39], v[160:163], v[200:203], v[36:39]
	v_mfma_f32_16x16x32_bf16 v[32:35], v[184:187], v[200:203], v[32:35]
	v_mfma_f32_16x16x32_bf16 v[20:23], v[160:163], v[208:211], v[20:23]
	v_mfma_f32_16x16x32_bf16 v[16:19], v[184:187], v[208:211], v[16:19]
	v_mfma_f32_16x16x32_bf16 v[4:7], v[160:163], v[216:219], v[4:7]
	v_mfma_f32_16x16x32_bf16 v[0:3], v[184:187], v[216:219], v[0:3]
	v_mfma_f32_16x16x32_bf16 v[52:55], v[164:167], v[196:199], v[52:55]
	v_mfma_f32_16x16x32_bf16 v[48:51], v[188:191], v[196:199], v[48:51]
	v_mfma_f32_16x16x32_bf16 v[36:39], v[164:167], v[204:207], v[36:39]
	v_mfma_f32_16x16x32_bf16 v[32:35], v[188:191], v[204:207], v[32:35]
	s_setprio 2
	s_barrier
	v_mfma_f32_16x16x32_bf16 v[20:23], v[164:167], v[212:215], v[20:23]
	v_mfma_f32_16x16x32_bf16 v[16:19], v[188:191], v[212:215], v[16:19]
	v_mfma_f32_16x16x32_bf16 v[4:7], v[164:167], v[220:223], v[4:7]
	v_mfma_f32_16x16x32_bf16 v[0:3], v[188:191], v[220:223], v[0:3]
	s_setprio 0
	s_add_i32 s92, s92, 2
	s_add_u32 s72, s72, 0x100
	s_addc_u32 s73, s73, 0
	s_add_u32 s90, s90, 0x100
	s_addc_u32 s91, s91, 0
	s_cmp_gt_u32 s92, 29
	s_cbranch_scc0 .LBB0_809
	s_and_b64 vcc, exec, s[42:43]
	s_cbranch_vccz .LBB0_812
	s_barrier

; #define PG8_STAGE(bufoff, gbase, voff) do { _Pragma("unroll") for (int _i = 0; _i < 2; ++_i) \
;         __builtin_amdgcn_global_load_lds((const unsigned*)((const char*)(gbase) + (voff)[_i]), (PG8_LAS unsigned*)(lds + (bufoff) + ldsw + _i * 8192), 16, 0, 0); } while (0)
; #define PG8_LDA(dst, b, h) do { _Pragma("unroll") for (int m = 0; m < 4; ++m) _Pragma("unroll") for (int k = 0; k < 2; ++k) dst[m][k] = *(const PG8_LAS bf16x8*)(lds + PG8_SA(b, h) + aoff + m * 2048 + k * 1024); } while (0)
; #define PG8_LDB(dst, b, h) do { _Pragma("unroll") for (int n = 0; n < 2; ++n) _Pragma("unroll") for (int k = 0; k < 2; ++k) dst[n][k] = *(const PG8_LAS bf16x8*)(lds + PG8_SB(b, h) + boff + n * 2048 + k * 1024); } while (0)
; #define PG8_MMA(ai, bj, At, Bt) do { __builtin_amdgcn_s_setprio(1); _Pragma("unroll") for (int m = 0; m < 4; ++m) _Pragma("unroll") for (int n = 0; n < 2; ++n) _Pragma("unroll") for (int k = 0; k < 2; ++k) \
;         acc[ai][bj][m][n] = __builtin_amdgcn_mfma_f32_16x16x32_bf16(Bt[n][k], At[m][k], acc[ai][bj][m][n], 0, 0, 0); __builtin_amdgcn_s_setprio(0); } while (0)
; #define PG8_WAIT_V(n) asm volatile("s_waitcnt vmcnt(" #n ")" ::: "memory")
; #define PG8_WAIT_L(n) asm volatile("s_waitcnt lgkmcnt(" #n ")" ::: "memory")
; #define PG8_BAR __builtin_amdgcn_s_barrier()
; template <class Epi, class Sched, bool ALIGN_EPI = false, bool SP2 = false>
; __device__ __forceinline__ void gemm_phase(PG8_LAS unsigned char* lds, const Gemm g, const Sched& S, const Epi& E) {
;     ...
;             const bool last = (t == nt - 2);
;             const char* a1 = cA + (size_t)(t + 1) * kstep;
;             const char* a2 = last ? nA : cA + (size_t)(t + 2) * kstep; const char* b2 = last ? nB : cB + (size_t)(t + 2) * kstep;
;             const char* a3 = a2 + kstep; const char* b3 = b2 + kstep;
;             if constexpr (SP2) {
;             PG8_LDB(B0, 0, 0); PG8_LDB(B1, 0, 1); PG8_SCHED; PG8_LDA(At, 0, 0); PG8_STAGE(PG8_SA(1, 1), a1 + hstep, voffA);
;             PG8_WAIT_V(8); PG8_WAIT_L(0); PG8_BAR; PG8_MMA(0, 0, At, B0); PG8_MMA(0, 1, At, B1); PG8_BAR; PG8_SCHED;
;             PG8_LDA(At, 0, 1); PG8_STAGE(PG8_SB(0, 0), b2, voffB); PG8_STAGE(PG8_SB(0, 1), b2 + hstep, voffB); PG8_STAGE(PG8_SA(0, 0), a2, voffA);
;             PG8_WAIT_V(8); PG8_WAIT_L(0); PG8_BAR; PG8_MMA(1, 0, At, B0); PG8_MMA(1, 1, At, B1); PG8_BAR; PG8_SCHED;
.LBB0_1051:
	ds_read_b128 v[128:131], v205
	ds_read_b128 v[132:135], v205 offset:1024
	ds_read_b128 v[154:157], v205 offset:2048
	ds_read_b128 v[158:161], v205 offset:3072
	ds_read_b128 v[162:165], v206
	ds_read_b128 v[166:169], v206 offset:1024
	ds_read_b128 v[170:173], v206 offset:2048
	ds_read_b128 v[174:177], v206 offset:3072
	s_add_u32 s54, s52, 0xfff80080
	s_addc_u32 s55, s53, -1
	s_cmp_eq_u32 s77, 28
	s_cselect_b32 s57, s43, s55
	s_cselect_b32 s56, s49, s54
	s_cselect_b32 s55, s37, s76
	s_cselect_b32 s54, s51, s75
	v_lshl_add_u64 v[218:219], s[52:53], 0, v[144:145]
	s_add_i32 m0, s61, 0xc000
	ds_read_b128 v[178:181], v207
	ds_read_b128 v[182:185], v207 offset:1024
	ds_read_b128 v[186:189], v207 offset:2048
	ds_read_b128 v[190:193], v207 offset:3072
	ds_read_b128 v[194:197], v207 offset:4096
	ds_read_b128 v[198:201], v207 offset:5120
	ds_read_b128 v[210:213], v207 offset:6144
	ds_read_b128 v[214:217], v207 offset:7168
	global_load_lds_dwordx4 v[218:219], off
	v_lshl_add_u64 v[218:219], s[52:53], 0, v[148:149]
	s_add_i32 m0, s61, 0xe000
	s_nop 0
	global_load_lds_dwordx4 v[218:219], off
	s_waitcnt vmcnt(8)
	s_waitcnt lgkmcnt(0)
	s_barrier
	s_setprio 1
	s_waitcnt lgkmcnt(0)
	v_mfma_f32_16x16x32_bf16 v[124:127], v[128:131], v[178:181], v[124:127]
	v_mfma_f32_16x16x32_bf16 v[120:123], v[154:157], v[178:181], v[120:123]
	v_mfma_f32_16x16x32_bf16 v[116:119], v[128:131], v[186:189], v[116:119]
	v_mfma_f32_16x16x32_bf16 v[112:115], v[154:157], v[186:189], v[112:115]
	v_mfma_f32_16x16x32_bf16 v[108:111], v[128:131], v[194:197], v[108:111]
	v_mfma_f32_16x16x32_bf16 v[104:107], v[154:157], v[194:197], v[104:107]
	v_mfma_f32_16x16x32_bf16 v[100:103], v[128:131], v[210:213], v[100:103]
	v_mfma_f32_16x16x32_bf16 v[96:99], v[154:157], v[210:213], v[96:99]
	v_mfma_f32_16x16x32_bf16 v[124:127], v[132:135], v[182:185], v[124:127]
	v_mfma_f32_16x16x32_bf16 v[120:123], v[158:161], v[182:185], v[120:123]
	v_mfma_f32_16x16x32_bf16 v[116:119], v[132:135], v[190:193], v[116:119]
	v_mfma_f32_16x16x32_bf16 v[112:115], v[158:161], v[190:193], v[112:115]
	v_mfma_f32_16x16x32_bf16 v[108:111], v[132:135], v[198:201], v[108:111]
	v_mfma_f32_16x16x32_bf16 v[104:107], v[158:161], v[198:201], v[104:107]
	v_mfma_f32_16x16x32_bf16 v[100:103], v[132:135], v[214:217], v[100:103]
	v_mfma_f32_16x16x32_bf16 v[96:99], v[158:161], v[214:217], v[96:99]
	s_setprio 0
	s_setprio 1
	v_mfma_f32_16x16x32_bf16 v[60:63], v[162:165], v[178:181], v[60:63]
	v_mfma_f32_16x16x32_bf16 v[56:59], v[170:173], v[178:181], v[56:59]
	v_mfma_f32_16x16x32_bf16 v[52:55], v[162:165], v[186:189], v[52:55]
	v_mfma_f32_16x16x32_bf16 v[48:51], v[170:173], v[186:189], v[48:51]
	v_mfma_f32_16x16x32_bf16 v[44:47], v[162:165], v[194:197], v[44:47]
	v_mfma_f32_16x16x32_bf16 v[40:43], v[170:173], v[194:197], v[40:43]
	v_mfma_f32_16x16x32_bf16 v[36:39], v[162:165], v[210:213], v[36:39]
	v_mfma_f32_16x16x32_bf16 v[32:35], v[170:173], v[210:213], v[32:35]
	v_mfma_f32_16x16x32_bf16 v[60:63], v[166:169], v[182:185], v[60:63]
	v_mfma_f32_16x16x32_bf16 v[56:59], v[174:177], v[182:185], v[56:59]
	v_mfma_f32_16x16x32_bf16 v[52:55], v[166:169], v[190:193], v[52:55]
	v_mfma_f32_16x16x32_bf16 v[48:51], v[174:177], v[190:193], v[48:51]
	s_setprio 2
	s_barrier
	v_mfma_f32_16x16x32_bf16 v[44:47], v[166:169], v[198:201], v[44:47]
	v_mfma_f32_16x16x32_bf16 v[40:43], v[174:177], v[198:201], v[40:43]
	v_mfma_f32_16x16x32_bf16 v[36:39], v[166:169], v[214:217], v[36:39]
	v_mfma_f32_16x16x32_bf16 v[32:35], v[174:177], v[214:217], v[32:35]
	s_setprio 0
	s_add_i32 s78, s33, s60
	v_lshl_add_u64 v[218:219], s[54:55], 0, v[138:139]
	s_mov_b32 m0, s78
	ds_read_b128 v[178:181], v207 offset:16384
	ds_read_b128 v[182:185], v207 offset:17408
	ds_read_b128 v[186:189], v207 offset:18432
	ds_read_b128 v[190:193], v207 offset:19456
	ds_read_b128 v[194:197], v207 offset:20480
	ds_read_b128 v[198:201], v207 offset:21504
	ds_read_b128 v[210:213], v207 offset:22528
	ds_read_b128 v[214:217], v207 offset:23552
	global_load_lds_dwordx4 v[218:219], off
	s_add_i32 m0, s78, 0x2000
	s_add_u32 s78, s54, 0x80000
	v_lshl_add_u64 v[220:221], s[54:55], 0, v[142:143]
	s_addc_u32 s79, s55, 0
	s_add_i32 s80, s74, s60
	global_load_lds_dwordx4 v[220:221], off
	v_lshl_add_u64 v[222:223], s[78:79], 0, v[138:139]
	s_mov_b32 m0, s80
	v_lshl_add_u64 v[224:225], s[56:57], 0, v[140:141]
	global_load_lds_dwordx4 v[222:223], off
	v_lshl_add_u64 v[222:223], s[78:79], 0, v[142:143]
	s_add_i32 m0, s80, 0x2000
	s_nop 0
	global_load_lds_dwordx4 v[222:223], off
	v_lshl_add_u64 v[222:223], s[56:57], 0, v[136:137]
	s_mov_b32 m0, s61
	s_nop 0
	global_load_lds_dwordx4 v[222:223], off
	s_mov_b32 m0, s62
	s_nop 0
	global_load_lds_dwordx4 v[224:225], off
	s_waitcnt vmcnt(8)
	s_waitcnt lgkmcnt(0)
	s_barrier
; #define PG8_STAGE(bufoff, gbase, voff) do { _Pragma("unroll") for (int _i = 0; _i < 2; ++_i) \
;         __builtin_amdgcn_global_load_lds((const unsigned*)((const char*)(gbase) + (voff)[_i]), (PG8_LAS unsigned*)(lds + (bufoff) + ldsw + _i * 8192), 16, 0, 0); } while (0)
; #define PG8_LDA(dst, b, h) do { _Pragma("unroll") for (int m = 0; m < 4; ++m) _Pragma("unroll") for (int k = 0; k < 2; ++k) dst[m][k] = *(const PG8_LAS bf16x8*)(lds + PG8_SA(b, h) + aoff + m * 2048 + k * 1024); } while (0)
; #define PG8_LDB(dst, b, h) do { _Pragma("unroll") for (int n = 0; n < 2; ++n) _Pragma("unroll") for (int k = 0; k < 2; ++k) dst[n][k] = *(const PG8_LAS bf16x8*)(lds + PG8_SB(b, h) + boff + n * 2048 + k * 1024); } while (0)
; #define PG8_MMA(ai, bj, At, Bt) do { __builtin_amdgcn_s_setprio(1); _Pragma("unroll") for (int m = 0; m < 4; ++m) _Pragma("unroll") for (int n = 0; n < 2; ++n) _Pragma("unroll") for (int k = 0; k < 2; ++k) \
;         acc[ai][bj][m][n] = __builtin_amdgcn_mfma_f32_16x16x32_bf16(Bt[n][k], At[m][k], acc[ai][bj][m][n], 0, 0, 0); __builtin_amdgcn_s_setprio(0); } while (0)
; #define PG8_WAIT_V(n) asm volatile("s_waitcnt vmcnt(" #n ")" ::: "memory")
; #define PG8_WAIT_L(n) asm volatile("s_waitcnt lgkmcnt(" #n ")" ::: "memory")
; #define PG8_BAR __builtin_amdgcn_s_barrier()
; #define PG8_SCHED __builtin_amdgcn_sched_barrier(0)
; template <class Epi, class Sched, bool ALIGN_EPI = false, bool SP2 = false>
; __device__ __forceinline__ void gemm_phase(PG8_LAS unsigned char* lds, const Gemm g, const Sched& S, const Epi& E) {
;     ...
;             PG8_WAIT_V(8); PG8_WAIT_L(0); PG8_BAR; PG8_MMA(1, 0, At, B0); PG8_MMA(1, 1, At, B1); PG8_BAR; PG8_SCHED;
;             PG8_LDB(B0, 1, 0); PG8_LDB(B1, 1, 1); PG8_SCHED; PG8_LDA(At, 1, 0); PG8_STAGE(PG8_SA(0, 1), a2 + hstep, voffA);
;             PG8_WAIT_V(8); PG8_WAIT_L(0); PG8_BAR; PG8_MMA(0, 0, At, B0); PG8_MMA(0, 1, At, B1); PG8_BAR; PG8_SCHED;
	s_setprio 1
	s_waitcnt lgkmcnt(0)
	v_mfma_f32_16x16x32_bf16 v[92:95], v[128:131], v[178:181], v[92:95]
	v_mfma_f32_16x16x32_bf16 v[88:91], v[154:157], v[178:181], v[88:91]
	v_mfma_f32_16x16x32_bf16 v[84:87], v[128:131], v[186:189], v[84:87]
	v_mfma_f32_16x16x32_bf16 v[80:83], v[154:157], v[186:189], v[80:83]
	v_mfma_f32_16x16x32_bf16 v[76:79], v[128:131], v[194:197], v[76:79]
	v_mfma_f32_16x16x32_bf16 v[72:75], v[154:157], v[194:197], v[72:75]
	v_mfma_f32_16x16x32_bf16 v[68:71], v[128:131], v[210:213], v[68:71]
	v_mfma_f32_16x16x32_bf16 v[64:67], v[154:157], v[210:213], v[64:67]
	v_mfma_f32_16x16x32_bf16 v[92:95], v[132:135], v[182:185], v[92:95]
	v_mfma_f32_16x16x32_bf16 v[88:91], v[158:161], v[182:185], v[88:91]
	v_mfma_f32_16x16x32_bf16 v[84:87], v[132:135], v[190:193], v[84:87]
	v_mfma_f32_16x16x32_bf16 v[80:83], v[158:161], v[190:193], v[80:83]
	v_mfma_f32_16x16x32_bf16 v[76:79], v[132:135], v[198:201], v[76:79]
	v_mfma_f32_16x16x32_bf16 v[72:75], v[158:161], v[198:201], v[72:75]
	v_mfma_f32_16x16x32_bf16 v[68:71], v[132:135], v[214:217], v[68:71]
	v_mfma_f32_16x16x32_bf16 v[64:67], v[158:161], v[214:217], v[64:67]
	s_setprio 0
	s_setprio 1
	v_mfma_f32_16x16x32_bf16 v[28:31], v[162:165], v[178:181], v[28:31]
	v_mfma_f32_16x16x32_bf16 v[24:27], v[170:173], v[178:181], v[24:27]
	v_mfma_f32_16x16x32_bf16 v[20:23], v[162:165], v[186:189], v[20:23]
	v_mfma_f32_16x16x32_bf16 v[16:19], v[170:173], v[186:189], v[16:19]
	v_mfma_f32_16x16x32_bf16 v[12:15], v[162:165], v[194:197], v[12:15]
	v_mfma_f32_16x16x32_bf16 v[8:11], v[170:173], v[194:197], v[8:11]
	v_mfma_f32_16x16x32_bf16 v[4:7], v[162:165], v[210:213], v[4:7]
	v_mfma_f32_16x16x32_bf16 v[0:3], v[170:173], v[210:213], v[0:3]
	v_mfma_f32_16x16x32_bf16 v[28:31], v[166:169], v[182:185], v[28:31]
	v_mfma_f32_16x16x32_bf16 v[24:27], v[174:177], v[182:185], v[24:27]
	v_mfma_f32_16x16x32_bf16 v[20:23], v[166:169], v[190:193], v[20:23]
	v_mfma_f32_16x16x32_bf16 v[16:19], v[174:177], v[190:193], v[16:19]
	s_setprio 2
	s_barrier
	v_mfma_f32_16x16x32_bf16 v[12:15], v[166:169], v[198:201], v[12:15]
	v_mfma_f32_16x16x32_bf16 v[8:11], v[174:177], v[198:201], v[8:11]
	v_mfma_f32_16x16x32_bf16 v[4:7], v[166:169], v[214:217], v[4:7]
	v_mfma_f32_16x16x32_bf16 v[0:3], v[174:177], v[214:217], v[0:3]
	s_setprio 0
	s_add_i32 s78, 0, 0x18000
	s_add_i32 s79, 0, 0x1c000
	v_add_u32_e32 v158, s78, v203
	v_add_u32_e32 v174, s79, v203
	ds_read_b128 v[128:131], v158
	ds_read_b128 v[132:135], v158 offset:1024
	ds_read_b128 v[154:157], v158 offset:2048
	ds_read_b128 v[158:161], v158 offset:3072
	ds_read_b128 v[162:165], v174
	ds_read_b128 v[166:169], v174 offset:1024
	ds_read_b128 v[170:173], v174 offset:2048
	ds_read_b128 v[174:177], v174 offset:3072
	s_add_u32 s56, s56, 0x80000
	s_addc_u32 s57, s57, 0
	s_mov_b32 m0, s63
	v_lshl_add_u64 v[226:227], s[56:57], 0, v[136:137]
	ds_read_b128 v[178:181], v207 offset:32768
	ds_read_b128 v[182:185], v207 offset:33792
	ds_read_b128 v[186:189], v207 offset:34816
	ds_read_b128 v[190:193], v207 offset:35840
	ds_read_b128 v[194:197], v207 offset:36864
	ds_read_b128 v[198:201], v207 offset:37888
	ds_read_b128 v[210:213], v207 offset:38912
	ds_read_b128 v[214:217], v207 offset:39936
	global_load_lds_dwordx4 v[226:227], off
	v_lshl_add_u64 v[226:227], s[56:57], 0, v[140:141]
	s_mov_b32 m0, s64
	s_nop 0
	global_load_lds_dwordx4 v[226:227], off
	s_waitcnt vmcnt(8)
	s_waitcnt lgkmcnt(0)
	s_barrier
	s_setprio 1
	s_waitcnt lgkmcnt(0)
	v_mfma_f32_16x16x32_bf16 v[124:127], v[128:131], v[178:181], v[124:127]
	v_mfma_f32_16x16x32_bf16 v[120:123], v[154:157], v[178:181], v[120:123]
	v_mfma_f32_16x16x32_bf16 v[116:119], v[128:131], v[186:189], v[116:119]
	v_mfma_f32_16x16x32_bf16 v[112:115], v[154:157], v[186:189], v[112:115]
	v_mfma_f32_16x16x32_bf16 v[108:111], v[128:131], v[194:197], v[108:111]
	v_mfma_f32_16x16x32_bf16 v[104:107], v[154:157], v[194:197], v[104:107]
	v_mfma_f32_16x16x32_bf16 v[100:103], v[128:131], v[210:213], v[100:103]
	v_mfma_f32_16x16x32_bf16 v[96:99], v[154:157], v[210:213], v[96:99]
	v_mfma_f32_16x16x32_bf16 v[124:127], v[132:135], v[182:185], v[124:127]
	v_mfma_f32_16x16x32_bf16 v[120:123], v[158:161], v[182:185], v[120:123]
	v_mfma_f32_16x16x32_bf16 v[116:119], v[132:135], v[190:193], v[116:119]
	v_mfma_f32_16x16x32_bf16 v[112:115], v[158:161], v[190:193], v[112:115]
	v_mfma_f32_16x16x32_bf16 v[108:111], v[132:135], v[198:201], v[108:111]
	v_mfma_f32_16x16x32_bf16 v[104:107], v[158:161], v[198:201], v[104:107]
	v_mfma_f32_16x16x32_bf16 v[100:103], v[132:135], v[214:217], v[100:103]
	v_mfma_f32_16x16x32_bf16 v[96:99], v[158:161], v[214:217], v[96:99]
	s_setprio 0
	s_setprio 1
	v_mfma_f32_16x16x32_bf16 v[60:63], v[162:165], v[178:181], v[60:63]
	v_mfma_f32_16x16x32_bf16 v[56:59], v[170:173], v[178:181], v[56:59]
	v_mfma_f32_16x16x32_bf16 v[52:55], v[162:165], v[186:189], v[52:55]
	v_mfma_f32_16x16x32_bf16 v[48:51], v[170:173], v[186:189], v[48:51]
	v_mfma_f32_16x16x32_bf16 v[44:47], v[162:165], v[194:197], v[44:47]
	v_mfma_f32_16x16x32_bf16 v[40:43], v[170:173], v[194:197], v[40:43]
	v_mfma_f32_16x16x32_bf16 v[36:39], v[162:165], v[210:213], v[36:39]
	v_mfma_f32_16x16x32_bf16 v[32:35], v[170:173], v[210:213], v[32:35]
	v_mfma_f32_16x16x32_bf16 v[60:63], v[166:169], v[182:185], v[60:63]
	v_mfma_f32_16x16x32_bf16 v[56:59], v[174:177], v[182:185], v[56:59]
	v_mfma_f32_16x16x32_bf16 v[52:55], v[166:169], v[190:193], v[52:55]
	v_mfma_f32_16x16x32_bf16 v[48:51], v[174:177], v[190:193], v[48:51]
	s_setprio 2
	s_barrier
; #define PG8_STAGE(bufoff, gbase, voff) do { _Pragma("unroll") for (int _i = 0; _i < 2; ++_i) \
;         __builtin_amdgcn_global_load_lds((const unsigned*)((const char*)(gbase) + (voff)[_i]), (PG8_LAS unsigned*)(lds + (bufoff) + ldsw + _i * 8192), 16, 0, 0); } while (0)
; #define PG8_LDA(dst, b, h) do { _Pragma("unroll") for (int m = 0; m < 4; ++m) _Pragma("unroll") for (int k = 0; k < 2; ++k) dst[m][k] = *(const PG8_LAS bf16x8*)(lds + PG8_SA(b, h) + aoff + m * 2048 + k * 1024); } while (0)
; #define PG8_MMA(ai, bj, At, Bt) do { __builtin_amdgcn_s_setprio(1); _Pragma("unroll") for (int m = 0; m < 4; ++m) _Pragma("unroll") for (int n = 0; n < 2; ++n) _Pragma("unroll") for (int k = 0; k < 2; ++k) \
;         acc[ai][bj][m][n] = __builtin_amdgcn_mfma_f32_16x16x32_bf16(Bt[n][k], At[m][k], acc[ai][bj][m][n], 0, 0, 0); __builtin_amdgcn_s_setprio(0); } while (0)
; #define PG8_WAIT_V(n) asm volatile("s_waitcnt vmcnt(" #n ")" ::: "memory")
; #define PG8_WAIT_L(n) asm volatile("s_waitcnt lgkmcnt(" #n ")" ::: "memory")
; #define PG8_BAR __builtin_amdgcn_s_barrier()
; #define PG8_SCHED __builtin_amdgcn_sched_barrier(0)
; template <class Epi, class Sched, bool ALIGN_EPI = false, bool SP2 = false>
; __device__ __forceinline__ void gemm_phase(PG8_LAS unsigned char* lds, const Gemm g, const Sched& S, const Epi& E) {
;     ...
;             PG8_WAIT_V(8); PG8_WAIT_L(0); PG8_BAR; PG8_MMA(0, 0, At, B0); PG8_MMA(0, 1, At, B1); PG8_BAR; PG8_SCHED;
;             PG8_LDA(At, 1, 1); PG8_STAGE(PG8_SB(1, 0), b3, voffB); PG8_STAGE(PG8_SB(1, 1), b3 + hstep, voffB); PG8_STAGE(PG8_SA(1, 0), a3, voffA);
;             PG8_WAIT_V(8); PG8_WAIT_L(0); PG8_BAR; PG8_MMA(1, 0, At, B0); PG8_MMA(1, 1, At, B1); PG8_BAR; PG8_SCHED;
	v_mfma_f32_16x16x32_bf16 v[44:47], v[166:169], v[198:201], v[44:47]
	v_mfma_f32_16x16x32_bf16 v[40:43], v[174:177], v[198:201], v[40:43]
	v_mfma_f32_16x16x32_bf16 v[36:39], v[166:169], v[214:217], v[36:39]
	v_mfma_f32_16x16x32_bf16 v[32:35], v[174:177], v[214:217], v[32:35]
	s_setprio 0
	s_add_i32 s56, s78, s60
	v_lshl_add_u64 v[218:219], v[218:219], 0, s[12:13]
	s_mov_b32 m0, s56
	ds_read_b128 v[178:181], v207 offset:49152
	ds_read_b128 v[182:185], v207 offset:50176
	ds_read_b128 v[186:189], v207 offset:51200
	ds_read_b128 v[190:193], v207 offset:52224
	ds_read_b128 v[194:197], v207 offset:53248
	ds_read_b128 v[198:201], v207 offset:54272
	ds_read_b128 v[210:213], v207 offset:55296
	ds_read_b128 v[214:217], v207 offset:56320
	global_load_lds_dwordx4 v[218:219], off
	s_add_i32 m0, s56, 0x2000
	s_add_u32 s54, s54, 0x80080
	v_lshl_add_u64 v[218:219], v[220:221], 0, s[12:13]
	s_addc_u32 s55, s55, 0
	s_add_i32 s56, s79, s60
	global_load_lds_dwordx4 v[218:219], off
	v_lshl_add_u64 v[218:219], s[54:55], 0, v[138:139]
	s_mov_b32 m0, s56
	s_nop 0
	global_load_lds_dwordx4 v[218:219], off
	v_lshl_add_u64 v[218:219], s[54:55], 0, v[142:143]
	s_add_i32 m0, s56, 0x2000
	s_nop 0
	global_load_lds_dwordx4 v[218:219], off
	v_lshl_add_u64 v[218:219], v[222:223], 0, s[12:13]
	s_mov_b32 m0, s70
	s_nop 0
	global_load_lds_dwordx4 v[218:219], off
	v_lshl_add_u64 v[218:219], v[224:225], 0, s[12:13]
	s_mov_b32 m0, s71
	s_nop 0
	global_load_lds_dwordx4 v[218:219], off
	s_waitcnt vmcnt(8)
	s_waitcnt lgkmcnt(0)
	s_barrier
	s_setprio 1
	s_waitcnt lgkmcnt(0)
	v_mfma_f32_16x16x32_bf16 v[92:95], v[128:131], v[178:181], v[92:95]
	v_mfma_f32_16x16x32_bf16 v[88:91], v[154:157], v[178:181], v[88:91]
	v_mfma_f32_16x16x32_bf16 v[84:87], v[128:131], v[186:189], v[84:87]
	v_mfma_f32_16x16x32_bf16 v[80:83], v[154:157], v[186:189], v[80:83]
	v_mfma_f32_16x16x32_bf16 v[76:79], v[128:131], v[194:197], v[76:79]
	v_mfma_f32_16x16x32_bf16 v[72:75], v[154:157], v[194:197], v[72:75]
	v_mfma_f32_16x16x32_bf16 v[68:71], v[128:131], v[210:213], v[68:71]
	v_mfma_f32_16x16x32_bf16 v[64:67], v[154:157], v[210:213], v[64:67]
	v_mfma_f32_16x16x32_bf16 v[92:95], v[132:135], v[182:185], v[92:95]
	v_mfma_f32_16x16x32_bf16 v[88:91], v[158:161], v[182:185], v[88:91]
	v_mfma_f32_16x16x32_bf16 v[84:87], v[132:135], v[190:193], v[84:87]
	v_mfma_f32_16x16x32_bf16 v[80:83], v[158:161], v[190:193], v[80:83]
	v_mfma_f32_16x16x32_bf16 v[76:79], v[132:135], v[198:201], v[76:79]
	v_mfma_f32_16x16x32_bf16 v[72:75], v[158:161], v[198:201], v[72:75]
	v_mfma_f32_16x16x32_bf16 v[68:71], v[132:135], v[214:217], v[68:71]
	v_mfma_f32_16x16x32_bf16 v[64:67], v[158:161], v[214:217], v[64:67]
	s_setprio 0
	s_setprio 1
	v_mfma_f32_16x16x32_bf16 v[28:31], v[162:165], v[178:181], v[28:31]
	v_mfma_f32_16x16x32_bf16 v[24:27], v[170:173], v[178:181], v[24:27]
	v_mfma_f32_16x16x32_bf16 v[20:23], v[162:165], v[186:189], v[20:23]
	v_mfma_f32_16x16x32_bf16 v[16:19], v[170:173], v[186:189], v[16:19]
	v_mfma_f32_16x16x32_bf16 v[12:15], v[162:165], v[194:197], v[12:15]
	v_mfma_f32_16x16x32_bf16 v[8:11], v[170:173], v[194:197], v[8:11]
	v_mfma_f32_16x16x32_bf16 v[4:7], v[162:165], v[210:213], v[4:7]
	v_mfma_f32_16x16x32_bf16 v[0:3], v[170:173], v[210:213], v[0:3]
	v_mfma_f32_16x16x32_bf16 v[28:31], v[166:169], v[182:185], v[28:31]
	v_mfma_f32_16x16x32_bf16 v[24:27], v[174:177], v[182:185], v[24:27]
	v_mfma_f32_16x16x32_bf16 v[20:23], v[166:169], v[190:193], v[20:23]
	v_mfma_f32_16x16x32_bf16 v[16:19], v[174:177], v[190:193], v[16:19]
	s_setprio 2
	s_barrier
	v_mfma_f32_16x16x32_bf16 v[12:15], v[166:169], v[198:201], v[12:15]
	v_mfma_f32_16x16x32_bf16 v[8:11], v[174:177], v[198:201], v[8:11]
	v_mfma_f32_16x16x32_bf16 v[4:7], v[166:169], v[214:217], v[4:7]
	v_mfma_f32_16x16x32_bf16 v[0:3], v[174:177], v[214:217], v[0:3]
	s_setprio 0
	s_add_i32 s77, s77, 2
	s_add_u32 s52, s52, 0x100
	s_addc_u32 s53, s53, 0
	s_add_u32 s75, s75, 0x100
	s_addc_u32 s76, s76, 0
	s_cmp_gt_u32 s77, 29
	s_cbranch_scc0 .LBB0_1051
	s_and_b64 vcc, exec, s[14:15]
	s_cbranch_vccz .LBB0_1054
	s_barrier

; #define PG8_STAGE(bufoff, gbase, voff) do { _Pragma("unroll") for (int _i = 0; _i < 2; ++_i) \
;         __builtin_amdgcn_global_load_lds((const unsigned*)((const char*)(gbase) + (voff)[_i]), (PG8_LAS unsigned*)(lds + (bufoff) + ldsw + _i * 8192), 16, 0, 0); } while (0)
; #define PG8_LDA(dst, b, h) do { _Pragma("unroll") for (int m = 0; m < 4; ++m) _Pragma("unroll") for (int k = 0; k < 2; ++k) dst[m][k] = *(const PG8_LAS bf16x8*)(lds + PG8_SA(b, h) + aoff + m * 2048 + k * 1024); } while (0)
; #define PG8_LDB(dst, b, h) do { _Pragma("unroll") for (int n = 0; n < 2; ++n) _Pragma("unroll") for (int k = 0; k < 2; ++k) dst[n][k] = *(const PG8_LAS bf16x8*)(lds + PG8_SB(b, h) + boff + n * 2048 + k * 1024); } while (0)
; #define PG8_MMA(ai, bj, At, Bt) do { __builtin_amdgcn_s_setprio(1); _Pragma("unroll") for (int m = 0; m < 4; ++m) _Pragma("unroll") for (int n = 0; n < 2; ++n) _Pragma("unroll") for (int k = 0; k < 2; ++k) \
;         acc[ai][bj][m][n] = __builtin_amdgcn_mfma_f32_16x16x32_bf16(Bt[n][k], At[m][k], acc[ai][bj][m][n], 0, 0, 0); __builtin_amdgcn_s_setprio(0); } while (0)
; #define PG8_WAIT_V(n) asm volatile("s_waitcnt vmcnt(" #n ")" ::: "memory")
; #define PG8_WAIT_L(n) asm volatile("s_waitcnt lgkmcnt(" #n ")" ::: "memory")
; #define PG8_BAR __builtin_amdgcn_s_barrier()
; template <class Epi, class Sched, bool ALIGN_EPI = false, bool SP2 = false>
; __device__ __forceinline__ void gemm_phase(PG8_LAS unsigned char* lds, const Gemm g, const Sched& S, const Epi& E) {
;     ...
;             const bool last = (t == nt - 2);
;             const char* a1 = cA + (size_t)(t + 1) * kstep;
;             const char* a2 = last ? nA : cA + (size_t)(t + 2) * kstep; const char* b2 = last ? nB : cB + (size_t)(t + 2) * kstep;
;             const char* a3 = a2 + kstep; const char* b3 = b2 + kstep;
;             if constexpr (SP2) {
;             PG8_LDB(B0, 0, 0); PG8_LDB(B1, 0, 1); PG8_SCHED; PG8_LDA(At, 0, 0); PG8_STAGE(PG8_SA(1, 1), a1 + hstep, voffA);
;             PG8_WAIT_V(8); PG8_WAIT_L(0); PG8_BAR; PG8_MMA(0, 0, At, B0); PG8_MMA(0, 1, At, B1); PG8_BAR; PG8_SCHED;
;             PG8_LDA(At, 0, 1); PG8_STAGE(PG8_SB(0, 0), b2, voffB); PG8_STAGE(PG8_SB(0, 1), b2 + hstep, voffB); PG8_STAGE(PG8_SA(0, 0), a2, voffA);
;             PG8_WAIT_V(8); PG8_WAIT_L(0); PG8_BAR; PG8_MMA(1, 0, At, B0); PG8_MMA(1, 1, At, B1); PG8_BAR; PG8_SCHED;
.LBB0_1142:
	ds_read_b128 v[80:83], v171
	ds_read_b128 v[84:87], v171 offset:1024
	ds_read_b128 v[88:91], v171 offset:2048
	ds_read_b128 v[92:95], v171 offset:3072
	ds_read_b128 v[164:167], v172
	ds_read_b128 v[176:179], v172 offset:1024
	ds_read_b128 v[180:183], v172 offset:2048
	ds_read_b128 v[184:187], v172 offset:3072
	s_add_u32 s44, s42, 0xfff80080
	s_addc_u32 s45, s43, -1
	s_cmp_eq_u32 s64, 28
	s_cselect_b32 s47, s15, s45
	s_cselect_b32 s46, s60, s44
	s_cselect_b32 s45, s13, s63
	s_cselect_b32 s44, s61, s62
	v_lshl_add_u64 v[220:221], s[42:43], 0, v[156:157]
	s_add_i32 m0, s41, 0xc000
	ds_read_b128 v[188:191], v173
	ds_read_b128 v[192:195], v173 offset:1024
	ds_read_b128 v[196:199], v173 offset:2048
	ds_read_b128 v[200:203], v173 offset:3072
	ds_read_b128 v[204:207], v173 offset:4096
	ds_read_b128 v[208:211], v173 offset:5120
	ds_read_b128 v[212:215], v173 offset:6144
	ds_read_b128 v[216:219], v173 offset:7168
	global_load_lds_dwordx4 v[220:221], off
	v_lshl_add_u64 v[220:221], s[42:43], 0, v[158:159]
	s_add_i32 m0, s41, 0xe000
	s_nop 0
	global_load_lds_dwordx4 v[220:221], off
	s_waitcnt vmcnt(8)
	s_waitcnt lgkmcnt(0)
	s_barrier
	s_setprio 1
	s_waitcnt lgkmcnt(0)
	v_mfma_f32_16x16x32_bf16 v[140:143], v[80:83], v[188:191], v[140:143]
	v_mfma_f32_16x16x32_bf16 v[136:139], v[88:91], v[188:191], v[136:139]
	v_mfma_f32_16x16x32_bf16 v[124:127], v[80:83], v[196:199], v[124:127]
	v_mfma_f32_16x16x32_bf16 v[120:123], v[88:91], v[196:199], v[120:123]
	v_mfma_f32_16x16x32_bf16 v[108:111], v[80:83], v[204:207], v[108:111]
	v_mfma_f32_16x16x32_bf16 v[104:107], v[88:91], v[204:207], v[104:107]
	v_mfma_f32_16x16x32_bf16 v[76:79], v[80:83], v[212:215], v[76:79]
	v_mfma_f32_16x16x32_bf16 v[72:75], v[88:91], v[212:215], v[72:75]
	v_mfma_f32_16x16x32_bf16 v[140:143], v[84:87], v[192:195], v[140:143]
	v_mfma_f32_16x16x32_bf16 v[136:139], v[92:95], v[192:195], v[136:139]
	v_mfma_f32_16x16x32_bf16 v[124:127], v[84:87], v[200:203], v[124:127]
	v_mfma_f32_16x16x32_bf16 v[120:123], v[92:95], v[200:203], v[120:123]
	v_mfma_f32_16x16x32_bf16 v[108:111], v[84:87], v[208:211], v[108:111]
	v_mfma_f32_16x16x32_bf16 v[104:107], v[92:95], v[208:211], v[104:107]
	v_mfma_f32_16x16x32_bf16 v[76:79], v[84:87], v[216:219], v[76:79]
	v_mfma_f32_16x16x32_bf16 v[72:75], v[92:95], v[216:219], v[72:75]
	s_setprio 0
	s_setprio 1
	v_mfma_f32_16x16x32_bf16 v[132:135], v[164:167], v[188:191], v[132:135]
	v_mfma_f32_16x16x32_bf16 v[128:131], v[180:183], v[188:191], v[128:131]
	v_mfma_f32_16x16x32_bf16 v[116:119], v[164:167], v[196:199], v[116:119]
	v_mfma_f32_16x16x32_bf16 v[112:115], v[180:183], v[196:199], v[112:115]
	v_mfma_f32_16x16x32_bf16 v[100:103], v[164:167], v[204:207], v[100:103]
	v_mfma_f32_16x16x32_bf16 v[96:99], v[180:183], v[204:207], v[96:99]
	v_mfma_f32_16x16x32_bf16 v[68:71], v[164:167], v[212:215], v[68:71]
	v_mfma_f32_16x16x32_bf16 v[64:67], v[180:183], v[212:215], v[64:67]
	v_mfma_f32_16x16x32_bf16 v[132:135], v[176:179], v[192:195], v[132:135]
	v_mfma_f32_16x16x32_bf16 v[128:131], v[184:187], v[192:195], v[128:131]
	v_mfma_f32_16x16x32_bf16 v[116:119], v[176:179], v[200:203], v[116:119]
	v_mfma_f32_16x16x32_bf16 v[112:115], v[184:187], v[200:203], v[112:115]
	s_setprio 2
	s_barrier
	v_mfma_f32_16x16x32_bf16 v[100:103], v[176:179], v[208:211], v[100:103]
	v_mfma_f32_16x16x32_bf16 v[96:99], v[184:187], v[208:211], v[96:99]
	v_mfma_f32_16x16x32_bf16 v[68:71], v[176:179], v[216:219], v[68:71]
	v_mfma_f32_16x16x32_bf16 v[64:67], v[184:187], v[216:219], v[64:67]
	s_setprio 0
	s_add_i32 s65, s56, s33
	v_lshl_add_u64 v[220:221], s[44:45], 0, v[148:149]
	s_mov_b32 m0, s65
	ds_read_b128 v[188:191], v173 offset:16384
	ds_read_b128 v[192:195], v173 offset:17408
	ds_read_b128 v[196:199], v173 offset:18432
	ds_read_b128 v[200:203], v173 offset:19456
	ds_read_b128 v[204:207], v173 offset:20480
	ds_read_b128 v[208:211], v173 offset:21504
	ds_read_b128 v[212:215], v173 offset:22528
	ds_read_b128 v[216:219], v173 offset:23552
	global_load_lds_dwordx4 v[220:221], off
	s_add_i32 m0, s65, 0x2000
	s_add_u32 s66, s44, 0x80000
	v_lshl_add_u64 v[222:223], s[44:45], 0, v[152:153]
	s_addc_u32 s67, s45, 0
	s_add_i32 s65, s57, s33
	global_load_lds_dwordx4 v[222:223], off
	v_lshl_add_u64 v[224:225], s[66:67], 0, v[148:149]
	s_mov_b32 m0, s65
	v_lshl_add_u64 v[226:227], s[46:47], 0, v[150:151]
	global_load_lds_dwordx4 v[224:225], off
	v_lshl_add_u64 v[224:225], s[66:67], 0, v[152:153]
	s_add_i32 m0, s65, 0x2000
	s_nop 0
	global_load_lds_dwordx4 v[224:225], off
	v_lshl_add_u64 v[224:225], s[46:47], 0, v[144:145]
	s_mov_b32 m0, s41
	s_nop 0
	global_load_lds_dwordx4 v[224:225], off
	s_mov_b32 m0, s48
	s_nop 0
	global_load_lds_dwordx4 v[226:227], off
	s_waitcnt vmcnt(8)
	s_waitcnt lgkmcnt(0)
	s_barrier
; #define PG8_STAGE(bufoff, gbase, voff) do { _Pragma("unroll") for (int _i = 0; _i < 2; ++_i) \
;         __builtin_amdgcn_global_load_lds((const unsigned*)((const char*)(gbase) + (voff)[_i]), (PG8_LAS unsigned*)(lds + (bufoff) + ldsw + _i * 8192), 16, 0, 0); } while (0)
; #define PG8_LDA(dst, b, h) do { _Pragma("unroll") for (int m = 0; m < 4; ++m) _Pragma("unroll") for (int k = 0; k < 2; ++k) dst[m][k] = *(const PG8_LAS bf16x8*)(lds + PG8_SA(b, h) + aoff + m * 2048 + k * 1024); } while (0)
; #define PG8_LDB(dst, b, h) do { _Pragma("unroll") for (int n = 0; n < 2; ++n) _Pragma("unroll") for (int k = 0; k < 2; ++k) dst[n][k] = *(const PG8_LAS bf16x8*)(lds + PG8_SB(b, h) + boff + n * 2048 + k * 1024); } while (0)
; #define PG8_MMA(ai, bj, At, Bt) do { __builtin_amdgcn_s_setprio(1); _Pragma("unroll") for (int m = 0; m < 4; ++m) _Pragma("unroll") for (int n = 0; n < 2; ++n) _Pragma("unroll") for (int k = 0; k < 2; ++k) \
;         acc[ai][bj][m][n] = __builtin_amdgcn_mfma_f32_16x16x32_bf16(Bt[n][k], At[m][k], acc[ai][bj][m][n], 0, 0, 0); __builtin_amdgcn_s_setprio(0); } while (0)
; #define PG8_WAIT_V(n) asm volatile("s_waitcnt vmcnt(" #n ")" ::: "memory")
; #define PG8_WAIT_L(n) asm volatile("s_waitcnt lgkmcnt(" #n ")" ::: "memory")
; #define PG8_BAR __builtin_amdgcn_s_barrier()
; #define PG8_SCHED __builtin_amdgcn_sched_barrier(0)
; template <class Epi, class Sched, bool ALIGN_EPI = false, bool SP2 = false>
; __device__ __forceinline__ void gemm_phase(PG8_LAS unsigned char* lds, const Gemm g, const Sched& S, const Epi& E) {
;     ...
;             PG8_WAIT_V(8); PG8_WAIT_L(0); PG8_BAR; PG8_MMA(1, 0, At, B0); PG8_MMA(1, 1, At, B1); PG8_BAR; PG8_SCHED;
;             PG8_LDB(B0, 1, 0); PG8_LDB(B1, 1, 1); PG8_SCHED; PG8_LDA(At, 1, 0); PG8_STAGE(PG8_SA(0, 1), a2 + hstep, voffA);
;             PG8_WAIT_V(8); PG8_WAIT_L(0); PG8_BAR; PG8_MMA(0, 0, At, B0); PG8_MMA(0, 1, At, B1); PG8_BAR; PG8_SCHED;
	s_setprio 1
	s_waitcnt lgkmcnt(0)
	v_mfma_f32_16x16x32_bf16 v[60:63], v[80:83], v[188:191], v[60:63]
	v_mfma_f32_16x16x32_bf16 v[56:59], v[88:91], v[188:191], v[56:59]
	v_mfma_f32_16x16x32_bf16 v[44:47], v[80:83], v[196:199], v[44:47]
	v_mfma_f32_16x16x32_bf16 v[40:43], v[88:91], v[196:199], v[40:43]
	v_mfma_f32_16x16x32_bf16 v[28:31], v[80:83], v[204:207], v[28:31]
	v_mfma_f32_16x16x32_bf16 v[24:27], v[88:91], v[204:207], v[24:27]
	v_mfma_f32_16x16x32_bf16 v[12:15], v[80:83], v[212:215], v[12:15]
	v_mfma_f32_16x16x32_bf16 v[8:11], v[88:91], v[212:215], v[8:11]
	v_mfma_f32_16x16x32_bf16 v[60:63], v[84:87], v[192:195], v[60:63]
	v_mfma_f32_16x16x32_bf16 v[56:59], v[92:95], v[192:195], v[56:59]
	v_mfma_f32_16x16x32_bf16 v[44:47], v[84:87], v[200:203], v[44:47]
	v_mfma_f32_16x16x32_bf16 v[40:43], v[92:95], v[200:203], v[40:43]
	v_mfma_f32_16x16x32_bf16 v[28:31], v[84:87], v[208:211], v[28:31]
	v_mfma_f32_16x16x32_bf16 v[24:27], v[92:95], v[208:211], v[24:27]
	v_mfma_f32_16x16x32_bf16 v[12:15], v[84:87], v[216:219], v[12:15]
	v_mfma_f32_16x16x32_bf16 v[8:11], v[92:95], v[216:219], v[8:11]
	s_setprio 0
	s_setprio 1
	v_mfma_f32_16x16x32_bf16 v[52:55], v[164:167], v[188:191], v[52:55]
	v_mfma_f32_16x16x32_bf16 v[48:51], v[180:183], v[188:191], v[48:51]
	v_mfma_f32_16x16x32_bf16 v[36:39], v[164:167], v[196:199], v[36:39]
	v_mfma_f32_16x16x32_bf16 v[32:35], v[180:183], v[196:199], v[32:35]
	v_mfma_f32_16x16x32_bf16 v[20:23], v[164:167], v[204:207], v[20:23]
	v_mfma_f32_16x16x32_bf16 v[16:19], v[180:183], v[204:207], v[16:19]
	v_mfma_f32_16x16x32_bf16 v[4:7], v[164:167], v[212:215], v[4:7]
	v_mfma_f32_16x16x32_bf16 v[0:3], v[180:183], v[212:215], v[0:3]
	v_mfma_f32_16x16x32_bf16 v[52:55], v[176:179], v[192:195], v[52:55]
	v_mfma_f32_16x16x32_bf16 v[48:51], v[184:187], v[192:195], v[48:51]
	v_mfma_f32_16x16x32_bf16 v[36:39], v[176:179], v[200:203], v[36:39]
	v_mfma_f32_16x16x32_bf16 v[32:35], v[184:187], v[200:203], v[32:35]
	s_setprio 2
	s_barrier
	v_mfma_f32_16x16x32_bf16 v[20:23], v[176:179], v[208:211], v[20:23]
	v_mfma_f32_16x16x32_bf16 v[16:19], v[184:187], v[208:211], v[16:19]
	v_mfma_f32_16x16x32_bf16 v[4:7], v[176:179], v[216:219], v[4:7]
	v_mfma_f32_16x16x32_bf16 v[0:3], v[184:187], v[216:219], v[0:3]
	s_setprio 0
	s_add_i32 s65, 0, 0x18000
	s_add_i32 s66, 0, 0x1c000
	v_add_u32_e32 v92, s65, v169
	v_add_u32_e32 v184, s66, v169
	ds_read_b128 v[80:83], v92
	ds_read_b128 v[84:87], v92 offset:1024
	ds_read_b128 v[88:91], v92 offset:2048
	ds_read_b128 v[92:95], v92 offset:3072
	ds_read_b128 v[164:167], v184
	ds_read_b128 v[176:179], v184 offset:1024
	ds_read_b128 v[180:183], v184 offset:2048
	ds_read_b128 v[184:187], v184 offset:3072
	s_add_u32 s46, s46, 0x80000
	s_addc_u32 s47, s47, 0
	s_mov_b32 m0, s49
	v_lshl_add_u64 v[228:229], s[46:47], 0, v[144:145]
	ds_read_b128 v[188:191], v173 offset:32768
	ds_read_b128 v[192:195], v173 offset:33792
	ds_read_b128 v[196:199], v173 offset:34816
	ds_read_b128 v[200:203], v173 offset:35840
	ds_read_b128 v[204:207], v173 offset:36864
	ds_read_b128 v[208:211], v173 offset:37888
	ds_read_b128 v[212:215], v173 offset:38912
	ds_read_b128 v[216:219], v173 offset:39936
	global_load_lds_dwordx4 v[228:229], off
	v_lshl_add_u64 v[228:229], s[46:47], 0, v[150:151]
	s_mov_b32 m0, s50
	s_nop 0
	global_load_lds_dwordx4 v[228:229], off
	s_waitcnt vmcnt(8)
	s_waitcnt lgkmcnt(0)
	s_barrier
	s_setprio 1
	s_waitcnt lgkmcnt(0)
	v_mfma_f32_16x16x32_bf16 v[140:143], v[80:83], v[188:191], v[140:143]
	v_mfma_f32_16x16x32_bf16 v[136:139], v[88:91], v[188:191], v[136:139]
	v_mfma_f32_16x16x32_bf16 v[124:127], v[80:83], v[196:199], v[124:127]
	v_mfma_f32_16x16x32_bf16 v[120:123], v[88:91], v[196:199], v[120:123]
	v_mfma_f32_16x16x32_bf16 v[108:111], v[80:83], v[204:207], v[108:111]
	v_mfma_f32_16x16x32_bf16 v[104:107], v[88:91], v[204:207], v[104:107]
	v_mfma_f32_16x16x32_bf16 v[76:79], v[80:83], v[212:215], v[76:79]
	v_mfma_f32_16x16x32_bf16 v[72:75], v[88:91], v[212:215], v[72:75]
	v_mfma_f32_16x16x32_bf16 v[140:143], v[84:87], v[192:195], v[140:143]
	v_mfma_f32_16x16x32_bf16 v[136:139], v[92:95], v[192:195], v[136:139]
	v_mfma_f32_16x16x32_bf16 v[124:127], v[84:87], v[200:203], v[124:127]
	v_mfma_f32_16x16x32_bf16 v[120:123], v[92:95], v[200:203], v[120:123]
	v_mfma_f32_16x16x32_bf16 v[108:111], v[84:87], v[208:211], v[108:111]
	v_mfma_f32_16x16x32_bf16 v[104:107], v[92:95], v[208:211], v[104:107]
	v_mfma_f32_16x16x32_bf16 v[76:79], v[84:87], v[216:219], v[76:79]
	v_mfma_f32_16x16x32_bf16 v[72:75], v[92:95], v[216:219], v[72:75]
	s_setprio 0
	s_setprio 1
	v_mfma_f32_16x16x32_bf16 v[132:135], v[164:167], v[188:191], v[132:135]
	v_mfma_f32_16x16x32_bf16 v[128:131], v[180:183], v[188:191], v[128:131]
	v_mfma_f32_16x16x32_bf16 v[116:119], v[164:167], v[196:199], v[116:119]
	v_mfma_f32_16x16x32_bf16 v[112:115], v[180:183], v[196:199], v[112:115]
	v_mfma_f32_16x16x32_bf16 v[100:103], v[164:167], v[204:207], v[100:103]
	v_mfma_f32_16x16x32_bf16 v[96:99], v[180:183], v[204:207], v[96:99]
	v_mfma_f32_16x16x32_bf16 v[68:71], v[164:167], v[212:215], v[68:71]
	v_mfma_f32_16x16x32_bf16 v[64:67], v[180:183], v[212:215], v[64:67]
	v_mfma_f32_16x16x32_bf16 v[132:135], v[176:179], v[192:195], v[132:135]
	v_mfma_f32_16x16x32_bf16 v[128:131], v[184:187], v[192:195], v[128:131]
	v_mfma_f32_16x16x32_bf16 v[116:119], v[176:179], v[200:203], v[116:119]
	v_mfma_f32_16x16x32_bf16 v[112:115], v[184:187], v[200:203], v[112:115]
	s_setprio 2
	s_barrier
; #define PG8_STAGE(bufoff, gbase, voff) do { _Pragma("unroll") for (int _i = 0; _i < 2; ++_i) \
;         __builtin_amdgcn_global_load_lds((const unsigned*)((const char*)(gbase) + (voff)[_i]), (PG8_LAS unsigned*)(lds + (bufoff) + ldsw + _i * 8192), 16, 0, 0); } while (0)
; #define PG8_LDA(dst, b, h) do { _Pragma("unroll") for (int m = 0; m < 4; ++m) _Pragma("unroll") for (int k = 0; k < 2; ++k) dst[m][k] = *(const PG8_LAS bf16x8*)(lds + PG8_SA(b, h) + aoff + m * 2048 + k * 1024); } while (0)
; #define PG8_MMA(ai, bj, At, Bt) do { __builtin_amdgcn_s_setprio(1); _Pragma("unroll") for (int m = 0; m < 4; ++m) _Pragma("unroll") for (int n = 0; n < 2; ++n) _Pragma("unroll") for (int k = 0; k < 2; ++k) \
;         acc[ai][bj][m][n] = __builtin_amdgcn_mfma_f32_16x16x32_bf16(Bt[n][k], At[m][k], acc[ai][bj][m][n], 0, 0, 0); __builtin_amdgcn_s_setprio(0); } while (0)
; #define PG8_WAIT_V(n) asm volatile("s_waitcnt vmcnt(" #n ")" ::: "memory")
; #define PG8_WAIT_L(n) asm volatile("s_waitcnt lgkmcnt(" #n ")" ::: "memory")
; #define PG8_BAR __builtin_amdgcn_s_barrier()
; #define PG8_SCHED __builtin_amdgcn_sched_barrier(0)
; template <class Epi, class Sched, bool ALIGN_EPI = false, bool SP2 = false>
; __device__ __forceinline__ void gemm_phase(PG8_LAS unsigned char* lds, const Gemm g, const Sched& S, const Epi& E) {
;     ...
;             PG8_WAIT_V(8); PG8_WAIT_L(0); PG8_BAR; PG8_MMA(0, 0, At, B0); PG8_MMA(0, 1, At, B1); PG8_BAR; PG8_SCHED;
;             PG8_LDA(At, 1, 1); PG8_STAGE(PG8_SB(1, 0), b3, voffB); PG8_STAGE(PG8_SB(1, 1), b3 + hstep, voffB); PG8_STAGE(PG8_SA(1, 0), a3, voffA);
;             PG8_WAIT_V(8); PG8_WAIT_L(0); PG8_BAR; PG8_MMA(1, 0, At, B0); PG8_MMA(1, 1, At, B1); PG8_BAR; PG8_SCHED;
	v_mfma_f32_16x16x32_bf16 v[100:103], v[176:179], v[208:211], v[100:103]
	v_mfma_f32_16x16x32_bf16 v[96:99], v[184:187], v[208:211], v[96:99]
	v_mfma_f32_16x16x32_bf16 v[68:71], v[176:179], v[216:219], v[68:71]
	v_mfma_f32_16x16x32_bf16 v[64:67], v[184:187], v[216:219], v[64:67]
	s_setprio 0
	s_add_i32 s46, s65, s33
	v_lshl_add_u64 v[220:221], v[220:221], 0, s[8:9]
	s_mov_b32 m0, s46
	ds_read_b128 v[188:191], v173 offset:49152
	ds_read_b128 v[192:195], v173 offset:50176
	ds_read_b128 v[196:199], v173 offset:51200
	ds_read_b128 v[200:203], v173 offset:52224
	ds_read_b128 v[204:207], v173 offset:53248
	ds_read_b128 v[208:211], v173 offset:54272
	ds_read_b128 v[212:215], v173 offset:55296
	ds_read_b128 v[216:219], v173 offset:56320
	global_load_lds_dwordx4 v[220:221], off
	s_add_i32 m0, s46, 0x2000
	s_add_u32 s44, s44, 0x80080
	v_lshl_add_u64 v[220:221], v[222:223], 0, s[8:9]
	s_addc_u32 s45, s45, 0
	s_add_i32 s46, s66, s33
	global_load_lds_dwordx4 v[220:221], off
	v_lshl_add_u64 v[220:221], s[44:45], 0, v[148:149]
	s_mov_b32 m0, s46
	s_nop 0
	global_load_lds_dwordx4 v[220:221], off
	v_lshl_add_u64 v[220:221], s[44:45], 0, v[152:153]
	s_add_i32 m0, s46, 0x2000
	s_nop 0
	global_load_lds_dwordx4 v[220:221], off
	v_lshl_add_u64 v[220:221], v[224:225], 0, s[8:9]
	s_mov_b32 m0, s52
	s_nop 0
	global_load_lds_dwordx4 v[220:221], off
	v_lshl_add_u64 v[220:221], v[226:227], 0, s[8:9]
	s_mov_b32 m0, s53
	s_nop 0
	global_load_lds_dwordx4 v[220:221], off
	s_waitcnt vmcnt(8)
	s_waitcnt lgkmcnt(0)
	s_barrier
	s_setprio 1
	s_waitcnt lgkmcnt(0)
	v_mfma_f32_16x16x32_bf16 v[60:63], v[80:83], v[188:191], v[60:63]
	v_mfma_f32_16x16x32_bf16 v[56:59], v[88:91], v[188:191], v[56:59]
	v_mfma_f32_16x16x32_bf16 v[44:47], v[80:83], v[196:199], v[44:47]
	v_mfma_f32_16x16x32_bf16 v[40:43], v[88:91], v[196:199], v[40:43]
	v_mfma_f32_16x16x32_bf16 v[28:31], v[80:83], v[204:207], v[28:31]
	v_mfma_f32_16x16x32_bf16 v[24:27], v[88:91], v[204:207], v[24:27]
	v_mfma_f32_16x16x32_bf16 v[12:15], v[80:83], v[212:215], v[12:15]
	v_mfma_f32_16x16x32_bf16 v[8:11], v[88:91], v[212:215], v[8:11]
	v_mfma_f32_16x16x32_bf16 v[60:63], v[84:87], v[192:195], v[60:63]
	v_mfma_f32_16x16x32_bf16 v[56:59], v[92:95], v[192:195], v[56:59]
	v_mfma_f32_16x16x32_bf16 v[44:47], v[84:87], v[200:203], v[44:47]
	v_mfma_f32_16x16x32_bf16 v[40:43], v[92:95], v[200:203], v[40:43]
	v_mfma_f32_16x16x32_bf16 v[28:31], v[84:87], v[208:211], v[28:31]
	v_mfma_f32_16x16x32_bf16 v[24:27], v[92:95], v[208:211], v[24:27]
	v_mfma_f32_16x16x32_bf16 v[12:15], v[84:87], v[216:219], v[12:15]
	v_mfma_f32_16x16x32_bf16 v[8:11], v[92:95], v[216:219], v[8:11]
	s_setprio 0
	s_setprio 1
	v_mfma_f32_16x16x32_bf16 v[52:55], v[164:167], v[188:191], v[52:55]
	v_mfma_f32_16x16x32_bf16 v[48:51], v[180:183], v[188:191], v[48:51]
	v_mfma_f32_16x16x32_bf16 v[36:39], v[164:167], v[196:199], v[36:39]
	v_mfma_f32_16x16x32_bf16 v[32:35], v[180:183], v[196:199], v[32:35]
	v_mfma_f32_16x16x32_bf16 v[20:23], v[164:167], v[204:207], v[20:23]
	v_mfma_f32_16x16x32_bf16 v[16:19], v[180:183], v[204:207], v[16:19]
	v_mfma_f32_16x16x32_bf16 v[4:7], v[164:167], v[212:215], v[4:7]
	v_mfma_f32_16x16x32_bf16 v[0:3], v[180:183], v[212:215], v[0:3]
	v_mfma_f32_16x16x32_bf16 v[52:55], v[176:179], v[192:195], v[52:55]
	v_mfma_f32_16x16x32_bf16 v[48:51], v[184:187], v[192:195], v[48:51]
	v_mfma_f32_16x16x32_bf16 v[36:39], v[176:179], v[200:203], v[36:39]
	v_mfma_f32_16x16x32_bf16 v[32:35], v[184:187], v[200:203], v[32:35]
	s_setprio 2
	s_barrier
	v_mfma_f32_16x16x32_bf16 v[20:23], v[176:179], v[208:211], v[20:23]
	v_mfma_f32_16x16x32_bf16 v[16:19], v[184:187], v[208:211], v[16:19]
	v_mfma_f32_16x16x32_bf16 v[4:7], v[176:179], v[216:219], v[4:7]
	v_mfma_f32_16x16x32_bf16 v[0:3], v[184:187], v[216:219], v[0:3]
	s_setprio 0
	s_add_i32 s64, s64, 2
	s_add_u32 s42, s42, 0x100
	s_addc_u32 s43, s43, 0
	s_add_u32 s62, s62, 0x100
	s_addc_u32 s63, s63, 0
	s_cmp_gt_u32 s64, 29
	s_cbranch_scc0 .LBB0_1142
	s_and_b64 vcc, exec, s[10:11]
	s_cbranch_vccz .LBB0_1145
	s_barrier

; #define PG8_STAGE(bufoff, gbase, voff) do { _Pragma("unroll") for (int _i = 0; _i < 2; ++_i) \
;         __builtin_amdgcn_global_load_lds((const unsigned*)((const char*)(gbase) + (voff)[_i]), (PG8_LAS unsigned*)(lds + (bufoff) + ldsw + _i * 8192), 16, 0, 0); } while (0)
; #define PG8_LDA(dst, b, h) do { _Pragma("unroll") for (int m = 0; m < 4; ++m) _Pragma("unroll") for (int k = 0; k < 2; ++k) dst[m][k] = *(const PG8_LAS bf16x8*)(lds + PG8_SA(b, h) + aoff + m * 2048 + k * 1024); } while (0)
; #define PG8_LDB(dst, b, h) do { _Pragma("unroll") for (int n = 0; n < 2; ++n) _Pragma("unroll") for (int k = 0; k < 2; ++k) dst[n][k] = *(const PG8_LAS bf16x8*)(lds + PG8_SB(b, h) + boff + n * 2048 + k * 1024); } while (0)
; #define PG8_MMA(ai, bj, At, Bt) do { __builtin_amdgcn_s_setprio(1); _Pragma("unroll") for (int m = 0; m < 4; ++m) _Pragma("unroll") for (int n = 0; n < 2; ++n) _Pragma("unroll") for (int k = 0; k < 2; ++k) \
;         acc[ai][bj][m][n] = __builtin_amdgcn_mfma_f32_16x16x32_bf16(Bt[n][k], At[m][k], acc[ai][bj][m][n], 0, 0, 0); __builtin_amdgcn_s_setprio(0); } while (0)
; #define PG8_WAIT_V(n) asm volatile("s_waitcnt vmcnt(" #n ")" ::: "memory")
; #define PG8_WAIT_L(n) asm volatile("s_waitcnt lgkmcnt(" #n ")" ::: "memory")
; #define PG8_BAR __builtin_amdgcn_s_barrier()
; template <class Epi, class Sched, bool ALIGN_EPI = false, bool SP2 = false>
; __device__ __forceinline__ void gemm_phase(PG8_LAS unsigned char* lds, const Gemm g, const Sched& S, const Epi& E) {
;     ...
;             const bool last = (t == nt - 2);
;             const char* a1 = cA + (size_t)(t + 1) * kstep;
;             const char* a2 = last ? nA : cA + (size_t)(t + 2) * kstep; const char* b2 = last ? nB : cB + (size_t)(t + 2) * kstep;
;             const char* a3 = a2 + kstep; const char* b3 = b2 + kstep;
;             if constexpr (SP2) {
;             PG8_LDB(B0, 0, 0); PG8_LDB(B1, 0, 1); PG8_SCHED; PG8_LDA(At, 0, 0); PG8_STAGE(PG8_SA(1, 1), a1 + hstep, voffA);
;             PG8_WAIT_V(8); PG8_WAIT_L(0); PG8_BAR; PG8_MMA(0, 0, At, B0); PG8_MMA(0, 1, At, B1); PG8_BAR; PG8_SCHED;
;             PG8_LDA(At, 0, 1); PG8_STAGE(PG8_SB(0, 0), b2, voffB); PG8_STAGE(PG8_SB(0, 1), b2 + hstep, voffB); PG8_STAGE(PG8_SA(0, 0), a2, voffA);
;             PG8_WAIT_V(8); PG8_WAIT_L(0); PG8_BAR; PG8_MMA(1, 0, At, B0); PG8_MMA(1, 1, At, B1); PG8_BAR; PG8_SCHED;
.LBB0_1219:
	ds_read_b128 v[128:131], v167
	ds_read_b128 v[132:135], v167 offset:1024
	ds_read_b128 v[154:157], v167 offset:2048
	ds_read_b128 v[158:161], v167 offset:3072
	ds_read_b128 v[170:173], v168
	ds_read_b128 v[174:177], v168 offset:1024
	ds_read_b128 v[178:181], v168 offset:2048
	ds_read_b128 v[182:185], v168 offset:3072
	s_add_u32 s42, s40, 0xffe00080
	s_addc_u32 s43, s41, -1
	s_cmpk_eq_i32 s63, 0x7c
	s_cselect_b32 s45, s15, s43
	s_cselect_b32 s44, s59, s42
	s_cselect_b32 s43, s13, s62
	s_cselect_b32 s42, s60, s61
	v_lshl_add_u64 v[162:163], s[40:41], 0, v[144:145]
	s_add_i32 m0, s39, 0xc000
	ds_read_b128 v[186:189], v169
	ds_read_b128 v[190:193], v169 offset:1024
	ds_read_b128 v[194:197], v169 offset:2048
	ds_read_b128 v[198:201], v169 offset:3072
	ds_read_b128 v[202:205], v169 offset:4096
	ds_read_b128 v[206:209], v169 offset:5120
	ds_read_b128 v[210:213], v169 offset:6144
	ds_read_b128 v[214:217], v169 offset:7168
	global_load_lds_dwordx4 v[162:163], off
	v_lshl_add_u64 v[162:163], s[40:41], 0, v[148:149]
	s_add_i32 m0, s39, 0xe000
	s_nop 0
	global_load_lds_dwordx4 v[162:163], off
	s_waitcnt vmcnt(8)
	s_waitcnt lgkmcnt(0)
	s_barrier
	s_setprio 1
	s_waitcnt lgkmcnt(0)
	v_mfma_f32_16x16x32_bf16 v[124:127], v[128:131], v[186:189], v[124:127]
	v_mfma_f32_16x16x32_bf16 v[120:123], v[154:157], v[186:189], v[120:123]
	v_mfma_f32_16x16x32_bf16 v[116:119], v[128:131], v[194:197], v[116:119]
	v_mfma_f32_16x16x32_bf16 v[112:115], v[154:157], v[194:197], v[112:115]
	v_mfma_f32_16x16x32_bf16 v[108:111], v[128:131], v[202:205], v[108:111]
	v_mfma_f32_16x16x32_bf16 v[104:107], v[154:157], v[202:205], v[104:107]
	v_mfma_f32_16x16x32_bf16 v[100:103], v[128:131], v[210:213], v[100:103]
	v_mfma_f32_16x16x32_bf16 v[96:99], v[154:157], v[210:213], v[96:99]
	v_mfma_f32_16x16x32_bf16 v[124:127], v[132:135], v[190:193], v[124:127]
	v_mfma_f32_16x16x32_bf16 v[120:123], v[158:161], v[190:193], v[120:123]
	v_mfma_f32_16x16x32_bf16 v[116:119], v[132:135], v[198:201], v[116:119]
	v_mfma_f32_16x16x32_bf16 v[112:115], v[158:161], v[198:201], v[112:115]
	v_mfma_f32_16x16x32_bf16 v[108:111], v[132:135], v[206:209], v[108:111]
	v_mfma_f32_16x16x32_bf16 v[104:107], v[158:161], v[206:209], v[104:107]
	v_mfma_f32_16x16x32_bf16 v[100:103], v[132:135], v[214:217], v[100:103]
	v_mfma_f32_16x16x32_bf16 v[96:99], v[158:161], v[214:217], v[96:99]
	s_setprio 0
	s_setprio 1
	v_mfma_f32_16x16x32_bf16 v[68:71], v[170:173], v[186:189], v[68:71]
	v_mfma_f32_16x16x32_bf16 v[60:63], v[178:181], v[186:189], v[60:63]
	v_mfma_f32_16x16x32_bf16 v[52:55], v[170:173], v[194:197], v[52:55]
	v_mfma_f32_16x16x32_bf16 v[48:51], v[178:181], v[194:197], v[48:51]
	v_mfma_f32_16x16x32_bf16 v[44:47], v[170:173], v[202:205], v[44:47]
	v_mfma_f32_16x16x32_bf16 v[40:43], v[178:181], v[202:205], v[40:43]
	v_mfma_f32_16x16x32_bf16 v[36:39], v[170:173], v[210:213], v[36:39]
	v_mfma_f32_16x16x32_bf16 v[32:35], v[178:181], v[210:213], v[32:35]
	v_mfma_f32_16x16x32_bf16 v[68:71], v[174:177], v[190:193], v[68:71]
	v_mfma_f32_16x16x32_bf16 v[60:63], v[182:185], v[190:193], v[60:63]
	v_mfma_f32_16x16x32_bf16 v[52:55], v[174:177], v[198:201], v[52:55]
	v_mfma_f32_16x16x32_bf16 v[48:51], v[182:185], v[198:201], v[48:51]
	s_setprio 2
	s_barrier
	v_mfma_f32_16x16x32_bf16 v[44:47], v[174:177], v[206:209], v[44:47]
	v_mfma_f32_16x16x32_bf16 v[40:43], v[182:185], v[206:209], v[40:43]
	v_mfma_f32_16x16x32_bf16 v[36:39], v[174:177], v[214:217], v[36:39]
	v_mfma_f32_16x16x32_bf16 v[32:35], v[182:185], v[214:217], v[32:35]
	s_setprio 0
	s_add_i32 s64, s56, s33
	v_lshl_add_u64 v[162:163], s[42:43], 0, v[138:139]
	s_mov_b32 m0, s64
	ds_read_b128 v[186:189], v169 offset:16384
	ds_read_b128 v[190:193], v169 offset:17408
	ds_read_b128 v[194:197], v169 offset:18432
	ds_read_b128 v[198:201], v169 offset:19456
	ds_read_b128 v[202:205], v169 offset:20480
	ds_read_b128 v[206:209], v169 offset:21504
	ds_read_b128 v[210:213], v169 offset:22528
	ds_read_b128 v[214:217], v169 offset:23552
	global_load_lds_dwordx4 v[162:163], off
	s_add_i32 m0, s64, 0x2000
	s_add_u32 s64, s42, 0x200000
	v_lshl_add_u64 v[218:219], s[42:43], 0, v[142:143]
	s_addc_u32 s65, s43, 0
	s_add_i32 s66, s57, s33
	global_load_lds_dwordx4 v[218:219], off
	v_lshl_add_u64 v[220:221], s[64:65], 0, v[138:139]
	s_mov_b32 m0, s66
	v_lshl_add_u64 v[222:223], s[44:45], 0, v[140:141]
	global_load_lds_dwordx4 v[220:221], off
	v_lshl_add_u64 v[220:221], s[64:65], 0, v[142:143]
	s_add_i32 m0, s66, 0x2000
	s_nop 0
	global_load_lds_dwordx4 v[220:221], off
	v_lshl_add_u64 v[220:221], s[44:45], 0, v[136:137]
	s_mov_b32 m0, s39
	s_nop 0
	global_load_lds_dwordx4 v[220:221], off
	s_mov_b32 m0, s46
	s_nop 0
	global_load_lds_dwordx4 v[222:223], off
	s_waitcnt vmcnt(8)
	s_waitcnt lgkmcnt(0)
	s_barrier
; #define PG8_STAGE(bufoff, gbase, voff) do { _Pragma("unroll") for (int _i = 0; _i < 2; ++_i) \
;         __builtin_amdgcn_global_load_lds((const unsigned*)((const char*)(gbase) + (voff)[_i]), (PG8_LAS unsigned*)(lds + (bufoff) + ldsw + _i * 8192), 16, 0, 0); } while (0)
; #define PG8_LDA(dst, b, h) do { _Pragma("unroll") for (int m = 0; m < 4; ++m) _Pragma("unroll") for (int k = 0; k < 2; ++k) dst[m][k] = *(const PG8_LAS bf16x8*)(lds + PG8_SA(b, h) + aoff + m * 2048 + k * 1024); } while (0)
; #define PG8_LDB(dst, b, h) do { _Pragma("unroll") for (int n = 0; n < 2; ++n) _Pragma("unroll") for (int k = 0; k < 2; ++k) dst[n][k] = *(const PG8_LAS bf16x8*)(lds + PG8_SB(b, h) + boff + n * 2048 + k * 1024); } while (0)
; #define PG8_MMA(ai, bj, At, Bt) do { __builtin_amdgcn_s_setprio(1); _Pragma("unroll") for (int m = 0; m < 4; ++m) _Pragma("unroll") for (int n = 0; n < 2; ++n) _Pragma("unroll") for (int k = 0; k < 2; ++k) \
;         acc[ai][bj][m][n] = __builtin_amdgcn_mfma_f32_16x16x32_bf16(Bt[n][k], At[m][k], acc[ai][bj][m][n], 0, 0, 0); __builtin_amdgcn_s_setprio(0); } while (0)
; #define PG8_WAIT_V(n) asm volatile("s_waitcnt vmcnt(" #n ")" ::: "memory")
; #define PG8_WAIT_L(n) asm volatile("s_waitcnt lgkmcnt(" #n ")" ::: "memory")
; #define PG8_BAR __builtin_amdgcn_s_barrier()
; #define PG8_SCHED __builtin_amdgcn_sched_barrier(0)
; template <class Epi, class Sched, bool ALIGN_EPI = false, bool SP2 = false>
; __device__ __forceinline__ void gemm_phase(PG8_LAS unsigned char* lds, const Gemm g, const Sched& S, const Epi& E) {
;     ...
;             PG8_WAIT_V(8); PG8_WAIT_L(0); PG8_BAR; PG8_MMA(1, 0, At, B0); PG8_MMA(1, 1, At, B1); PG8_BAR; PG8_SCHED;
;             PG8_LDB(B0, 1, 0); PG8_LDB(B1, 1, 1); PG8_SCHED; PG8_LDA(At, 1, 0); PG8_STAGE(PG8_SA(0, 1), a2 + hstep, voffA);
;             PG8_WAIT_V(8); PG8_WAIT_L(0); PG8_BAR; PG8_MMA(0, 0, At, B0); PG8_MMA(0, 1, At, B1); PG8_BAR; PG8_SCHED;
	s_setprio 1
	s_waitcnt lgkmcnt(0)
	v_mfma_f32_16x16x32_bf16 v[92:95], v[128:131], v[186:189], v[92:95]
	v_mfma_f32_16x16x32_bf16 v[88:91], v[154:157], v[186:189], v[88:91]
	v_mfma_f32_16x16x32_bf16 v[84:87], v[128:131], v[194:197], v[84:87]
	v_mfma_f32_16x16x32_bf16 v[80:83], v[154:157], v[194:197], v[80:83]
	v_mfma_f32_16x16x32_bf16 v[76:79], v[128:131], v[202:205], v[76:79]
	v_mfma_f32_16x16x32_bf16 v[72:75], v[154:157], v[202:205], v[72:75]
	v_mfma_f32_16x16x32_bf16 v[64:67], v[128:131], v[210:213], v[64:67]
	v_mfma_f32_16x16x32_bf16 v[56:59], v[154:157], v[210:213], v[56:59]
	v_mfma_f32_16x16x32_bf16 v[92:95], v[132:135], v[190:193], v[92:95]
	v_mfma_f32_16x16x32_bf16 v[88:91], v[158:161], v[190:193], v[88:91]
	v_mfma_f32_16x16x32_bf16 v[84:87], v[132:135], v[198:201], v[84:87]
	v_mfma_f32_16x16x32_bf16 v[80:83], v[158:161], v[198:201], v[80:83]
	v_mfma_f32_16x16x32_bf16 v[76:79], v[132:135], v[206:209], v[76:79]
	v_mfma_f32_16x16x32_bf16 v[72:75], v[158:161], v[206:209], v[72:75]
	v_mfma_f32_16x16x32_bf16 v[64:67], v[132:135], v[214:217], v[64:67]
	v_mfma_f32_16x16x32_bf16 v[56:59], v[158:161], v[214:217], v[56:59]
	s_setprio 0
	s_setprio 1
	v_mfma_f32_16x16x32_bf16 v[28:31], v[170:173], v[186:189], v[28:31]
	v_mfma_f32_16x16x32_bf16 v[24:27], v[178:181], v[186:189], v[24:27]
	v_mfma_f32_16x16x32_bf16 v[20:23], v[170:173], v[194:197], v[20:23]
	v_mfma_f32_16x16x32_bf16 v[16:19], v[178:181], v[194:197], v[16:19]
	v_mfma_f32_16x16x32_bf16 v[12:15], v[170:173], v[202:205], v[12:15]
	v_mfma_f32_16x16x32_bf16 v[8:11], v[178:181], v[202:205], v[8:11]
	v_mfma_f32_16x16x32_bf16 v[4:7], v[170:173], v[210:213], v[4:7]
	v_mfma_f32_16x16x32_bf16 v[0:3], v[178:181], v[210:213], v[0:3]
	v_mfma_f32_16x16x32_bf16 v[28:31], v[174:177], v[190:193], v[28:31]
	v_mfma_f32_16x16x32_bf16 v[24:27], v[182:185], v[190:193], v[24:27]
	v_mfma_f32_16x16x32_bf16 v[20:23], v[174:177], v[198:201], v[20:23]
	v_mfma_f32_16x16x32_bf16 v[16:19], v[182:185], v[198:201], v[16:19]
	s_setprio 2
	s_barrier
	v_mfma_f32_16x16x32_bf16 v[12:15], v[174:177], v[206:209], v[12:15]
	v_mfma_f32_16x16x32_bf16 v[8:11], v[182:185], v[206:209], v[8:11]
	v_mfma_f32_16x16x32_bf16 v[4:7], v[174:177], v[214:217], v[4:7]
	v_mfma_f32_16x16x32_bf16 v[0:3], v[182:185], v[214:217], v[0:3]
	s_setprio 0
	s_add_i32 s64, 0, 0x18000
	s_add_i32 s65, 0, 0x1c000
	v_add_u32_e32 v158, s64, v165
	v_add_u32_e32 v182, s65, v165
	ds_read_b128 v[128:131], v158
	ds_read_b128 v[132:135], v158 offset:1024
	ds_read_b128 v[154:157], v158 offset:2048
	ds_read_b128 v[158:161], v158 offset:3072
	ds_read_b128 v[170:173], v182
	ds_read_b128 v[174:177], v182 offset:1024
	ds_read_b128 v[178:181], v182 offset:2048
	ds_read_b128 v[182:185], v182 offset:3072
	s_add_u32 s44, s44, 0x200000
	s_addc_u32 s45, s45, 0
	s_mov_b32 m0, s47
	v_lshl_add_u64 v[224:225], s[44:45], 0, v[136:137]
	ds_read_b128 v[186:189], v169 offset:32768
	ds_read_b128 v[190:193], v169 offset:33792
	ds_read_b128 v[194:197], v169 offset:34816
	ds_read_b128 v[198:201], v169 offset:35840
	ds_read_b128 v[202:205], v169 offset:36864
	ds_read_b128 v[206:209], v169 offset:37888
	ds_read_b128 v[210:213], v169 offset:38912
	ds_read_b128 v[214:217], v169 offset:39936
	global_load_lds_dwordx4 v[224:225], off
	v_lshl_add_u64 v[224:225], s[44:45], 0, v[140:141]
	s_mov_b32 m0, s48
	s_nop 0
	global_load_lds_dwordx4 v[224:225], off
	s_waitcnt vmcnt(8)
	s_waitcnt lgkmcnt(0)
	s_barrier
	s_setprio 1
	s_waitcnt lgkmcnt(0)
	v_mfma_f32_16x16x32_bf16 v[124:127], v[128:131], v[186:189], v[124:127]
	v_mfma_f32_16x16x32_bf16 v[120:123], v[154:157], v[186:189], v[120:123]
	v_mfma_f32_16x16x32_bf16 v[116:119], v[128:131], v[194:197], v[116:119]
	v_mfma_f32_16x16x32_bf16 v[112:115], v[154:157], v[194:197], v[112:115]
	v_mfma_f32_16x16x32_bf16 v[108:111], v[128:131], v[202:205], v[108:111]
	v_mfma_f32_16x16x32_bf16 v[104:107], v[154:157], v[202:205], v[104:107]
	v_mfma_f32_16x16x32_bf16 v[100:103], v[128:131], v[210:213], v[100:103]
	v_mfma_f32_16x16x32_bf16 v[96:99], v[154:157], v[210:213], v[96:99]
	v_mfma_f32_16x16x32_bf16 v[124:127], v[132:135], v[190:193], v[124:127]
	v_mfma_f32_16x16x32_bf16 v[120:123], v[158:161], v[190:193], v[120:123]
	v_mfma_f32_16x16x32_bf16 v[116:119], v[132:135], v[198:201], v[116:119]
	v_mfma_f32_16x16x32_bf16 v[112:115], v[158:161], v[198:201], v[112:115]
	v_mfma_f32_16x16x32_bf16 v[108:111], v[132:135], v[206:209], v[108:111]
	v_mfma_f32_16x16x32_bf16 v[104:107], v[158:161], v[206:209], v[104:107]
	v_mfma_f32_16x16x32_bf16 v[100:103], v[132:135], v[214:217], v[100:103]
	v_mfma_f32_16x16x32_bf16 v[96:99], v[158:161], v[214:217], v[96:99]
	s_setprio 0
	s_setprio 1
	v_mfma_f32_16x16x32_bf16 v[68:71], v[170:173], v[186:189], v[68:71]
	v_mfma_f32_16x16x32_bf16 v[60:63], v[178:181], v[186:189], v[60:63]
	v_mfma_f32_16x16x32_bf16 v[52:55], v[170:173], v[194:197], v[52:55]
	v_mfma_f32_16x16x32_bf16 v[48:51], v[178:181], v[194:197], v[48:51]
	v_mfma_f32_16x16x32_bf16 v[44:47], v[170:173], v[202:205], v[44:47]
	v_mfma_f32_16x16x32_bf16 v[40:43], v[178:181], v[202:205], v[40:43]
	v_mfma_f32_16x16x32_bf16 v[36:39], v[170:173], v[210:213], v[36:39]
	v_mfma_f32_16x16x32_bf16 v[32:35], v[178:181], v[210:213], v[32:35]
	v_mfma_f32_16x16x32_bf16 v[68:71], v[174:177], v[190:193], v[68:71]
	v_mfma_f32_16x16x32_bf16 v[60:63], v[182:185], v[190:193], v[60:63]
	v_mfma_f32_16x16x32_bf16 v[52:55], v[174:177], v[198:201], v[52:55]
	v_mfma_f32_16x16x32_bf16 v[48:51], v[182:185], v[198:201], v[48:51]
	s_setprio 2
	s_barrier
; #define PG8_STAGE(bufoff, gbase, voff) do { _Pragma("unroll") for (int _i = 0; _i < 2; ++_i) \
;         __builtin_amdgcn_global_load_lds((const unsigned*)((const char*)(gbase) + (voff)[_i]), (PG8_LAS unsigned*)(lds + (bufoff) + ldsw + _i * 8192), 16, 0, 0); } while (0)
; #define PG8_LDA(dst, b, h) do { _Pragma("unroll") for (int m = 0; m < 4; ++m) _Pragma("unroll") for (int k = 0; k < 2; ++k) dst[m][k] = *(const PG8_LAS bf16x8*)(lds + PG8_SA(b, h) + aoff + m * 2048 + k * 1024); } while (0)
; #define PG8_MMA(ai, bj, At, Bt) do { __builtin_amdgcn_s_setprio(1); _Pragma("unroll") for (int m = 0; m < 4; ++m) _Pragma("unroll") for (int n = 0; n < 2; ++n) _Pragma("unroll") for (int k = 0; k < 2; ++k) \
;         acc[ai][bj][m][n] = __builtin_amdgcn_mfma_f32_16x16x32_bf16(Bt[n][k], At[m][k], acc[ai][bj][m][n], 0, 0, 0); __builtin_amdgcn_s_setprio(0); } while (0)
; #define PG8_WAIT_V(n) asm volatile("s_waitcnt vmcnt(" #n ")" ::: "memory")
; #define PG8_WAIT_L(n) asm volatile("s_waitcnt lgkmcnt(" #n ")" ::: "memory")
; #define PG8_BAR __builtin_amdgcn_s_barrier()
; #define PG8_SCHED __builtin_amdgcn_sched_barrier(0)
; template <class Epi, class Sched, bool ALIGN_EPI = false, bool SP2 = false>
; __device__ __forceinline__ void gemm_phase(PG8_LAS unsigned char* lds, const Gemm g, const Sched& S, const Epi& E) {
;     ...
;             PG8_WAIT_V(8); PG8_WAIT_L(0); PG8_BAR; PG8_MMA(0, 0, At, B0); PG8_MMA(0, 1, At, B1); PG8_BAR; PG8_SCHED;
;             PG8_LDA(At, 1, 1); PG8_STAGE(PG8_SB(1, 0), b3, voffB); PG8_STAGE(PG8_SB(1, 1), b3 + hstep, voffB); PG8_STAGE(PG8_SA(1, 0), a3, voffA);
;             PG8_WAIT_V(8); PG8_WAIT_L(0); PG8_BAR; PG8_MMA(1, 0, At, B0); PG8_MMA(1, 1, At, B1); PG8_BAR; PG8_SCHED;
	v_mfma_f32_16x16x32_bf16 v[44:47], v[174:177], v[206:209], v[44:47]
	v_mfma_f32_16x16x32_bf16 v[40:43], v[182:185], v[206:209], v[40:43]
	v_mfma_f32_16x16x32_bf16 v[36:39], v[174:177], v[214:217], v[36:39]
	v_mfma_f32_16x16x32_bf16 v[32:35], v[182:185], v[214:217], v[32:35]
	s_setprio 0
	s_add_i32 s44, s64, s33
	v_lshl_add_u64 v[162:163], v[162:163], 0, s[8:9]
	s_mov_b32 m0, s44
	ds_read_b128 v[186:189], v169 offset:49152
	ds_read_b128 v[190:193], v169 offset:50176
	ds_read_b128 v[194:197], v169 offset:51200
	ds_read_b128 v[198:201], v169 offset:52224
	ds_read_b128 v[202:205], v169 offset:53248
	ds_read_b128 v[206:209], v169 offset:54272
	ds_read_b128 v[210:213], v169 offset:55296
	ds_read_b128 v[214:217], v169 offset:56320
	global_load_lds_dwordx4 v[162:163], off
	s_add_i32 m0, s44, 0x2000
	s_add_u32 s42, s42, 0x200080
	v_lshl_add_u64 v[162:163], v[218:219], 0, s[8:9]
	s_addc_u32 s43, s43, 0
	s_add_i32 s44, s65, s33
	global_load_lds_dwordx4 v[162:163], off
	v_lshl_add_u64 v[162:163], s[42:43], 0, v[138:139]
	s_mov_b32 m0, s44
	s_nop 0
	global_load_lds_dwordx4 v[162:163], off
	v_lshl_add_u64 v[162:163], s[42:43], 0, v[142:143]
	s_add_i32 m0, s44, 0x2000
	s_nop 0
	global_load_lds_dwordx4 v[162:163], off
	v_lshl_add_u64 v[162:163], v[220:221], 0, s[8:9]
	s_mov_b32 m0, s52
	s_nop 0
	global_load_lds_dwordx4 v[162:163], off
	v_lshl_add_u64 v[162:163], v[222:223], 0, s[8:9]
	s_mov_b32 m0, s53
	s_nop 0
	global_load_lds_dwordx4 v[162:163], off
	s_waitcnt vmcnt(8)
	s_waitcnt lgkmcnt(0)
	s_barrier
	s_setprio 1
	s_waitcnt lgkmcnt(0)
	v_mfma_f32_16x16x32_bf16 v[92:95], v[128:131], v[186:189], v[92:95]
	v_mfma_f32_16x16x32_bf16 v[88:91], v[154:157], v[186:189], v[88:91]
	v_mfma_f32_16x16x32_bf16 v[84:87], v[128:131], v[194:197], v[84:87]
	v_mfma_f32_16x16x32_bf16 v[80:83], v[154:157], v[194:197], v[80:83]
	v_mfma_f32_16x16x32_bf16 v[76:79], v[128:131], v[202:205], v[76:79]
	v_mfma_f32_16x16x32_bf16 v[72:75], v[154:157], v[202:205], v[72:75]
	v_mfma_f32_16x16x32_bf16 v[64:67], v[128:131], v[210:213], v[64:67]
	v_mfma_f32_16x16x32_bf16 v[56:59], v[154:157], v[210:213], v[56:59]
	v_mfma_f32_16x16x32_bf16 v[92:95], v[132:135], v[190:193], v[92:95]
	v_mfma_f32_16x16x32_bf16 v[88:91], v[158:161], v[190:193], v[88:91]
	v_mfma_f32_16x16x32_bf16 v[84:87], v[132:135], v[198:201], v[84:87]
	v_mfma_f32_16x16x32_bf16 v[80:83], v[158:161], v[198:201], v[80:83]
	v_mfma_f32_16x16x32_bf16 v[76:79], v[132:135], v[206:209], v[76:79]
	v_mfma_f32_16x16x32_bf16 v[72:75], v[158:161], v[206:209], v[72:75]
	v_mfma_f32_16x16x32_bf16 v[64:67], v[132:135], v[214:217], v[64:67]
	v_mfma_f32_16x16x32_bf16 v[56:59], v[158:161], v[214:217], v[56:59]
	s_setprio 0
	s_setprio 1
	v_mfma_f32_16x16x32_bf16 v[28:31], v[170:173], v[186:189], v[28:31]
	v_mfma_f32_16x16x32_bf16 v[24:27], v[178:181], v[186:189], v[24:27]
	v_mfma_f32_16x16x32_bf16 v[20:23], v[170:173], v[194:197], v[20:23]
	v_mfma_f32_16x16x32_bf16 v[16:19], v[178:181], v[194:197], v[16:19]
	v_mfma_f32_16x16x32_bf16 v[12:15], v[170:173], v[202:205], v[12:15]
	v_mfma_f32_16x16x32_bf16 v[8:11], v[178:181], v[202:205], v[8:11]
	v_mfma_f32_16x16x32_bf16 v[4:7], v[170:173], v[210:213], v[4:7]
	v_mfma_f32_16x16x32_bf16 v[0:3], v[178:181], v[210:213], v[0:3]
	v_mfma_f32_16x16x32_bf16 v[28:31], v[174:177], v[190:193], v[28:31]
	v_mfma_f32_16x16x32_bf16 v[24:27], v[182:185], v[190:193], v[24:27]
	v_mfma_f32_16x16x32_bf16 v[20:23], v[174:177], v[198:201], v[20:23]
	v_mfma_f32_16x16x32_bf16 v[16:19], v[182:185], v[198:201], v[16:19]
	s_setprio 2
	s_barrier
	v_mfma_f32_16x16x32_bf16 v[12:15], v[174:177], v[206:209], v[12:15]
	v_mfma_f32_16x16x32_bf16 v[8:11], v[182:185], v[206:209], v[8:11]
	v_mfma_f32_16x16x32_bf16 v[4:7], v[174:177], v[214:217], v[4:7]
	v_mfma_f32_16x16x32_bf16 v[0:3], v[182:185], v[214:217], v[0:3]
	s_setprio 0
	s_add_i32 s63, s63, 2
	s_add_u32 s40, s40, 0x100
	s_addc_u32 s41, s41, 0
	s_add_u32 s61, s61, 0x100
	s_addc_u32 s62, s62, 0
	s_cmpk_gt_u32 s63, 0x7d
	s_cbranch_scc0 .LBB0_1219
	s_and_b64 vcc, exec, s[10:11]
	s_cbranch_vccz .LBB0_1222
	s_barrier
